# producer/consumer wave specialization (2 MFMA waves 128x64 + 2 LDS-DMA waves, roles by SIMD id) for in-proj/ff1/gate/GLU GEMMs; per-block K rotation; classic LDS-DMA loop for split-K GEMMs
# speedup vs baseline: 1.0455x; 1.0455x over previous
.LBB0_5:
	s_or_b64 exec, exec, s[2:3]
	s_load_dwordx2 s[98:99], s[0:1], 0x178
	s_getreg_b32 s101, hwreg(HW_REG_HW_ID, 8, 7)
	s_and_b32 s100, s20, 7
	s_lshl_b32 s100, s100, 7
	s_or_b32 s101, s101, s100
	s_lshl_b32 s101, s101, 2
	v_cmp_eq_u32_e32 vcc, 0, v194
	s_and_saveexec_b64 s[2:3], vcc
	s_cbranch_execz .Lab_skip
	v_mov_b32_e32 v1, s101
	v_mov_b32_e32 v2, 1
	s_waitcnt lgkmcnt(0)
	global_atomic_add v1, v1, v2, s[98:99] offset:512 sc0
	s_waitcnt vmcnt(0)
	v_and_b32_e32 v1, 1, v1
	v_mov_b32_e32 v2, 0x10018
	ds_write_b32 v2, v1
	s_waitcnt lgkmcnt(0)
.Lab_skip:
	s_or_b64 exec, exec, s[2:3]
	s_waitcnt lgkmcnt(0)
	s_barrier
	v_mov_b32_e32 v1, 0x10018
	ds_read_b32 v1, v1
	v_lshrrev_b32_e32 v2, 6, v194
	s_waitcnt lgkmcnt(0)
	s_nop 0
	v_readfirstlane_b32 s101, v1
	v_readfirstlane_b32 s100, v2
	s_getreg_b32 s98, hwreg(HW_REG_HW_ID, 4, 2)
	s_lshr_b32 s99, s98, 1
	s_cmp_eq_u32 s99, s101
	s_cselect_b32 s99, 1, 0
	s_and_b32 s98, s98, 1
	s_lshl_b32 s98, s98, 1
	s_or_b32 s99, s99, s98
	s_lshl_b32 s100, s100, 2
	s_or_b32 s101, s99, s100
	v_readlane_b32 s98, v252, 0
	s_lshr_b32 s98, s98, 3
	s_and_b32 s98, s98, 0xff
	s_lshl_b32 s98, s98, 8
	s_or_b32 s101, s101, s98
	s_load_dwordx2 s[52:53], s[0:1], 0x210
	s_waitcnt lgkmcnt(0)
	s_cmp_ge_i32 s52, s53
	s_cbranch_scc1 .Lend_near
	s_load_dwordx2 s[22:23], s[0:1], 0x1a8
	s_load_dwordx16 s[56:71], s[0:1], 0x0
	s_load_dwordx16 s[36:51], s[0:1], 0x40
	s_load_dwordx16 s[4:19], s[0:1], 0x80
	v_lshrrev_b32_e32 v1, 20, v0
	v_lshrrev_b32_e32 v0, 10, v0
	v_or_b32_e32 v0, v0, v1
	s_mov_b32 s97, 0
	s_waitcnt lgkmcnt(0)
	v_writelane_b32 v252, s4, 5
	s_movk_i32 s55, 0x4000
	v_mov_b32_e32 v2, 0
	v_writelane_b32 v252, s5, 6
	v_writelane_b32 v252, s6, 7
	v_writelane_b32 v252, s7, 8
	v_writelane_b32 v252, s8, 9
	v_writelane_b32 v252, s9, 10
	v_writelane_b32 v252, s10, 11
	v_writelane_b32 v252, s11, 12
	v_writelane_b32 v252, s12, 13
	v_writelane_b32 v252, s13, 14
	v_writelane_b32 v252, s14, 15
	v_writelane_b32 v252, s15, 16
	v_writelane_b32 v252, s16, 17
	v_writelane_b32 v252, s17, 18
	v_writelane_b32 v252, s18, 19
	v_writelane_b32 v252, s19, 20
	s_load_dwordx16 s[4:19], s[0:1], 0xc0
	s_mov_b32 s28, 0x10000
	v_mov_b32_e32 v198, 0x358637bd
	s_movk_i32 s96, 0x43ff
	s_mov_b32 s29, 0x20000
	s_waitcnt lgkmcnt(0)
	v_writelane_b32 v252, s4, 21
	v_mov_b32_e32 v199, 0x10000
	s_movk_i32 s33, 0x110
	v_writelane_b32 v252, s5, 22
	v_writelane_b32 v252, s6, 23
	v_writelane_b32 v252, s7, 24
	v_writelane_b32 v252, s8, 25
	v_writelane_b32 v252, s9, 26
	v_writelane_b32 v252, s10, 27
	v_writelane_b32 v252, s11, 28
	v_writelane_b32 v252, s12, 29
	v_writelane_b32 v252, s13, 30
	v_writelane_b32 v252, s14, 31
	v_writelane_b32 v252, s15, 32
	v_writelane_b32 v252, s16, 33
	v_writelane_b32 v252, s17, 34
	v_writelane_b32 v252, s18, 35
	v_writelane_b32 v252, s19, 36
	s_load_dwordx16 s[4:19], s[0:1], 0x100
	v_mov_b32_e32 v201, 0x3ecc95a3
	v_mov_b64_e32 v[212:213], 0xe00
	v_mov_b64_e32 v[196:197], 0x3600
	v_mov_b32_e32 v204, 0x7f800000
	s_waitcnt lgkmcnt(0)
	v_writelane_b32 v252, s4, 37
	v_mov_b32_e32 v206, 0x41b17218
	v_mov_b32_e32 v136, 0x3f317218
	v_writelane_b32 v252, s5, 38
	v_writelane_b32 v252, s6, 39
	v_writelane_b32 v252, s7, 40
	v_writelane_b32 v252, s8, 41
	v_writelane_b32 v252, s9, 42
	v_writelane_b32 v252, s10, 43
	v_writelane_b32 v252, s11, 44
	v_writelane_b32 v252, s12, 45
	v_writelane_b32 v252, s13, 46
	v_writelane_b32 v252, s14, 47
	v_writelane_b32 v252, s15, 48
	v_writelane_b32 v252, s16, 49
	v_writelane_b32 v252, s17, 50
	v_writelane_b32 v252, s18, 51
	v_writelane_b32 v252, s19, 52
	s_load_dwordx16 s[72:87], s[0:1], 0x140
	s_load_dwordx16 s[4:19], s[0:1], 0x1b0
	v_mov_b32_e32 v203, 0x7fc00000
	v_mov_b32_e32 v195, 0xff800000
	v_mov_b32_e32 v205, 0xe400
	v_mov_b32_e32 v200, 0x9f00
	s_waitcnt lgkmcnt(0)
	v_writelane_b32 v252, s4, 53
	v_mov_b32_e32 v207, 0x42800000
	s_nop 0
	v_writelane_b32 v252, s5, 54
	v_writelane_b32 v252, s6, 55
	v_writelane_b32 v252, s7, 56
	v_writelane_b32 v253, s15, 0
	v_writelane_b32 v252, s8, 57
	v_writelane_b32 v253, s16, 1
	v_writelane_b32 v252, s9, 58
	v_writelane_b32 v253, s17, 2
	v_writelane_b32 v252, s10, 59
	v_writelane_b32 v253, s18, 3
	v_writelane_b32 v252, s11, 60
	v_writelane_b32 v253, s19, 4
	s_load_dwordx8 s[4:11], s[0:1], 0x1f0
	s_add_u32 s0, s0, 0x218
	s_addc_u32 s1, s1, 0
	v_writelane_b32 v252, s12, 61
	v_writelane_b32 v252, s13, 62
	s_waitcnt lgkmcnt(0)
	v_writelane_b32 v253, s4, 5
	v_writelane_b32 v252, s14, 63
	s_nop 0
	v_writelane_b32 v253, s5, 6
	v_writelane_b32 v253, s6, 7
	v_writelane_b32 v253, s7, 8
	v_writelane_b32 v253, s8, 9
	v_writelane_b32 v253, s9, 10
	v_writelane_b32 v253, s10, 11
	v_writelane_b32 v253, s11, 12
	v_writelane_b32 v253, s0, 13
	s_nop 1
	v_writelane_b32 v253, s1, 14
	s_add_u32 s0, s88, 0x200
	s_addc_u32 s1, s89, 0
	v_writelane_b32 v253, s0, 15
	s_nop 1
	v_writelane_b32 v253, s1, 16
	s_add_u32 s0, s88, 0x1000
	s_addc_u32 s1, s89, 0
	v_writelane_b32 v253, s0, 17
	s_nop 1
	v_writelane_b32 v253, s1, 18
	s_add_u32 s0, s88, 0x1100
	s_addc_u32 s1, s89, 0
	v_writelane_b32 v253, s0, 19
	s_nop 1
	v_writelane_b32 v253, s1, 20
	s_add_u32 s0, s88, 0x1200
	s_addc_u32 s1, s89, 0
	v_writelane_b32 v253, s0, 21
	s_nop 1
	v_writelane_b32 v253, s1, 22
	s_add_u32 s0, s88, 0x1300
	s_addc_u32 s1, s89, 0
	v_writelane_b32 v253, s0, 23
	s_cmp_eq_u32 s20, 15
	s_nop 0
	v_writelane_b32 v253, s1, 24
	s_cselect_b64 s[0:1], -1, 0
	v_writelane_b32 v253, s0, 25
	s_cmp_eq_u32 s20, 14
	s_nop 0
	v_writelane_b32 v253, s1, 26
	s_cselect_b64 s[0:1], -1, 0
	v_writelane_b32 v253, s0, 27
	s_cmp_eq_u32 s20, 13
	s_nop 0
	v_writelane_b32 v253, s1, 28
	s_cselect_b64 s[0:1], -1, 0
	v_writelane_b32 v253, s0, 29
	s_cmp_eq_u32 s20, 12
	s_nop 0
	v_writelane_b32 v253, s1, 30
	s_cselect_b64 s[0:1], -1, 0
	v_writelane_b32 v253, s0, 31
	s_cmp_eq_u32 s20, 11
	s_nop 0
	v_writelane_b32 v253, s1, 32
	s_cselect_b64 s[0:1], -1, 0
	v_writelane_b32 v253, s0, 33
	s_cmp_eq_u32 s20, 10
	s_nop 0
	v_writelane_b32 v253, s1, 34
	s_cselect_b64 s[0:1], -1, 0
	v_writelane_b32 v253, s0, 35
	s_cmp_eq_u32 s20, 9
	s_nop 0
	v_writelane_b32 v253, s1, 36
	s_cselect_b64 s[0:1], -1, 0
	v_writelane_b32 v253, s0, 37
	s_cmp_eq_u32 s20, 8
	s_nop 0
	v_writelane_b32 v253, s1, 38
	s_cselect_b64 s[0:1], -1, 0
	v_writelane_b32 v253, s0, 39
	s_cmp_eq_u32 s20, 7
	s_nop 0
	v_writelane_b32 v253, s1, 40
	s_cselect_b64 s[0:1], -1, 0
	v_writelane_b32 v253, s0, 41
	s_cmp_eq_u32 s20, 6
	s_nop 0
	v_writelane_b32 v253, s1, 42
	s_cselect_b64 s[0:1], -1, 0
	v_writelane_b32 v253, s0, 43
	s_cmp_eq_u32 s20, 5
	s_nop 0
	v_writelane_b32 v253, s1, 44
	s_cselect_b64 s[0:1], -1, 0
	v_writelane_b32 v253, s0, 45
	s_cmp_eq_u32 s20, 4
	s_nop 0
	v_writelane_b32 v253, s1, 46
	s_cselect_b64 s[0:1], -1, 0
	v_writelane_b32 v253, s0, 47
	s_cmp_eq_u32 s20, 3
	s_nop 0
	v_writelane_b32 v253, s1, 48
	s_cselect_b64 s[0:1], -1, 0
	v_writelane_b32 v253, s0, 49
	s_cmp_eq_u32 s20, 2
	s_nop 0
	v_writelane_b32 v253, s1, 50
	s_cselect_b64 s[0:1], -1, 0
	v_writelane_b32 v253, s0, 51
	s_cmp_eq_u32 s20, 1
	s_nop 0
	v_writelane_b32 v253, s1, 52
	s_cselect_b64 s[0:1], -1, 0
	v_writelane_b32 v253, s0, 53
	s_cmp_eq_u32 s20, 0
	s_nop 0
	v_writelane_b32 v253, s1, 54
	s_cselect_b64 s[0:1], -1, 0
	v_writelane_b32 v253, s0, 55
	s_nop 1
	v_writelane_b32 v253, s1, 56
	s_lshl_b32 s0, s20, 8
	s_add_u32 s0, s88, s0
	s_addc_u32 s1, s89, 0
	s_add_u32 s2, s0, 0x1400
	s_addc_u32 s3, s1, 0
	v_writelane_b32 v253, s2, 57
	s_add_u32 s0, s0, 0x2400
	s_addc_u32 s1, s1, 0
	v_writelane_b32 v253, s3, 58
	v_writelane_b32 v253, s0, 59
	v_readlane_b32 s3, v252, 0
	s_nop 0
	v_writelane_b32 v253, s1, 60
	s_add_u32 s0, s88, 0x3400
	s_addc_u32 s1, s89, 0
	v_writelane_b32 v253, s0, 61
	s_nop 1
	v_writelane_b32 v253, s1, 62
	s_add_u32 s0, s88, 0x3500
	s_addc_u32 s1, s89, 0
	v_writelane_b32 v253, s0, 63
	s_cmp_lt_i32 s53, 0
	s_nop 0
	v_writelane_b32 v254, s1, 0
	s_cselect_b64 s[0:1], -1, 0
	v_writelane_b32 v254, s0, 1
	s_nop 1
	v_writelane_b32 v254, s1, 2
	s_movk_i32 s0, 0x3ff
	v_and_or_b32 v0, v0, s0, v194
	v_cmp_eq_u32_e64 s[0:1], 0, v0
	s_nop 1
	v_writelane_b32 v254, s0, 3
	s_nop 1
	v_writelane_b32 v254, s1, 4
	s_lshl_b32 s0, s3, 2
	v_writelane_b32 v254, s0, 5
	s_add_u32 s0, s42, 0x1000
	v_writelane_b32 v254, s36, 6
	s_addc_u32 s1, s43, 0
	s_cmp_lg_u64 s[84:85], 0
	v_writelane_b32 v254, s37, 7
	v_writelane_b32 v254, s38, 8
	v_writelane_b32 v254, s39, 9
	v_writelane_b32 v254, s40, 10
	v_writelane_b32 v254, s41, 11
	v_writelane_b32 v254, s42, 12
	v_writelane_b32 v254, s43, 13
	v_writelane_b32 v254, s44, 14
	v_writelane_b32 v254, s45, 15
	v_writelane_b32 v254, s46, 16
	v_writelane_b32 v254, s47, 17
	v_writelane_b32 v254, s48, 18
	v_writelane_b32 v254, s49, 19
	v_writelane_b32 v254, s50, 20
	v_writelane_b32 v254, s51, 21
	v_writelane_b32 v254, s0, 22
	s_mov_b64 s[36:37], 0x800
	s_nop 0
	v_writelane_b32 v254, s1, 23
	s_cselect_b64 s[0:1], -1, 0
	v_writelane_b32 v254, s0, 24
	s_cmpk_lt_i32 s3, 0x1560
	s_nop 0
	v_writelane_b32 v254, s1, 25
	s_cselect_b64 s[0:1], -1, 0
	v_writelane_b32 v254, s0, 26
	s_cmp_lg_u64 s[76:77], 0
	s_nop 0
	v_writelane_b32 v254, s1, 27
	s_cselect_b64 s[0:1], -1, 0
	v_writelane_b32 v254, s0, 28
	s_and_b32 s4, s3, 7
	s_lshl_b32 s2, s3, 4
	v_writelane_b32 v254, s1, 29
	s_lshr_b32 s0, s3, 3
	s_lshl_b32 s1, s4, 6
	v_writelane_b32 v254, s0, 30
	s_add_i32 s0, s1, s0
	v_writelane_b32 v254, s1, 31
	s_lshl_b32 s0, s0, 4
	s_and_b32 s2, s2, 0x380
	s_and_b32 s1, s0, 0xfffffc00
	v_writelane_b32 v254, s2, 32
	s_and_b32 s0, s0, 0x380
	v_writelane_b32 v254, s0, 33
	s_lshl_b32 s0, s3, 1
	s_and_b32 s0, s0, 0x7fffff80
	s_or_b32 s1, s1, s2
	s_addk_i32 s0, 0x4000
	v_writelane_b32 v254, s0, 34
	s_add_i32 s54, s1, 0x2000
	s_lshl_b32 s0, s4, 22
	v_writelane_b32 v254, s1, 35
	s_add_u32 s0, s80, s0
	v_writelane_b32 v254, s4, 36
	s_addc_u32 s1, s81, 0
	v_writelane_b32 v254, s0, 37
	s_nop 1
	v_writelane_b32 v254, s1, 38
	s_add_i32 s1, s22, -1
	s_mul_i32 s0, s1, 0x60
	v_writelane_b32 v254, s0, 39
	s_mul_i32 s0, s1, 0xa0
	v_writelane_b32 v254, s0, 40
	s_ashr_i32 s0, s1, 31
	v_writelane_b32 v254, s0, 41
	v_writelane_b32 v254, s22, 42
	s_sub_i32 s0, 1, s22
	s_max_i32 s0, s1, s0
	v_cvt_f32_u32_e32 v0, s0
	v_writelane_b32 v254, s23, 43
	v_writelane_b32 v254, s1, 44
	v_writelane_b32 v254, s0, 45
	v_rcp_iflag_f32_e32 v0, v0
	s_sub_i32 s0, 0, s0
	v_mul_f32_e32 v0, 0x4f7ffffe, v0
	v_cvt_u32_f32_e32 v0, v0
	s_nop 0
	v_readfirstlane_b32 s1, v0
	s_mul_i32 s0, s0, s1
	s_mul_hi_u32 s0, s1, s0
	s_add_i32 s0, s1, s0
	v_writelane_b32 v254, s0, 46
	s_add_u32 s0, s78, 64
	s_addc_u32 s1, s79, 0
	v_writelane_b32 v254, s0, 47
	v_mbcnt_lo_u32_b32 v0, -1, 0
	s_nop 0
	v_writelane_b32 v254, s1, 48
	v_readlane_b32 s0, v252, 1
	v_readlane_b32 s1, v252, 2
	s_add_u32 s2, s0, 0x100
	s_addc_u32 s3, s1, 0
	v_writelane_b32 v254, s2, 49
	v_mbcnt_hi_u32_b32 v202, -1, v0
	s_nop 0
	v_writelane_b32 v254, s3, 50
	s_add_u32 s2, s0, 0x140
	s_addc_u32 s3, s1, 0
	v_writelane_b32 v254, s2, 51
	s_nop 1
	v_writelane_b32 v254, s3, 52
	s_add_u32 s2, s0, 0x180
	s_addc_u32 s3, s1, 0
	v_writelane_b32 v254, s2, 53
	s_add_u32 s0, s0, 0x1c0
	s_addc_u32 s1, s1, 0
	v_writelane_b32 v254, s3, 54
	v_writelane_b32 v254, s0, 55
	s_mov_b32 s2, s52
	s_nop 0
	v_writelane_b32 v254, s1, 56
	s_add_u32 s0, s78, 0x2c00
	s_addc_u32 s1, s79, 0
	v_writelane_b32 v254, s0, 57
	s_nop 1
	v_writelane_b32 v254, s1, 58
	v_writelane_b32 v254, s54, 59
	v_writelane_b32 v254, s52, 60
	s_nop 1
	v_writelane_b32 v254, s53, 61
	s_branch .LBB0_9
.Lend_near:
	s_endpgm
.LBB0_7:
	s_or_b64 exec, exec, s[0:1]
	v_readlane_b32 s2, v254, 62

.LBB0_134:
	s_andn2_b64 vcc, exec, s[2:3]
	s_movk_i32 s55, 0x4000
	v_readlane_b32 s54, v254, 59
	s_cbranch_vccnz .LBB0_165
	s_waitcnt vmcnt(0)
	v_mov_b32_e32 v74, v194
	s_movk_i32 s22, 0x1000
	s_movk_i32 s24, 0x1000
	s_movk_i32 s2, 0x1000
	v_lshlrev_b32_e32 v0, 3, v74
	v_ashrrev_i32_e32 v3, 3, v74
	v_and_b32_e32 v0, 56, v0
	v_lshrrev_b32_e32 v132, 4, v74
	v_xor_b32_e32 v132, v132, v74
	v_and_b32_e32 v132, 7, v132
	v_lshlrev_b32_e32 v0, 3, v132
	v_mov_b32_e32 v1, v2
	s_ashr_i32 s40, s2, 6
	s_ashr_i32 s41, s2, 9
	v_mad_i64_i32 v[4:5], s[2:3], s22, v3, v[0:1]
	v_mad_i64_i32 v[6:7], s[2:3], s24, v3, v[0:1]
	v_readlane_b32 s47, v254, 35
	s_mul_hi_i32 s3, s22, s47
	s_mul_i32 s2, s22, s47
	s_ashr_i32 s23, s22, 31
	s_ashr_i32 s25, s24, 31
	s_lshl_b64 s[2:3], s[2:3], 1
	s_add_u32 s2, s78, s2
	s_addc_u32 s3, s79, s3
	v_lshlrev_b64 v[68:69], 1, v[4:5]
	v_readlane_b32 s46, v254, 33
	v_lshl_add_u64 v[0:1], s[2:3], 0, v[68:69]
	s_mul_hi_i32 s3, s24, s46
	s_mul_i32 s2, s24, s46
	s_lshl_b64 s[26:27], s[2:3], 1
	s_add_u32 s2, s0, s26
	s_addc_u32 s3, s1, s27
	v_lshlrev_b64 v[70:71], 1, v[6:7]
	v_lshl_add_u64 v[138:139], s[2:3], 0, v[70:71]
	s_lshl_b64 s[2:3], s[22:23], 6
	s_waitcnt vmcnt(0)
	v_lshl_add_u64 v[28:29], v[0:1], 0, s[2:3]
	s_lshl_b64 s[20:21], s[24:25], 6
	s_waitcnt vmcnt(0)
	v_lshl_add_u64 v[36:37], v[28:29], 0, s[2:3]
	s_waitcnt vmcnt(0)
	v_lshl_add_u64 v[56:57], v[138:139], 0, s[20:21]
	v_lshl_add_u64 v[40:41], v[36:37], 0, s[2:3]
	s_waitcnt vmcnt(0)
	v_lshl_add_u64 v[60:61], v[56:57], 0, s[20:21]
	s_waitcnt vmcnt(0)
	v_lshl_add_u64 v[64:65], v[60:61], 0, s[20:21]
	v_lshrrev_b32_e32 v8, 6, v194
	v_lshlrev_b32_e32 v8, 10, v8
	s_mov_b64 s[98:99], 0x80
	v_readfirstlane_b32 s100, v8
	s_add_u32 m0, s100, 0x0
	s_nop 0
	global_load_lds_dwordx4 v[0:1], off
	s_add_u32 m0, s100, 0x1000
	s_nop 0
	global_load_lds_dwordx4 v[28:29], off
	s_add_u32 m0, s100, 0x2000
	s_nop 0
	global_load_lds_dwordx4 v[36:37], off
	s_add_u32 m0, s100, 0x3000
	s_nop 0
	global_load_lds_dwordx4 v[40:41], off
	s_add_u32 m0, s100, 0x4000
	s_nop 0
	global_load_lds_dwordx4 v[138:139], off
	s_add_u32 m0, s100, 0x5000
	s_nop 0
	global_load_lds_dwordx4 v[56:57], off
	s_add_u32 m0, s100, 0x6000
	s_nop 0
	global_load_lds_dwordx4 v[60:61], off
	s_add_u32 m0, s100, 0x7000
	s_nop 0
	global_load_lds_dwordx4 v[64:65], off
	v_lshlrev_b32_e32 v72, 7, v3
	v_lshrrev_b32_e32 v3, 1, v3
	v_xor_b32_e32 v3, v3, v74
	v_lshl_add_u64 v[70:71], s[0:1], 0, v[70:71]
	v_readlane_b32 s0, v254, 34
	v_lshlrev_b32_e32 v3, 4, v3
	s_movk_i32 s6, 0x70
	v_lshl_add_u64 v[68:69], s[78:79], 0, v[68:69]
	s_mul_hi_i32 s1, s22, s0
	s_mul_i32 s0, s22, s0
	v_and_or_b32 v3, v3, s6, v72
	v_lshl_add_u64 v[72:73], s[0:1], 1, v[68:69]
	v_readlane_b32 s0, v254, 31
	s_mul_hi_i32 s1, s41, s0
	s_mul_i32 s0, s41, s0
	v_readlane_b32 s6, v254, 32
	s_lshl_b64 s[0:1], s[0:1], 1
	s_mul_hi_i32 s25, s24, s6
	s_mul_i32 s24, s24, s6
	v_lshl_add_u64 v[140:141], v[72:73], 0, s[0:1]
	v_lshl_add_u64 v[72:73], s[24:25], 1, v[70:71]
	v_lshl_add_u64 v[142:143], v[72:73], 0, s[0:1]
	s_mul_hi_i32 s1, s22, s54
	s_mul_i32 s0, s22, s54
	v_lshrrev_b32_e32 v75, 4, v74
	v_bfe_u32 v76, v74, 4, 2
	v_lshl_add_u64 v[144:145], s[0:1], 1, v[68:69]
	v_bfe_u32 v68, v74, 1, 3
	v_lshl_add_u64 v[146:147], v[70:71], 0, s[26:27]
	v_bitop3_b32 v69, v75, v68, 3 bitop3:0x6c
	v_lshlrev_b32_e32 v70, 6, v74
	v_lshlrev_b32_e32 v71, 7, v74
	v_bitop3_b32 v68, v76, v68, 4 bitop3:0x36
	v_lshlrev_b32_e32 v69, 4, v69
	v_and_b32_e32 v70, 0xffffe000, v70
	v_and_b32_e32 v72, 0x780, v71
	v_and_b32_e32 v71, 0x2000, v71
	v_lshlrev_b32_e32 v68, 4, v68
	v_or_b32_e32 v73, v69, v70
	v_or_b32_e32 v69, v69, v71
	v_or_b32_e32 v70, v68, v70
	v_or_b32_e32 v68, v68, v71
	s_mov_b32 s42, 0
	v_add_u32_e32 v137, v73, v72
	v_add_u32_e32 v192, v69, v72
	v_add_u32_e32 v193, v70, v72
	v_add_u32_e32 v214, v68, v72
	s_mov_b32 s43, s40
	s_mov_b32 s44, 0
	s_mov_b32 s45, 0
	v_and_b32_e32 v4, 15, v194
	v_lshrrev_b32_e32 v5, 1, v4
	v_bfe_u32 v6, v194, 4, 2
	v_xor_b32_e32 v5, v5, v6
	v_lshlrev_b32_e32 v5, 4, v5
	v_lshl_or_b32 v5, v4, 7, v5
	v_lshrrev_b32_e32 v6, 7, v194
	v_lshl_or_b32 v4, v6, 13, v5
	v_bfe_u32 v6, v194, 6, 1
	v_lshl_or_b32 v6, v6, 13, v5
	v_or_b32_e32 v6, 0x4000, v6
	v_xor_b32_e32 v5, 64, v4
	v_xor_b32_e32 v7, 64, v6
	s_waitcnt vmcnt(0) lgkmcnt(0)
	s_barrier
	s_branch .LBB0_138

.LBB0_144:
	s_cmp_lg_u32 s42, 2
	s_cselect_b64 s[22:23], -1, 0
	s_cmp_eq_u32 s42, 2
	s_cselect_b64 s[0:1], -1, 0
	s_cmp_lt_i32 s52, 1
	s_cbranch_scc1 .LBB0_161
	v_lshl_add_u64 v[152:153], v[0:1], 0, s[2:3]
	v_lshl_add_u64 v[158:159], v[138:139], 0, s[20:21]
	v_lshl_add_u64 v[164:165], v[150:151], 0, s[2:3]
	v_lshl_add_u64 v[170:171], v[148:149], 0, s[20:21]
	v_lshl_add_u64 v[154:155], v[152:153], 0, s[2:3]
	v_lshl_add_u64 v[160:161], v[158:159], 0, s[20:21]
	v_lshl_add_u64 v[166:167], v[164:165], 0, s[2:3]
	v_lshl_add_u64 v[172:173], v[170:171], 0, s[20:21]
	v_mov_b32_e32 v68, 0
	v_lshl_add_u64 v[156:157], v[154:155], 0, s[2:3]
	v_lshl_add_u64 v[162:163], v[160:161], 0, s[20:21]
	v_lshl_add_u64 v[168:169], v[166:167], 0, s[2:3]
	v_lshl_add_u64 v[174:175], v[172:173], 0, s[20:21]
	s_mov_b64 s[24:25], 0x80
	s_mov_b32 s53, 2
	v_mov_b32_e32 v69, v68
	v_mov_b32_e32 v70, v68
	v_mov_b32_e32 v71, v68
	v_mov_b32_e32 v72, v68
	v_mov_b32_e32 v73, v68
	v_mov_b32_e32 v74, v68
	v_mov_b32_e32 v75, v68
	v_mov_b32_e32 v76, v68
	v_mov_b32_e32 v77, v68
	v_mov_b32_e32 v78, v68
	v_mov_b32_e32 v79, v68
	v_mov_b32_e32 v80, v68
	v_mov_b32_e32 v81, v68
	v_mov_b32_e32 v82, v68
	v_mov_b32_e32 v83, v68
	v_mov_b32_e32 v84, v68
	v_mov_b32_e32 v85, v68
	v_mov_b32_e32 v86, v68
	v_mov_b32_e32 v87, v68
	v_mov_b32_e32 v88, v68
	v_mov_b32_e32 v89, v68
	v_mov_b32_e32 v90, v68
	v_mov_b32_e32 v91, v68
	v_mov_b32_e32 v92, v68
	v_mov_b32_e32 v93, v68
	v_mov_b32_e32 v94, v68
	v_mov_b32_e32 v95, v68
	v_mov_b32_e32 v96, v68
	v_mov_b32_e32 v97, v68
	v_mov_b32_e32 v98, v68
	v_mov_b32_e32 v99, v68
	v_mov_b32_e32 v100, v68
	v_mov_b32_e32 v101, v68
	v_mov_b32_e32 v102, v68
	v_mov_b32_e32 v103, v68
	v_mov_b32_e32 v104, v68
	v_mov_b32_e32 v105, v68
	v_mov_b32_e32 v106, v68
	v_mov_b32_e32 v107, v68
	v_mov_b32_e32 v108, v68
	v_mov_b32_e32 v109, v68
	v_mov_b32_e32 v110, v68
	v_mov_b32_e32 v111, v68
	v_mov_b32_e32 v116, v68
	v_mov_b32_e32 v117, v68
	v_mov_b32_e32 v118, v68
	v_mov_b32_e32 v119, v68
	v_mov_b32_e32 v112, v68
	v_mov_b32_e32 v113, v68
	v_mov_b32_e32 v114, v68
	v_mov_b32_e32 v115, v68
	v_mov_b32_e32 v120, v68
	v_mov_b32_e32 v121, v68
	v_mov_b32_e32 v122, v68
	v_mov_b32_e32 v123, v68
	v_mov_b32_e32 v124, v68
	v_mov_b32_e32 v125, v68
	v_mov_b32_e32 v126, v68
	v_mov_b32_e32 v127, v68
	v_mov_b32_e32 v128, v68
	v_mov_b32_e32 v129, v68
	v_mov_b32_e32 v130, v68
	v_mov_b32_e32 v131, v68
	s_branch .LBB0_147
.LBB0_147:
	v_lshl_add_u64 v[176:177], v[150:151], 0, s[24:25]
	v_lshl_add_u64 v[178:179], v[164:165], 0, s[24:25]
	v_lshl_add_u64 v[180:181], v[166:167], 0, s[24:25]
	v_lshl_add_u64 v[182:183], v[168:169], 0, s[24:25]
	v_lshl_add_u64 v[184:185], v[148:149], 0, s[24:25]
	v_lshl_add_u64 v[186:187], v[170:171], 0, s[24:25]
	v_lshl_add_u64 v[188:189], v[172:173], 0, s[24:25]
	v_lshl_add_u64 v[190:191], v[174:175], 0, s[24:25]
	ds_read_b128 v[8:11], v6
	ds_read_b128 v[12:15], v4
	ds_read_b128 v[16:19], v6 offset:2048
	ds_read_b128 v[20:23], v6 offset:4096
	ds_read_b128 v[24:27], v6 offset:6144
	ds_read_b128 v[28:31], v4 offset:2048
	ds_read_b128 v[32:35], v4 offset:4096
	ds_read_b128 v[36:39], v4 offset:6144
	s_branch .Lgd_body0_5

.Lgd_body0_5:
	s_cmp_lt_i32 s53, s52
	s_cselect_b64 s[30:31], -1, 0
	s_add_u32 m0, s100, 0x8000
	s_nop 0
	global_load_lds_dwordx4 v[176:177], off
	s_add_u32 m0, s100, 0x9000
	s_nop 0
	global_load_lds_dwordx4 v[178:179], off
	s_add_u32 m0, s100, 0xa000
	s_nop 0
	global_load_lds_dwordx4 v[180:181], off
	s_add_u32 m0, s100, 0xb000
	s_nop 0
	global_load_lds_dwordx4 v[182:183], off
	s_waitcnt lgkmcnt(7)
	ds_read_b128 v[40:43], v7
	ds_read_b128 v[44:47], v5
	ds_read_b128 v[48:51], v7 offset:2048
	ds_read_b128 v[52:55], v7 offset:4096
	ds_read_b128 v[56:59], v7 offset:6144
	ds_read_b128 v[60:63], v5 offset:2048
	ds_read_b128 v[64:67], v5 offset:4096
	ds_read_b128 v[132:135], v5 offset:6144
	s_add_u32 m0, s100, 0xc000
	s_waitcnt lgkmcnt(14)
	v_mfma_f32_16x16x32_bf16 v[128:131], v[8:11], v[12:15], v[128:131]
	global_load_lds_dwordx4 v[184:185], off
	s_waitcnt lgkmcnt(13)
	v_mfma_f32_16x16x32_bf16 v[124:127], v[16:19], v[12:15], v[124:127]
	s_waitcnt lgkmcnt(12)
	v_mfma_f32_16x16x32_bf16 v[120:123], v[20:23], v[12:15], v[120:123]
	s_waitcnt lgkmcnt(11)
	v_mfma_f32_16x16x32_bf16 v[112:115], v[24:27], v[12:15], v[112:115]
	s_add_u32 m0, s100, 0xd000
	s_waitcnt lgkmcnt(10)
	v_mfma_f32_16x16x32_bf16 v[116:119], v[8:11], v[28:31], v[116:119]
	global_load_lds_dwordx4 v[186:187], off
	v_mfma_f32_16x16x32_bf16 v[108:111], v[16:19], v[28:31], v[108:111]
	v_mfma_f32_16x16x32_bf16 v[104:107], v[20:23], v[28:31], v[104:107]
	v_mfma_f32_16x16x32_bf16 v[100:103], v[24:27], v[28:31], v[100:103]
	s_add_u32 m0, s100, 0xe000
	s_waitcnt lgkmcnt(9)
	v_mfma_f32_16x16x32_bf16 v[96:99], v[8:11], v[32:35], v[96:99]
	global_load_lds_dwordx4 v[188:189], off
	v_mfma_f32_16x16x32_bf16 v[92:95], v[16:19], v[32:35], v[92:95]
	v_mfma_f32_16x16x32_bf16 v[88:91], v[20:23], v[32:35], v[88:91]
	v_mfma_f32_16x16x32_bf16 v[84:87], v[24:27], v[32:35], v[84:87]
	s_add_u32 m0, s100, 0xf000
	s_waitcnt lgkmcnt(8)
	v_mfma_f32_16x16x32_bf16 v[80:83], v[8:11], v[36:39], v[80:83]
	global_load_lds_dwordx4 v[190:191], off
	v_mfma_f32_16x16x32_bf16 v[76:79], v[16:19], v[36:39], v[76:79]
	v_mfma_f32_16x16x32_bf16 v[72:75], v[20:23], v[36:39], v[72:75]
	v_mfma_f32_16x16x32_bf16 v[68:71], v[24:27], v[36:39], v[68:71]
	s_waitcnt lgkmcnt(6)
	v_mfma_f32_16x16x32_bf16 v[128:131], v[40:43], v[44:47], v[128:131]
	s_waitcnt lgkmcnt(5)
	v_mfma_f32_16x16x32_bf16 v[124:127], v[48:51], v[44:47], v[124:127]
	s_waitcnt lgkmcnt(4)
	v_mfma_f32_16x16x32_bf16 v[120:123], v[52:55], v[44:47], v[120:123]
	s_waitcnt lgkmcnt(3)
	v_mfma_f32_16x16x32_bf16 v[112:115], v[56:59], v[44:47], v[112:115]
	s_waitcnt lgkmcnt(2)
	v_mfma_f32_16x16x32_bf16 v[116:119], v[40:43], v[60:63], v[116:119]
	v_mfma_f32_16x16x32_bf16 v[108:111], v[48:51], v[60:63], v[108:111]
	v_mfma_f32_16x16x32_bf16 v[104:107], v[52:55], v[60:63], v[104:107]
	v_mfma_f32_16x16x32_bf16 v[100:103], v[56:59], v[60:63], v[100:103]
	s_and_b64 vcc, exec, s[30:31]
	s_cbranch_vccnz .Lgd_cur_5
	s_and_b64 vcc, exec, s[22:23]
	s_cbranch_vccnz .Lgd_next_5
	v_mov_b64_e32 v[176:177], v[150:151]
	v_mov_b64_e32 v[178:179], v[164:165]
	v_mov_b64_e32 v[180:181], v[166:167]
	v_mov_b64_e32 v[182:183], v[168:169]
	v_mov_b64_e32 v[184:185], v[148:149]
	v_mov_b64_e32 v[186:187], v[170:171]
	v_mov_b64_e32 v[188:189], v[172:173]
	v_mov_b64_e32 v[190:191], v[174:175]
	s_branch .Lgd_go_5
.Lgd_next_5:
	v_mov_b64_e32 v[176:177], v[0:1]
	v_mov_b64_e32 v[178:179], v[152:153]
	v_mov_b64_e32 v[180:181], v[154:155]
	v_mov_b64_e32 v[182:183], v[156:157]
	v_mov_b64_e32 v[184:185], v[138:139]
	v_mov_b64_e32 v[186:187], v[158:159]
	v_mov_b64_e32 v[188:189], v[160:161]
	v_mov_b64_e32 v[190:191], v[162:163]
	s_branch .Lgd_go_5
.Lgd_cur_5:
	v_lshl_add_u64 v[176:177], v[150:151], 0, s[24:25]
	v_lshl_add_u64 v[178:179], v[164:165], 0, s[24:25]
	v_lshl_add_u64 v[180:181], v[166:167], 0, s[24:25]
	v_lshl_add_u64 v[182:183], v[168:169], 0, s[24:25]
	v_lshl_add_u64 v[184:185], v[148:149], 0, s[24:25]
	v_lshl_add_u64 v[186:187], v[170:171], 0, s[24:25]
	v_lshl_add_u64 v[188:189], v[172:173], 0, s[24:25]
	v_lshl_add_u64 v[190:191], v[174:175], 0, s[24:25]
	v_lshl_add_u64 v[176:177], v[176:177], 0, s[98:99]
	v_lshl_add_u64 v[178:179], v[178:179], 0, s[98:99]
	v_lshl_add_u64 v[180:181], v[180:181], 0, s[98:99]
	v_lshl_add_u64 v[182:183], v[182:183], 0, s[98:99]
	v_lshl_add_u64 v[184:185], v[184:185], 0, s[98:99]
	v_lshl_add_u64 v[186:187], v[186:187], 0, s[98:99]
	v_lshl_add_u64 v[188:189], v[188:189], 0, s[98:99]
	v_lshl_add_u64 v[190:191], v[190:191], 0, s[98:99]
.Lgd_go_5:
	s_waitcnt vmcnt(0) lgkmcnt(0)
	s_barrier
	ds_read_b128 v[8:11], v6 offset:32768
	ds_read_b128 v[12:15], v4 offset:32768
	ds_read_b128 v[16:19], v6 offset:34816
	ds_read_b128 v[20:23], v6 offset:36864
	ds_read_b128 v[24:27], v6 offset:38912
	ds_read_b128 v[28:31], v4 offset:34816
	ds_read_b128 v[32:35], v4 offset:36864
	ds_read_b128 v[36:39], v4 offset:38912
	v_mfma_f32_16x16x32_bf16 v[96:99], v[40:43], v[64:67], v[96:99]
	v_mfma_f32_16x16x32_bf16 v[92:95], v[48:51], v[64:67], v[92:95]
	v_mfma_f32_16x16x32_bf16 v[88:91], v[52:55], v[64:67], v[88:91]
	v_mfma_f32_16x16x32_bf16 v[84:87], v[56:59], v[64:67], v[84:87]
	v_mfma_f32_16x16x32_bf16 v[80:83], v[40:43], v[132:135], v[80:83]
	v_mfma_f32_16x16x32_bf16 v[76:79], v[48:51], v[132:135], v[76:79]
	v_mfma_f32_16x16x32_bf16 v[72:75], v[52:55], v[132:135], v[72:75]
	v_mfma_f32_16x16x32_bf16 v[68:71], v[56:59], v[132:135], v[68:71]
	s_add_u32 m0, s100, 0x0
	s_nop 0
	global_load_lds_dwordx4 v[176:177], off
	s_add_u32 m0, s100, 0x1000
	s_nop 0
	global_load_lds_dwordx4 v[178:179], off
	s_add_u32 m0, s100, 0x2000
	s_nop 0
	global_load_lds_dwordx4 v[180:181], off
	s_add_u32 m0, s100, 0x3000
	s_nop 0
	global_load_lds_dwordx4 v[182:183], off
	s_waitcnt lgkmcnt(7)
	ds_read_b128 v[40:43], v7 offset:32768
	ds_read_b128 v[44:47], v5 offset:32768
	ds_read_b128 v[48:51], v7 offset:34816
	ds_read_b128 v[52:55], v7 offset:36864
	ds_read_b128 v[56:59], v7 offset:38912
	ds_read_b128 v[60:63], v5 offset:34816
	ds_read_b128 v[64:67], v5 offset:36864
	ds_read_b128 v[132:135], v5 offset:38912
	s_add_u32 m0, s100, 0x4000
	s_waitcnt lgkmcnt(14)
	v_mfma_f32_16x16x32_bf16 v[128:131], v[8:11], v[12:15], v[128:131]
	global_load_lds_dwordx4 v[184:185], off
	s_waitcnt lgkmcnt(13)
	v_mfma_f32_16x16x32_bf16 v[124:127], v[16:19], v[12:15], v[124:127]
	s_waitcnt lgkmcnt(12)
	v_mfma_f32_16x16x32_bf16 v[120:123], v[20:23], v[12:15], v[120:123]
	s_waitcnt lgkmcnt(11)
	v_mfma_f32_16x16x32_bf16 v[112:115], v[24:27], v[12:15], v[112:115]
	s_add_u32 m0, s100, 0x5000
	s_waitcnt lgkmcnt(10)
	v_mfma_f32_16x16x32_bf16 v[116:119], v[8:11], v[28:31], v[116:119]
	global_load_lds_dwordx4 v[186:187], off
	v_mfma_f32_16x16x32_bf16 v[108:111], v[16:19], v[28:31], v[108:111]
	v_mfma_f32_16x16x32_bf16 v[104:107], v[20:23], v[28:31], v[104:107]
	v_mfma_f32_16x16x32_bf16 v[100:103], v[24:27], v[28:31], v[100:103]
	s_add_u32 m0, s100, 0x6000
	s_waitcnt lgkmcnt(9)
	v_mfma_f32_16x16x32_bf16 v[96:99], v[8:11], v[32:35], v[96:99]
	global_load_lds_dwordx4 v[188:189], off
	v_mfma_f32_16x16x32_bf16 v[92:95], v[16:19], v[32:35], v[92:95]
	v_mfma_f32_16x16x32_bf16 v[88:91], v[20:23], v[32:35], v[88:91]
	v_mfma_f32_16x16x32_bf16 v[84:87], v[24:27], v[32:35], v[84:87]
	s_add_u32 m0, s100, 0x7000
	s_waitcnt lgkmcnt(8)
	v_mfma_f32_16x16x32_bf16 v[80:83], v[8:11], v[36:39], v[80:83]
	global_load_lds_dwordx4 v[190:191], off
	v_mfma_f32_16x16x32_bf16 v[76:79], v[16:19], v[36:39], v[76:79]
	v_mfma_f32_16x16x32_bf16 v[72:75], v[20:23], v[36:39], v[72:75]
	v_mfma_f32_16x16x32_bf16 v[68:71], v[24:27], v[36:39], v[68:71]
	s_waitcnt lgkmcnt(6)
	v_mfma_f32_16x16x32_bf16 v[128:131], v[40:43], v[44:47], v[128:131]
	s_waitcnt lgkmcnt(5)
	v_mfma_f32_16x16x32_bf16 v[124:127], v[48:51], v[44:47], v[124:127]
	s_waitcnt lgkmcnt(4)
	v_mfma_f32_16x16x32_bf16 v[120:123], v[52:55], v[44:47], v[120:123]
	s_waitcnt lgkmcnt(3)
	v_mfma_f32_16x16x32_bf16 v[112:115], v[56:59], v[44:47], v[112:115]
	s_waitcnt lgkmcnt(2)
	v_mfma_f32_16x16x32_bf16 v[116:119], v[40:43], v[60:63], v[116:119]
	v_mfma_f32_16x16x32_bf16 v[108:111], v[48:51], v[60:63], v[108:111]
	v_mfma_f32_16x16x32_bf16 v[104:107], v[52:55], v[60:63], v[104:107]
	v_mfma_f32_16x16x32_bf16 v[100:103], v[56:59], v[60:63], v[100:103]
	s_add_u32 s24, s24, 0x100
	s_addc_u32 s25, s25, 0
	s_add_i32 s53, s53, 2
	v_lshl_add_u64 v[176:177], v[150:151], 0, s[24:25]
	v_lshl_add_u64 v[178:179], v[164:165], 0, s[24:25]
	v_lshl_add_u64 v[180:181], v[166:167], 0, s[24:25]
	v_lshl_add_u64 v[182:183], v[168:169], 0, s[24:25]
	v_lshl_add_u64 v[184:185], v[148:149], 0, s[24:25]
	v_lshl_add_u64 v[186:187], v[170:171], 0, s[24:25]
	v_lshl_add_u64 v[188:189], v[172:173], 0, s[24:25]
	v_lshl_add_u64 v[190:191], v[174:175], 0, s[24:25]
	s_and_b64 vcc, exec, s[30:31]
	s_waitcnt vmcnt(0) lgkmcnt(0)
	s_barrier
	s_cbranch_vccnz .Lgd_top_5
	v_mfma_f32_16x16x32_bf16 v[96:99], v[40:43], v[64:67], v[96:99]
	v_mfma_f32_16x16x32_bf16 v[92:95], v[48:51], v[64:67], v[92:95]
	v_mfma_f32_16x16x32_bf16 v[88:91], v[52:55], v[64:67], v[88:91]
	v_mfma_f32_16x16x32_bf16 v[84:87], v[56:59], v[64:67], v[84:87]
	v_mfma_f32_16x16x32_bf16 v[80:83], v[40:43], v[132:135], v[80:83]
	v_mfma_f32_16x16x32_bf16 v[76:79], v[48:51], v[132:135], v[76:79]
	v_mfma_f32_16x16x32_bf16 v[72:75], v[52:55], v[132:135], v[72:75]
	v_mfma_f32_16x16x32_bf16 v[68:71], v[56:59], v[132:135], v[68:71]
	s_branch .LBB0_162

.LBB0_166:
	s_andn2_b64 vcc, exec, s[0:1]
	s_cbranch_vccnz .LBB0_191
	v_readlane_b32 s6, v253, 13
	s_waitcnt vmcnt(1)
	v_mov_b32_e32 v68, v194
	s_movk_i32 s0, 0x400
	s_movk_i32 s2, 0x400
	s_movk_i32 s3, 0x400
	v_readlane_b32 s7, v253, 14
	s_load_dword s1, s[6:7], 0x0
	v_readlane_b32 s6, v254, 30
	s_waitcnt lgkmcnt(0)
	s_lshr_b32 s46, s1, 3
	v_readlane_b32 s1, v254, 36
	s_mul_i32 s1, s46, s1
	s_add_i32 s1, s1, s6
	s_cmpk_gt_i32 s1, 0x10ff
	s_cbranch_scc1 .LBB0_191
	s_ashr_i32 s47, s3, 6
	s_lshl_b32 s3, s8, 1
	v_readlane_b32 s8, v252, 37
	v_readlane_b32 s18, v252, 47
	v_readlane_b32 s19, v252, 48
	s_add_u32 s24, s18, s3
	s_addc_u32 s25, s19, 0
	s_ashr_i32 s3, s1, 31
	s_lshr_b32 s3, s3, 24
	v_readlane_b32 s21, v252, 50
	s_add_i32 s3, s1, s3
	v_readlane_b32 s20, v252, 49
	s_ashr_i32 s3, s3, 8
	s_lshl_b32 s21, s1, 7
	v_lshlrev_b32_e32 v0, 3, v68
	v_ashrrev_i32_e32 v3, 3, v68
	s_lshl_b32 s20, s3, 10
	s_and_b32 s21, s21, 0x380
	v_and_b32_e32 v0, 56, v0
	v_lshrrev_b32_e32 v132, 4, v68
	v_xor_b32_e32 v132, v132, v68
	v_and_b32_e32 v132, 7, v132
	v_lshlrev_b32_e32 v0, 3, v132
	v_mov_b32_e32 v1, v2
	s_or_b32 s53, s20, s21
	s_lshl_b32 s3, s3, 12
	s_lshl_b32 s1, s1, 4
	v_mad_i64_i32 v[4:5], s[20:21], s0, v3, v[0:1]
	v_mad_i64_i32 v[0:1], s[20:21], s2, v3, v[0:1]
	s_sub_i32 s1, s1, s3
	s_mul_hi_i32 s21, s53, s0
	s_mul_i32 s20, s53, s0
	s_and_b32 s52, s1, 0xffffff80
	s_ashr_i32 s1, s0, 31
	s_ashr_i32 s3, s2, 31
	s_lshl_b64 s[20:21], s[20:21], 1
	s_add_u32 s20, s76, s20
	s_addc_u32 s21, s77, s21
	v_lshlrev_b64 v[70:71], 1, v[4:5]
	v_lshl_add_u64 v[144:145], s[20:21], 0, v[70:71]
	s_mul_hi_i32 s21, s52, s2
	s_mul_i32 s20, s52, s2
	s_lshl_b64 s[20:21], s[20:21], 1
	s_add_u32 s20, s24, s20
	s_addc_u32 s21, s25, s21
	s_waitcnt vmcnt(0)
	v_lshlrev_b64 v[72:73], 1, v[0:1]
	v_readlane_b32 s22, v252, 51
	v_readlane_b32 s23, v252, 52
	v_lshl_add_u64 v[146:147], s[20:21], 0, v[72:73]
	s_lshl_b64 s[20:21], s[0:1], 6
	v_lshl_add_u64 v[0:1], v[144:145], 0, s[20:21]
	s_lshl_b64 s[22:23], s[2:3], 6
	s_waitcnt vmcnt(0)
	v_lshl_add_u64 v[36:37], v[0:1], 0, s[20:21]
	s_waitcnt vmcnt(0)
	v_lshl_add_u64 v[56:57], v[146:147], 0, s[22:23]
	v_lshl_add_u64 v[40:41], v[36:37], 0, s[20:21]
	s_waitcnt vmcnt(0)
	v_lshl_add_u64 v[60:61], v[56:57], 0, s[22:23]
	s_waitcnt vmcnt(0)
	v_lshl_add_u64 v[64:65], v[60:61], 0, s[22:23]
	s_bfe_u32 s100, s101, 0x20002
	s_lshl_b32 s100, s100, 10
	s_bfe_u32 vcc_lo, s101, 0x80008
	s_add_u32 vcc_lo, vcc_lo, 0
	s_add_u32 vcc_hi, s47, -1
	s_and_b32 vcc_lo, vcc_lo, vcc_hi
	s_lshl_b32 vcc_lo, vcc_lo, 7
	s_mov_b32 vcc_hi, 0
	v_lshl_add_u64 v[20:21], v[144:145], 0, vcc
	s_add_u32 m0, s100, 0x0
	s_nop 0
	global_load_lds_dwordx4 v[20:21], off
	v_lshl_add_u64 v[20:21], v[0:1], 0, vcc
	s_add_u32 m0, s100, 0x1000
	s_nop 0
	global_load_lds_dwordx4 v[20:21], off
	v_lshl_add_u64 v[20:21], v[36:37], 0, vcc
	s_add_u32 m0, s100, 0x2000
	s_nop 0
	global_load_lds_dwordx4 v[20:21], off
	v_lshl_add_u64 v[20:21], v[40:41], 0, vcc
	s_add_u32 m0, s100, 0x3000
	s_nop 0
	global_load_lds_dwordx4 v[20:21], off
	v_lshl_add_u64 v[20:21], v[146:147], 0, vcc
	s_add_u32 m0, s100, 0x4000
	s_nop 0
	global_load_lds_dwordx4 v[20:21], off
	v_lshl_add_u64 v[20:21], v[56:57], 0, vcc
	s_add_u32 m0, s100, 0x5000
	s_nop 0
	global_load_lds_dwordx4 v[20:21], off
	v_lshl_add_u64 v[20:21], v[60:61], 0, vcc
	s_add_u32 m0, s100, 0x6000
	s_nop 0
	global_load_lds_dwordx4 v[20:21], off
	v_lshl_add_u64 v[20:21], v[64:65], 0, vcc
	s_add_u32 m0, s100, 0x7000
	s_nop 0
	global_load_lds_dwordx4 v[20:21], off
	s_bfe_u32 vcc_lo, s101, 0x80008
	s_add_u32 vcc_lo, vcc_lo, 1
	s_add_u32 vcc_hi, s47, -1
	s_and_b32 vcc_lo, vcc_lo, vcc_hi
	s_lshl_b32 vcc_lo, vcc_lo, 7
	s_mov_b32 vcc_hi, 0
	v_lshl_add_u64 v[20:21], v[144:145], 0, vcc
	s_add_u32 m0, s100, 0x8000
	s_nop 0
	global_load_lds_dwordx4 v[20:21], off
	v_lshl_add_u64 v[20:21], v[0:1], 0, vcc
	s_add_u32 m0, s100, 0x9000
	s_nop 0
	global_load_lds_dwordx4 v[20:21], off
	v_lshl_add_u64 v[20:21], v[36:37], 0, vcc
	s_add_u32 m0, s100, 0xa000
	s_nop 0
	global_load_lds_dwordx4 v[20:21], off
	v_lshl_add_u64 v[20:21], v[40:41], 0, vcc
	s_add_u32 m0, s100, 0xb000
	s_nop 0
	global_load_lds_dwordx4 v[20:21], off
	v_lshl_add_u64 v[20:21], v[146:147], 0, vcc
	s_add_u32 m0, s100, 0xc000
	s_nop 0
	global_load_lds_dwordx4 v[20:21], off
	v_lshl_add_u64 v[20:21], v[56:57], 0, vcc
	s_add_u32 m0, s100, 0xd000
	s_nop 0
	global_load_lds_dwordx4 v[20:21], off
	v_lshl_add_u64 v[20:21], v[60:61], 0, vcc
	s_add_u32 m0, s100, 0xe000
	s_nop 0
	global_load_lds_dwordx4 v[20:21], off
	v_lshl_add_u64 v[20:21], v[64:65], 0, vcc
	s_add_u32 m0, s100, 0xf000
	s_nop 0
	global_load_lds_dwordx4 v[20:21], off
	v_lshrrev_b32_e32 v1, 1, v3
	v_xor_b32_e32 v1, v1, v68
	v_lshlrev_b32_e32 v0, 7, v3
	v_lshlrev_b32_e32 v1, 4, v1
	s_movk_i32 s1, 0x70
	v_lshrrev_b32_e32 v69, 4, v68
	v_bfe_u32 v74, v68, 4, 2
	v_and_or_b32 v3, v1, s1, v0
	v_lshl_add_u64 v[0:1], s[76:77], 0, v[70:71]
	v_bfe_u32 v70, v68, 1, 3
	v_bitop3_b32 v69, v69, v70, 3 bitop3:0x6c
	v_lshlrev_b32_e32 v71, 6, v68
	v_lshlrev_b32_e32 v68, 7, v68
	v_bitop3_b32 v70, v74, v70, 4 bitop3:0x36
	v_lshl_add_u64 v[138:139], s[24:25], 0, v[72:73]
	v_lshlrev_b32_e32 v69, 4, v69
	v_and_b32_e32 v71, 0xffffe000, v71
	v_and_b32_e32 v72, 0x780, v68
	v_and_b32_e32 v68, 0x2000, v68
	v_lshlrev_b32_e32 v70, 4, v70
	s_cmp_gt_i32 s47, 0
	v_or_b32_e32 v73, v69, v71
	v_or_b32_e32 v69, v69, v68
	v_or_b32_e32 v71, v70, v71
	v_or_b32_e32 v68, v70, v68
	s_mov_b32 s1, 0
	s_cselect_b64 s[24:25], -1, 0
	v_add_u32_e32 v137, v73, v72
	v_add_u32_e32 v188, v69, v72
	v_add_u32_e32 v189, v71, v72
	v_add_u32_e32 v190, v68, v72
	s_mov_b32 s3, 0
	s_mov_b32 s49, 0
	v_readlane_b32 s9, v252, 38
	v_readlane_b32 s10, v252, 39
	v_readlane_b32 s11, v252, 40
	v_readlane_b32 s12, v252, 41
	v_readlane_b32 s13, v252, 42
	v_readlane_b32 s14, v252, 43
	v_readlane_b32 s15, v252, 44
	v_readlane_b32 s16, v252, 45
	v_readlane_b32 s17, v252, 46
	s_bfe_u32 vcc_lo, s101, 0x10001
	v_and_b32_e32 v20, 15, v194
	v_lshrrev_b32_e32 v21, 1, v20
	v_bfe_u32 v22, v194, 4, 2
	v_xor_b32_e32 v21, v21, v22
	v_lshlrev_b32_e32 v21, 4, v21
	v_lshl_or_b32 v250, v20, 7, v21
	v_mov_b32_e32 v22, vcc_lo
	v_lshl_or_b32 v22, v22, 13, v250
	v_or_b32_e32 v251, 0x4000, v22
	v_and_b32_e32 v20, 63, v194
	v_mov_b32_e32 v21, vcc_lo
	v_lshlrev_b32_e32 v21, 4, v21
	v_lshrrev_b32_e32 v22, 3, v20
	v_add_u32_e32 v21, v21, v22
	v_lshrrev_b32_e32 v22, 4, v20
	v_and_b32_e32 v23, 7, v20
	v_xor_b32_e32 v24, v23, v22
	v_lshlrev_b32_e32 v24, 4, v24
	v_or_b32_e32 v22, 4, v22
	v_xor_b32_e32 v25, v23, v22
	v_lshlrev_b32_e32 v25, 4, v25
	s_lshl_b32 s98, s0, 1
	s_lshl_b32 s99, s2, 1
	v_add_u32_e32 v26, 0, v21
	v_mad_u32_u24 v4, v26, s98, v24
	v_add_u32_e32 v26, 8, v21
	v_mad_u32_u24 v5, v26, s98, v25
	v_add_u32_e32 v26, 32, v21
	v_mad_u32_u24 v6, v26, s98, v24
	v_add_u32_e32 v26, 40, v21
	v_mad_u32_u24 v7, v26, s98, v25
	v_add_u32_e32 v26, 64, v21
	v_mad_u32_u24 v8, v26, s98, v24
	v_add_u32_e32 v26, 72, v21
	v_mad_u32_u24 v9, v26, s98, v25
	v_add_u32_e32 v26, 96, v21
	v_mad_u32_u24 v10, v26, s98, v24
	v_add_u32_e32 v26, 104, v21
	v_mad_u32_u24 v11, v26, s98, v25
	v_add_u32_e32 v26, 0, v21
	v_mad_u32_u24 v12, v26, s99, v24
	v_add_u32_e32 v26, 8, v21
	v_mad_u32_u24 v13, v26, s99, v25
	v_add_u32_e32 v26, 32, v21
	v_mad_u32_u24 v14, v26, s99, v24
	v_add_u32_e32 v26, 40, v21
	v_mad_u32_u24 v15, v26, s99, v25
	v_add_u32_e32 v26, 64, v21
	v_mad_u32_u24 v16, v26, s99, v24
	v_add_u32_e32 v26, 72, v21
	v_mad_u32_u24 v17, v26, s99, v25
	v_add_u32_e32 v26, 96, v21
	v_mad_u32_u24 v18, v26, s99, v24
	v_add_u32_e32 v26, 104, v21
	v_mad_u32_u24 v19, v26, s99, v25
	s_bfe_u32 vcc_hi, s101, 0x20002
	s_lshl_b32 vcc_hi, vcc_hi, 3
	s_mul_i32 s98, s98, vcc_hi
	s_mul_i32 s99, s99, vcc_hi
	s_lshl_b32 vcc_hi, vcc_hi, 3
	s_and_b32 vcc_hi, vcc_hi, 0x70
	s_add_u32 s98, s98, vcc_hi
	s_add_u32 s99, s99, vcc_hi
	s_lshl_b32 s100, vcc_lo, 11
	s_bitcmp1_b32 s101, 0
	s_cselect_b32 s100, -1, s100
	s_waitcnt vmcnt(0) lgkmcnt(0)
	s_barrier
	s_branch .LBB0_171

.LBB0_170:
	v_mov_b32_e32 v132, v194
	v_mov_b32_e32 v133, v194
	v_and_b32_e32 v145, 64, v202
	v_and_b32_e32 v134, 64, v133
	v_ashrrev_i32_e32 v133, 1, v133
	v_and_b32_e32 v135, 15, v132
	v_and_b32_e32 v133, 0xffffffc0, v133
	v_max_f32_e32 v112, v112, v112
	v_max_f32_e32 v113, v113, v113
	v_max_f32_e32 v108, v108, v108
	v_max_f32_e32 v109, v109, v109
	v_max_f32_e32 v96, v96, v96
	v_max_f32_e32 v97, v97, v97
	v_max_f32_e32 v92, v92, v92
	v_max_f32_e32 v93, v93, v93
	v_max_f32_e32 v80, v80, v80
	v_max_f32_e32 v81, v81, v81
	v_max_f32_e32 v76, v76, v76
	v_max_f32_e32 v77, v77, v77
	v_add3_u32 v144, v135, s53, v133
	v_xor_b32_e32 v135, 16, v202
	v_add_u32_e32 v145, 64, v145
	v_max_f32_e32 v128, v128, v128
	v_max_f32_e32 v129, v129, v129
	v_max_f32_e32 v130, v130, v130
	v_max_f32_e32 v131, v131, v131
	v_max_f32_e32 v124, v124, v124
	v_max_f32_e32 v125, v125, v125
	v_max_f32_e32 v126, v126, v126
	v_max_f32_e32 v127, v127, v127
	v_max_f32_e32 v112, 0, v112
	v_max_f32_e32 v113, 0, v113
	v_max_f32_e32 v108, 0, v108
	v_max_f32_e32 v109, 0, v109
	v_max_f32_e32 v106, v106, v106
	v_max_f32_e32 v107, v107, v107
	v_max_f32_e32 v100, v100, v100
	v_max_f32_e32 v101, v101, v101
	v_max_f32_e32 v96, 0, v96
	v_max_f32_e32 v97, 0, v97
	v_max_f32_e32 v92, 0, v92
	v_max_f32_e32 v93, 0, v93
	v_max_f32_e32 v90, v90, v90
	v_max_f32_e32 v91, v91, v91
	v_max_f32_e32 v84, v84, v84
	v_max_f32_e32 v85, v85, v85
	v_max_f32_e32 v80, 0, v80
	v_max_f32_e32 v81, 0, v81
	v_max_f32_e32 v76, 0, v76
	v_max_f32_e32 v77, 0, v77
	v_max_f32_e32 v74, v74, v74
	v_max_f32_e32 v75, v75, v75
	v_max_f32_e32 v68, v68, v68
	v_max_f32_e32 v69, v69, v69
	v_and_b32_e32 v133, 16, v132
	v_cmp_lt_i32_e32 vcc, v135, v145
	v_max_f32_e32 v128, 0, v128
	v_max_f32_e32 v129, 0, v129
	v_max_f32_e32 v130, 0, v130
	v_max_f32_e32 v131, 0, v131
	v_max_f32_e32 v124, 0, v124
	v_max_f32_e32 v125, 0, v125
	v_max_f32_e32 v126, 0, v126
	v_max_f32_e32 v127, 0, v127
	v_max_f32_e32 v116, v116, v116
	v_max_f32_e32 v117, v117, v117
	v_pk_mul_f32 v[112:113], v[112:113], v[112:113]
	v_pk_mul_f32 v[108:109], v[108:109], v[108:109]
	v_max_f32_e32 v110, v110, v110
	v_max_f32_e32 v111, v111, v111
	v_max_f32_e32 v106, 0, v106
	v_max_f32_e32 v107, 0, v107
	v_max_f32_e32 v100, 0, v100
	v_max_f32_e32 v101, 0, v101
	v_max_f32_e32 v102, v102, v102
	v_max_f32_e32 v103, v103, v103
	v_pk_mul_f32 v[96:97], v[96:97], v[96:97]
	v_pk_mul_f32 v[92:93], v[92:93], v[92:93]
	v_max_f32_e32 v94, v94, v94
	v_max_f32_e32 v95, v95, v95
	v_max_f32_e32 v90, 0, v90
	v_max_f32_e32 v91, 0, v91
	v_max_f32_e32 v84, 0, v84
	v_max_f32_e32 v85, 0, v85
	v_max_f32_e32 v86, v86, v86
	v_max_f32_e32 v87, v87, v87
	v_pk_mul_f32 v[80:81], v[80:81], v[80:81]
	v_pk_mul_f32 v[76:77], v[76:77], v[76:77]
	v_max_f32_e32 v78, v78, v78
	v_max_f32_e32 v79, v79, v79
	v_max_f32_e32 v74, 0, v74
	v_max_f32_e32 v75, 0, v75
	v_max_f32_e32 v68, 0, v68
	v_max_f32_e32 v69, 0, v69
	v_max_f32_e32 v70, v70, v70
	v_max_f32_e32 v71, v71, v71
	v_cndmask_b32_e32 v135, v202, v135, vcc
	v_pk_mul_f32 v[128:129], v[128:129], v[128:129]
	v_pk_mul_f32 v[130:131], v[130:131], v[130:131]
	v_pk_mul_f32 v[124:125], v[124:125], v[124:125]
	v_pk_mul_f32 v[126:127], v[126:127], v[126:127]
	v_max_f32_e32 v120, v120, v120
	v_max_f32_e32 v121, v121, v121
	v_max_f32_e32 v116, 0, v116
	v_max_f32_e32 v117, 0, v117
	v_cmp_eq_u32_e32 vcc, 0, v133
	v_cvt_pk_bf16_f32 v112, v112, v113
	v_max_f32_e32 v110, 0, v110
	v_max_f32_e32 v111, 0, v111
	v_cvt_pk_bf16_f32 v108, v108, v109
	v_pk_mul_f32 v[106:107], v[106:107], v[106:107]
	v_pk_mul_f32 v[100:101], v[100:101], v[100:101]
	v_max_f32_e32 v102, 0, v102
	v_max_f32_e32 v103, 0, v103
	v_cvt_pk_bf16_f32 v96, v96, v97
	v_max_f32_e32 v94, 0, v94
	v_max_f32_e32 v95, 0, v95
	v_cvt_pk_bf16_f32 v92, v92, v93
	v_pk_mul_f32 v[90:91], v[90:91], v[90:91]
	v_pk_mul_f32 v[84:85], v[84:85], v[84:85]
	v_max_f32_e32 v86, 0, v86
	v_max_f32_e32 v87, 0, v87
	v_cvt_pk_bf16_f32 v80, v80, v81
	v_max_f32_e32 v78, 0, v78
	v_max_f32_e32 v79, 0, v79
	v_cvt_pk_bf16_f32 v76, v76, v77
	v_pk_mul_f32 v[74:75], v[74:75], v[74:75]
	v_pk_mul_f32 v[68:69], v[68:69], v[68:69]
	v_max_f32_e32 v70, 0, v70
	v_max_f32_e32 v71, 0, v71
	v_lshlrev_b32_e32 v135, 2, v135
	v_cvt_pk_bf16_f32 v128, v128, v129
	v_cvt_pk_bf16_f32 v129, v130, v131
	v_cvt_pk_bf16_f32 v124, v124, v125
	v_cvt_pk_bf16_f32 v125, v126, v127
	v_max_f32_e32 v120, 0, v120
	v_max_f32_e32 v121, 0, v121
	v_pk_mul_f32 v[116:117], v[116:117], v[116:117]
	v_pk_mul_f32 v[110:111], v[110:111], v[110:111]
	v_cvt_pk_bf16_f32 v106, v106, v107
	v_pk_mul_f32 v[102:103], v[102:103], v[102:103]
	v_cvt_pk_bf16_f32 v107, v100, v101
	v_cndmask_b32_e32 v101, v112, v108, vcc
	v_pk_mul_f32 v[94:95], v[94:95], v[94:95]
	v_cvt_pk_bf16_f32 v90, v90, v91
	v_pk_mul_f32 v[86:87], v[86:87], v[86:87]
	v_cvt_pk_bf16_f32 v91, v84, v85
	v_cndmask_b32_e32 v85, v96, v92, vcc
	v_pk_mul_f32 v[78:79], v[78:79], v[78:79]
	v_cvt_pk_bf16_f32 v74, v74, v75
	v_pk_mul_f32 v[70:71], v[70:71], v[70:71]
	v_cvt_pk_bf16_f32 v75, v68, v69
	v_cndmask_b32_e32 v69, v80, v76, vcc
	v_pk_mul_f32 v[120:121], v[120:121], v[120:121]
	v_cvt_pk_bf16_f32 v130, v116, v117
	v_cndmask_b32_e32 v116, v128, v124, vcc
	v_cndmask_b32_e32 v117, v129, v125, vcc
	v_max_f32_e32 v114, v114, v114
	v_max_f32_e32 v115, v115, v115
	v_cvt_pk_bf16_f32 v109, v110, v111
	v_cvt_pk_bf16_f32 v111, v102, v103
	ds_bpermute_b32 v103, v135, v101
	v_max_f32_e32 v98, v98, v98
	v_max_f32_e32 v99, v99, v99
	v_cvt_pk_bf16_f32 v93, v94, v95
	v_cvt_pk_bf16_f32 v95, v86, v87
	ds_bpermute_b32 v87, v135, v85
	v_max_f32_e32 v82, v82, v82
	v_max_f32_e32 v83, v83, v83
	v_cvt_pk_bf16_f32 v77, v78, v79
	v_cvt_pk_bf16_f32 v79, v70, v71
	ds_bpermute_b32 v71, v135, v69
	v_lshrrev_b32_e32 v132, 2, v132
	v_max_f32_e32 v122, v122, v122
	v_max_f32_e32 v123, v123, v123
	v_cvt_pk_bf16_f32 v126, v120, v121
	v_max_f32_e32 v118, v118, v118
	v_max_f32_e32 v119, v119, v119
	ds_bpermute_b32 v120, v135, v116
	ds_bpermute_b32 v121, v135, v117
	v_max_f32_e32 v114, 0, v114
	v_max_f32_e32 v115, 0, v115
	v_max_f32_e32 v104, v104, v104
	v_max_f32_e32 v105, v105, v105
	v_max_f32_e32 v98, 0, v98
	v_max_f32_e32 v99, 0, v99
	v_max_f32_e32 v88, v88, v88
	v_max_f32_e32 v89, v89, v89
	v_max_f32_e32 v82, 0, v82
	v_max_f32_e32 v83, 0, v83
	v_max_f32_e32 v72, v72, v72
	v_max_f32_e32 v73, v73, v73
	v_and_b32_e32 v132, 8, v132
	v_add_u32_e32 v145, s52, v133
	v_max_f32_e32 v122, 0, v122
	v_max_f32_e32 v123, 0, v123
	v_max_f32_e32 v118, 0, v118
	v_max_f32_e32 v119, 0, v119
	v_pk_mul_f32 v[114:115], v[114:115], v[114:115]
	v_max_f32_e32 v104, 0, v104
	v_max_f32_e32 v105, 0, v105
	v_add_u32_e32 v100, 16, v144
	v_pk_mul_f32 v[98:99], v[98:99], v[98:99]
	v_max_f32_e32 v88, 0, v88
	v_max_f32_e32 v89, 0, v89
	v_add_u32_e32 v84, 32, v144
	v_pk_mul_f32 v[82:83], v[82:83], v[82:83]
	v_max_f32_e32 v72, 0, v72
	v_max_f32_e32 v73, 0, v73
	v_add_u32_e32 v68, 48, v144
	v_add3_u32 v132, v145, v134, v132
	v_pk_mul_f32 v[122:123], v[122:123], v[122:123]
	v_pk_mul_f32 v[118:119], v[118:119], v[118:119]
	v_ashrrev_i32_e32 v145, 31, v144
	v_cvt_pk_bf16_f32 v113, v114, v115
	v_pk_mul_f32 v[104:105], v[104:105], v[104:105]
	v_ashrrev_i32_e32 v101, 31, v100
	v_cvt_pk_bf16_f32 v97, v98, v99
	v_pk_mul_f32 v[88:89], v[88:89], v[88:89]
	v_ashrrev_i32_e32 v85, 31, v84
	v_cvt_pk_bf16_f32 v81, v82, v83
	v_pk_mul_f32 v[72:73], v[72:73], v[72:73]
	v_ashrrev_i32_e32 v69, 31, v68
	v_cvt_pk_bf16_f32 v127, v122, v123
	v_cvt_pk_bf16_f32 v131, v118, v119
	v_lshlrev_b64 v[116:117], 13, v[144:145]
	v_cvt_pk_bf16_f32 v110, v104, v105
	v_cndmask_b32_e32 v102, v113, v109, vcc
	v_lshlrev_b64 v[100:101], 13, v[100:101]
	v_cvt_pk_bf16_f32 v94, v88, v89
	v_cndmask_b32_e32 v86, v97, v93, vcc
	v_lshlrev_b64 v[84:85], 13, v[84:85]
	v_cvt_pk_bf16_f32 v78, v72, v73
	v_cndmask_b32_e32 v70, v81, v77, vcc
	v_lshlrev_b64 v[68:69], 13, v[68:69]
	v_lshl_add_u64 v[122:123], s[78:79], 0, v[116:117]
	v_cndmask_b32_e32 v116, v126, v130, vcc
	v_cndmask_b32_e32 v117, v127, v131, vcc
	ds_bpermute_b32 v114, v135, v102
	v_lshl_add_u64 v[104:105], s[78:79], 0, v[100:101]
	s_waitcnt lgkmcnt(5)
	v_cndmask_b32_e32 v100, v103, v112, vcc
	v_cndmask_b32_e32 v102, v108, v103, vcc
	v_cndmask_b32_e32 v103, v110, v107, vcc
	v_cndmask_b32_e32 v108, v106, v111, vcc
	ds_bpermute_b32 v98, v135, v86
	v_lshl_add_u64 v[88:89], s[78:79], 0, v[84:85]
	s_waitcnt lgkmcnt(5)
	v_cndmask_b32_e32 v84, v87, v96, vcc
	v_cndmask_b32_e32 v86, v92, v87, vcc
	v_cndmask_b32_e32 v87, v94, v91, vcc
	v_cndmask_b32_e32 v92, v90, v95, vcc
	ds_bpermute_b32 v82, v135, v70
	v_lshl_add_u64 v[72:73], s[78:79], 0, v[68:69]
	s_waitcnt lgkmcnt(5)
	v_cndmask_b32_e32 v68, v71, v80, vcc
	v_cndmask_b32_e32 v70, v76, v71, vcc
	v_cndmask_b32_e32 v71, v78, v75, vcc
	v_cndmask_b32_e32 v76, v74, v79, vcc
	s_waitcnt lgkmcnt(4)
	v_cndmask_b32_e32 v118, v120, v128, vcc
	s_waitcnt lgkmcnt(3)
	v_cndmask_b32_e32 v119, v121, v129, vcc
	v_cndmask_b32_e32 v120, v124, v120, vcc
	v_cndmask_b32_e32 v121, v125, v121, vcc
	ds_bpermute_b32 v124, v135, v116
	ds_bpermute_b32 v125, v135, v117
	ds_bpermute_b32 v112, v135, v103
	ds_bpermute_b32 v108, v135, v108
	ds_bpermute_b32 v96, v135, v87
	ds_bpermute_b32 v92, v135, v92
	ds_bpermute_b32 v80, v135, v71
	ds_bpermute_b32 v76, v135, v76
	v_ashrrev_i32_e32 v133, 31, v132
	v_lshlrev_b64 v[116:117], 1, v[132:133]
	v_lshl_add_u64 v[122:123], v[122:123], 0, v[116:117]
	s_waitcnt lgkmcnt(10)
	v_cndmask_b32_e32 v101, v114, v113, vcc
	v_cndmask_b32_e32 v103, v109, v114, vcc
	v_lshl_add_u64 v[104:105], v[104:105], 0, v[116:117]
	s_waitcnt lgkmcnt(9)
	v_cndmask_b32_e32 v85, v98, v97, vcc
	v_cndmask_b32_e32 v87, v93, v98, vcc
	v_lshl_add_u64 v[88:89], v[88:89], 0, v[116:117]
	s_waitcnt lgkmcnt(8)
	v_cndmask_b32_e32 v69, v82, v81, vcc
	v_cndmask_b32_e32 v71, v77, v82, vcc
	v_lshl_add_u64 v[72:73], v[72:73], 0, v[116:117]
	global_store_dwordx4 v[122:123], v[118:121], off
	global_store_dwordx4 v[104:105], v[100:103], off
	global_store_dwordx4 v[88:89], v[84:87], off
	s_waitcnt lgkmcnt(7)
	v_cndmask_b32_e32 v118, v124, v126, vcc
	s_waitcnt lgkmcnt(6)
	v_cndmask_b32_e32 v119, v125, v127, vcc
	v_cndmask_b32_e32 v120, v130, v124, vcc
	v_cndmask_b32_e32 v121, v131, v125, vcc
	s_waitcnt lgkmcnt(5)
	v_cndmask_b32_e32 v100, v112, v110, vcc
	s_waitcnt lgkmcnt(4)
	v_cndmask_b32_e32 v101, v108, v106, vcc
	v_cndmask_b32_e32 v102, v107, v112, vcc
	v_cndmask_b32_e32 v103, v111, v108, vcc
	s_waitcnt lgkmcnt(3)
	v_cndmask_b32_e32 v84, v96, v94, vcc
	s_waitcnt lgkmcnt(2)
	v_cndmask_b32_e32 v85, v92, v90, vcc
	v_cndmask_b32_e32 v86, v91, v96, vcc
	v_cndmask_b32_e32 v87, v95, v92, vcc
	global_store_dwordx4 v[72:73], v[68:71], off
	s_mov_b32 s53, s1
	s_mov_b32 s52, s3
	s_waitcnt lgkmcnt(1)
	v_cndmask_b32_e32 v68, v80, v78, vcc
	s_waitcnt lgkmcnt(0)
	v_cndmask_b32_e32 v69, v76, v74, vcc
	v_cndmask_b32_e32 v70, v75, v80, vcc
	v_cndmask_b32_e32 v71, v79, v76, vcc
	s_and_b64 vcc, exec, s[26:27]
	v_mov_b64_e32 v[146:147], v[142:143]
	v_mov_b64_e32 v[144:145], v[140:141]
	global_store_dwordx4 v[122:123], v[118:121], off offset:64
	global_store_dwordx4 v[104:105], v[100:103], off offset:64
	global_store_dwordx4 v[88:89], v[84:87], off offset:64
	global_store_dwordx4 v[72:73], v[68:71], off offset:64
	s_branch .Lpc_edone_2

.LBB0_173:
	s_mul_hi_i32 s35, s1, s0
	s_mul_i32 s34, s1, s0
	v_lshl_add_u64 v[140:141], s[34:35], 1, v[0:1]
	s_mul_hi_i32 s35, s3, s2
	s_mul_i32 s34, s3, s2
	v_lshl_add_u64 v[142:143], s[34:35], 1, v[138:139]
	s_andn2_b64 vcc, exec, s[24:25]
	s_cbranch_vccnz .LBB0_190
	v_lshl_add_u64 v[148:149], v[140:141], 0, s[20:21]
	v_lshl_add_u64 v[154:155], v[142:143], 0, s[22:23]
	v_lshl_add_u64 v[160:161], v[144:145], 0, s[20:21]
	v_lshl_add_u64 v[166:167], v[146:147], 0, s[22:23]
	v_lshl_add_u64 v[150:151], v[148:149], 0, s[20:21]
	v_lshl_add_u64 v[156:157], v[154:155], 0, s[22:23]
	v_lshl_add_u64 v[162:163], v[160:161], 0, s[20:21]
	v_lshl_add_u64 v[168:169], v[166:167], 0, s[22:23]
	v_mov_b32_e32 v68, 0
	v_lshl_add_u64 v[152:153], v[150:151], 0, s[20:21]
	v_lshl_add_u64 v[158:159], v[156:157], 0, s[22:23]
	v_lshl_add_u64 v[164:165], v[162:163], 0, s[20:21]
	v_lshl_add_u64 v[170:171], v[168:169], 0, s[22:23]
	s_mov_b64 s[34:35], 0x100
	s_mov_b32 s55, 2
	v_mov_b32_e32 v69, v68
	v_mov_b32_e32 v70, v68
	v_mov_b32_e32 v71, v68
	v_mov_b32_e32 v72, v68
	v_mov_b32_e32 v73, v68
	v_mov_b32_e32 v74, v68
	v_mov_b32_e32 v75, v68
	v_mov_b32_e32 v76, v68
	v_mov_b32_e32 v77, v68
	v_mov_b32_e32 v78, v68
	v_mov_b32_e32 v79, v68
	v_mov_b32_e32 v80, v68
	v_mov_b32_e32 v81, v68
	v_mov_b32_e32 v82, v68
	v_mov_b32_e32 v83, v68
	v_mov_b32_e32 v84, v68
	v_mov_b32_e32 v85, v68
	v_mov_b32_e32 v86, v68
	v_mov_b32_e32 v87, v68
	v_mov_b32_e32 v88, v68
	v_mov_b32_e32 v89, v68
	v_mov_b32_e32 v90, v68
	v_mov_b32_e32 v91, v68
	v_mov_b32_e32 v92, v68
	v_mov_b32_e32 v93, v68
	v_mov_b32_e32 v94, v68
	v_mov_b32_e32 v95, v68
	v_mov_b32_e32 v96, v68
	v_mov_b32_e32 v97, v68
	v_mov_b32_e32 v98, v68
	v_mov_b32_e32 v99, v68
	v_mov_b32_e32 v100, v68
	v_mov_b32_e32 v101, v68
	v_mov_b32_e32 v102, v68
	v_mov_b32_e32 v103, v68
	v_mov_b32_e32 v104, v68
	v_mov_b32_e32 v105, v68
	v_mov_b32_e32 v106, v68
	v_mov_b32_e32 v107, v68
	v_mov_b32_e32 v108, v68
	v_mov_b32_e32 v109, v68
	v_mov_b32_e32 v110, v68
	v_mov_b32_e32 v111, v68
	v_mov_b32_e32 v112, v68
	v_mov_b32_e32 v113, v68
	v_mov_b32_e32 v114, v68
	v_mov_b32_e32 v115, v68
	v_mov_b32_e32 v116, v68
	v_mov_b32_e32 v117, v68
	v_mov_b32_e32 v118, v68
	v_mov_b32_e32 v119, v68
	v_mov_b32_e32 v120, v68
	v_mov_b32_e32 v121, v68
	v_mov_b32_e32 v122, v68
	v_mov_b32_e32 v123, v68
	v_mov_b32_e32 v124, v68
	v_mov_b32_e32 v125, v68
	v_mov_b32_e32 v126, v68
	v_mov_b32_e32 v127, v68
	v_mov_b32_e32 v128, v68
	v_mov_b32_e32 v129, v68
	v_mov_b32_e32 v130, v68
	v_mov_b32_e32 v131, v68
	s_branch .LBB0_176
.LBB0_176:
	s_cmp_ge_i32 s100, 0
	s_cbranch_scc1 .Lpc_prod_2
	v_mov_b64_e32 v[4:5], 0
	v_mov_b64_e32 v[6:7], 0
	v_mov_b64_e32 v[8:9], 0
	v_mov_b64_e32 v[10:11], 0
	v_mov_b64_e32 v[12:13], 0
	v_mov_b64_e32 v[14:15], 0
	v_mov_b64_e32 v[16:17], 0
	v_mov_b64_e32 v[18:19], 0
	v_mov_b64_e32 v[20:21], 0
	v_mov_b64_e32 v[22:23], 0
	v_mov_b64_e32 v[24:25], 0
	v_mov_b64_e32 v[26:27], 0
	v_mov_b64_e32 v[28:29], 0
	v_mov_b64_e32 v[30:31], 0
	v_mov_b64_e32 v[32:33], 0
	v_mov_b64_e32 v[34:35], 0
	v_mov_b64_e32 v[36:37], 0
	v_mov_b64_e32 v[38:39], 0
	v_mov_b64_e32 v[40:41], 0
	v_mov_b64_e32 v[42:43], 0
	v_mov_b64_e32 v[44:45], 0
	v_mov_b64_e32 v[46:47], 0
	v_mov_b64_e32 v[48:49], 0
	v_mov_b64_e32 v[50:51], 0
	v_mov_b64_e32 v[52:53], 0
	v_mov_b64_e32 v[54:55], 0
	v_mov_b64_e32 v[56:57], 0
	v_mov_b64_e32 v[58:59], 0
	v_mov_b64_e32 v[60:61], 0
	v_mov_b64_e32 v[62:63], 0
	v_mov_b64_e32 v[64:65], 0
	v_mov_b64_e32 v[66:67], 0
	v_xor_b32_e32 v188, 64, v250
	v_xor_b32_e32 v137, 64, v251
	ds_read_b128 v[222:225], v251
	ds_read_b128 v[226:229], v251 offset:2048
	ds_read_b128 v[238:241], v251 offset:4096
	ds_read_b128 v[242:245], v251 offset:6144
	ds_read_b128 v[172:175], v250
	ds_read_b128 v[176:179], v250 offset:2048
	ds_read_b128 v[180:183], v250 offset:4096
	ds_read_b128 v[184:187], v250 offset:6144
	ds_read_b128 v[132:135], v250 offset:8192
	ds_read_b128 v[208:211], v250 offset:10240
	ds_read_b128 v[214:217], v250 offset:12288
	ds_read_b128 v[218:221], v250 offset:14336
	ds_read_b128 v[246:249], v137
	ds_read_b128 v[230:233], v137 offset:2048
	ds_read_b128 v[144:147], v137 offset:4096
	s_waitcnt lgkmcnt(14)
	ds_read_b128 v[160:163], v137 offset:6144
	s_waitcnt lgkmcnt(14)
	ds_read_b128 v[164:167], v188
	s_waitcnt lgkmcnt(14)
	ds_read_b128 v[168:171], v188 offset:2048
	s_waitcnt lgkmcnt(14)
	ds_read_b128 v[140:143], v188 offset:4096
	s_waitcnt lgkmcnt(14)
	ds_read_b128 v[148:151], v188 offset:6144
	s_waitcnt lgkmcnt(14)
	ds_read_b128 v[152:155], v188 offset:8192
	v_mfma_f32_16x16x32_bf16 v[128:131], v[222:225], v[172:175], v[128:131]
	v_mfma_f32_16x16x32_bf16 v[124:127], v[226:229], v[172:175], v[124:127]
	v_mfma_f32_16x16x32_bf16 v[120:123], v[238:241], v[172:175], v[120:123]
	v_mfma_f32_16x16x32_bf16 v[116:119], v[242:245], v[172:175], v[116:119]
	s_waitcnt lgkmcnt(14)
	ds_read_b128 v[172:175], v188 offset:10240
	v_mfma_f32_16x16x32_bf16 v[112:115], v[222:225], v[176:179], v[112:115]
	v_mfma_f32_16x16x32_bf16 v[108:111], v[226:229], v[176:179], v[108:111]
	v_mfma_f32_16x16x32_bf16 v[104:107], v[238:241], v[176:179], v[104:107]
	v_mfma_f32_16x16x32_bf16 v[100:103], v[242:245], v[176:179], v[100:103]
	s_waitcnt lgkmcnt(14)
	ds_read_b128 v[176:179], v188 offset:12288
	v_mfma_f32_16x16x32_bf16 v[96:99], v[222:225], v[180:183], v[96:99]
	v_mfma_f32_16x16x32_bf16 v[92:95], v[226:229], v[180:183], v[92:95]
	v_mfma_f32_16x16x32_bf16 v[88:91], v[238:241], v[180:183], v[88:91]
	v_mfma_f32_16x16x32_bf16 v[84:87], v[242:245], v[180:183], v[84:87]
	s_waitcnt lgkmcnt(14)
	ds_read_b128 v[180:183], v188 offset:14336
	v_mfma_f32_16x16x32_bf16 v[80:83], v[222:225], v[184:187], v[80:83]
	v_mfma_f32_16x16x32_bf16 v[76:79], v[226:229], v[184:187], v[76:79]
	v_mfma_f32_16x16x32_bf16 v[72:75], v[238:241], v[184:187], v[72:75]
	v_mfma_f32_16x16x32_bf16 v[68:71], v[242:245], v[184:187], v[68:71]
	v_mfma_f32_16x16x32_bf16 v[4:7], v[222:225], v[132:135], v[4:7]
	v_mfma_f32_16x16x32_bf16 v[8:11], v[226:229], v[132:135], v[8:11]
	v_mfma_f32_16x16x32_bf16 v[12:15], v[238:241], v[132:135], v[12:15]
	v_mfma_f32_16x16x32_bf16 v[16:19], v[242:245], v[132:135], v[16:19]
	s_waitcnt lgkmcnt(0)
	s_barrier
	v_mfma_f32_16x16x32_bf16 v[20:23], v[222:225], v[208:211], v[20:23]
	v_mfma_f32_16x16x32_bf16 v[24:27], v[226:229], v[208:211], v[24:27]
	v_mfma_f32_16x16x32_bf16 v[28:31], v[238:241], v[208:211], v[28:31]
	v_mfma_f32_16x16x32_bf16 v[32:35], v[242:245], v[208:211], v[32:35]
	v_mfma_f32_16x16x32_bf16 v[36:39], v[222:225], v[214:217], v[36:39]
	v_mfma_f32_16x16x32_bf16 v[40:43], v[226:229], v[214:217], v[40:43]
	v_mfma_f32_16x16x32_bf16 v[44:47], v[238:241], v[214:217], v[44:47]
	v_mfma_f32_16x16x32_bf16 v[48:51], v[242:245], v[214:217], v[48:51]
	v_mfma_f32_16x16x32_bf16 v[52:55], v[222:225], v[218:221], v[52:55]
	v_mfma_f32_16x16x32_bf16 v[56:59], v[226:229], v[218:221], v[56:59]
	v_mfma_f32_16x16x32_bf16 v[60:63], v[238:241], v[218:221], v[60:63]
	v_mfma_f32_16x16x32_bf16 v[64:67], v[242:245], v[218:221], v[64:67]
	v_mfma_f32_16x16x32_bf16 v[128:131], v[246:249], v[164:167], v[128:131]
	v_mfma_f32_16x16x32_bf16 v[124:127], v[230:233], v[164:167], v[124:127]
	v_mfma_f32_16x16x32_bf16 v[120:123], v[144:147], v[164:167], v[120:123]
	v_mfma_f32_16x16x32_bf16 v[116:119], v[160:163], v[164:167], v[116:119]
	v_mfma_f32_16x16x32_bf16 v[112:115], v[246:249], v[168:171], v[112:115]
	v_mfma_f32_16x16x32_bf16 v[108:111], v[230:233], v[168:171], v[108:111]
	v_mfma_f32_16x16x32_bf16 v[104:107], v[144:147], v[168:171], v[104:107]
	v_mfma_f32_16x16x32_bf16 v[100:103], v[160:163], v[168:171], v[100:103]
	v_mfma_f32_16x16x32_bf16 v[96:99], v[246:249], v[140:143], v[96:99]
	v_mfma_f32_16x16x32_bf16 v[92:95], v[230:233], v[140:143], v[92:95]
	v_mfma_f32_16x16x32_bf16 v[88:91], v[144:147], v[140:143], v[88:91]
	v_mfma_f32_16x16x32_bf16 v[84:87], v[160:163], v[140:143], v[84:87]
	v_mfma_f32_16x16x32_bf16 v[20:23], v[246:249], v[172:175], v[20:23]
	v_mfma_f32_16x16x32_bf16 v[24:27], v[230:233], v[172:175], v[24:27]
	v_mfma_f32_16x16x32_bf16 v[28:31], v[144:147], v[172:175], v[28:31]
	v_mfma_f32_16x16x32_bf16 v[32:35], v[160:163], v[172:175], v[32:35]
	v_mfma_f32_16x16x32_bf16 v[36:39], v[246:249], v[176:179], v[36:39]
	v_mfma_f32_16x16x32_bf16 v[40:43], v[230:233], v[176:179], v[40:43]
	v_mfma_f32_16x16x32_bf16 v[44:47], v[144:147], v[176:179], v[44:47]
	v_mfma_f32_16x16x32_bf16 v[48:51], v[160:163], v[176:179], v[48:51]
	v_mfma_f32_16x16x32_bf16 v[52:55], v[246:249], v[180:183], v[52:55]
	v_mfma_f32_16x16x32_bf16 v[56:59], v[230:233], v[180:183], v[56:59]
	v_mfma_f32_16x16x32_bf16 v[60:63], v[144:147], v[180:183], v[60:63]
	v_mfma_f32_16x16x32_bf16 v[64:67], v[160:163], v[180:183], v[64:67]
	s_barrier
	s_branch .Lpc_ck1_2
.Lpc_ctop_2:
	ds_read_b128 v[222:225], v251
	ds_read_b128 v[226:229], v251 offset:2048
	ds_read_b128 v[238:241], v251 offset:4096
	ds_read_b128 v[242:245], v251 offset:6144
	ds_read_b128 v[172:175], v250
	ds_read_b128 v[176:179], v250 offset:2048
	ds_read_b128 v[180:183], v250 offset:4096
	ds_read_b128 v[184:187], v250 offset:6144
	ds_read_b128 v[132:135], v250 offset:8192
	ds_read_b128 v[208:211], v250 offset:10240
	v_mfma_f32_16x16x32_bf16 v[80:83], v[246:249], v[148:151], v[80:83]
	v_mfma_f32_16x16x32_bf16 v[76:79], v[230:233], v[148:151], v[76:79]
	v_mfma_f32_16x16x32_bf16 v[72:75], v[144:147], v[148:151], v[72:75]
	v_mfma_f32_16x16x32_bf16 v[68:71], v[160:163], v[148:151], v[68:71]
	v_mfma_f32_16x16x32_bf16 v[4:7], v[246:249], v[152:155], v[4:7]
	v_mfma_f32_16x16x32_bf16 v[8:11], v[230:233], v[152:155], v[8:11]
	v_mfma_f32_16x16x32_bf16 v[12:15], v[144:147], v[152:155], v[12:15]
	v_mfma_f32_16x16x32_bf16 v[16:19], v[160:163], v[152:155], v[16:19]
	ds_read_b128 v[214:217], v250 offset:12288
	ds_read_b128 v[218:221], v250 offset:14336
	ds_read_b128 v[246:249], v137
	ds_read_b128 v[230:233], v137 offset:2048
	ds_read_b128 v[144:147], v137 offset:4096
	s_waitcnt lgkmcnt(14)
	ds_read_b128 v[160:163], v137 offset:6144
	s_waitcnt lgkmcnt(14)
	ds_read_b128 v[164:167], v188
	s_waitcnt lgkmcnt(14)
	ds_read_b128 v[168:171], v188 offset:2048
	s_waitcnt lgkmcnt(14)
	ds_read_b128 v[140:143], v188 offset:4096
	s_waitcnt lgkmcnt(14)
	ds_read_b128 v[148:151], v188 offset:6144
	s_waitcnt lgkmcnt(14)
	ds_read_b128 v[152:155], v188 offset:8192
	v_mfma_f32_16x16x32_bf16 v[128:131], v[222:225], v[172:175], v[128:131]
	v_mfma_f32_16x16x32_bf16 v[124:127], v[226:229], v[172:175], v[124:127]
	v_mfma_f32_16x16x32_bf16 v[120:123], v[238:241], v[172:175], v[120:123]
	v_mfma_f32_16x16x32_bf16 v[116:119], v[242:245], v[172:175], v[116:119]
	s_waitcnt lgkmcnt(14)
	ds_read_b128 v[172:175], v188 offset:10240
	v_mfma_f32_16x16x32_bf16 v[112:115], v[222:225], v[176:179], v[112:115]
	v_mfma_f32_16x16x32_bf16 v[108:111], v[226:229], v[176:179], v[108:111]
	v_mfma_f32_16x16x32_bf16 v[104:107], v[238:241], v[176:179], v[104:107]
	v_mfma_f32_16x16x32_bf16 v[100:103], v[242:245], v[176:179], v[100:103]
	s_waitcnt lgkmcnt(14)
	ds_read_b128 v[176:179], v188 offset:12288
	v_mfma_f32_16x16x32_bf16 v[96:99], v[222:225], v[180:183], v[96:99]
	v_mfma_f32_16x16x32_bf16 v[92:95], v[226:229], v[180:183], v[92:95]
	v_mfma_f32_16x16x32_bf16 v[88:91], v[238:241], v[180:183], v[88:91]
	v_mfma_f32_16x16x32_bf16 v[84:87], v[242:245], v[180:183], v[84:87]
	s_waitcnt lgkmcnt(14)
	ds_read_b128 v[180:183], v188 offset:14336
	v_mfma_f32_16x16x32_bf16 v[80:83], v[222:225], v[184:187], v[80:83]
	v_mfma_f32_16x16x32_bf16 v[76:79], v[226:229], v[184:187], v[76:79]
	v_mfma_f32_16x16x32_bf16 v[72:75], v[238:241], v[184:187], v[72:75]
	v_mfma_f32_16x16x32_bf16 v[68:71], v[242:245], v[184:187], v[68:71]
	v_mfma_f32_16x16x32_bf16 v[4:7], v[222:225], v[132:135], v[4:7]
	v_mfma_f32_16x16x32_bf16 v[8:11], v[226:229], v[132:135], v[8:11]
	v_mfma_f32_16x16x32_bf16 v[12:15], v[238:241], v[132:135], v[12:15]
	v_mfma_f32_16x16x32_bf16 v[16:19], v[242:245], v[132:135], v[16:19]
	s_waitcnt lgkmcnt(0)
	s_barrier
	v_mfma_f32_16x16x32_bf16 v[20:23], v[222:225], v[208:211], v[20:23]
	v_mfma_f32_16x16x32_bf16 v[24:27], v[226:229], v[208:211], v[24:27]
	v_mfma_f32_16x16x32_bf16 v[28:31], v[238:241], v[208:211], v[28:31]
	v_mfma_f32_16x16x32_bf16 v[32:35], v[242:245], v[208:211], v[32:35]
	v_mfma_f32_16x16x32_bf16 v[36:39], v[222:225], v[214:217], v[36:39]
	v_mfma_f32_16x16x32_bf16 v[40:43], v[226:229], v[214:217], v[40:43]
	v_mfma_f32_16x16x32_bf16 v[44:47], v[238:241], v[214:217], v[44:47]
	v_mfma_f32_16x16x32_bf16 v[48:51], v[242:245], v[214:217], v[48:51]
	v_mfma_f32_16x16x32_bf16 v[52:55], v[222:225], v[218:221], v[52:55]
	v_mfma_f32_16x16x32_bf16 v[56:59], v[226:229], v[218:221], v[56:59]
	v_mfma_f32_16x16x32_bf16 v[60:63], v[238:241], v[218:221], v[60:63]
	v_mfma_f32_16x16x32_bf16 v[64:67], v[242:245], v[218:221], v[64:67]
	v_mfma_f32_16x16x32_bf16 v[128:131], v[246:249], v[164:167], v[128:131]
	v_mfma_f32_16x16x32_bf16 v[124:127], v[230:233], v[164:167], v[124:127]
	v_mfma_f32_16x16x32_bf16 v[120:123], v[144:147], v[164:167], v[120:123]
	v_mfma_f32_16x16x32_bf16 v[116:119], v[160:163], v[164:167], v[116:119]
	v_mfma_f32_16x16x32_bf16 v[112:115], v[246:249], v[168:171], v[112:115]
	v_mfma_f32_16x16x32_bf16 v[108:111], v[230:233], v[168:171], v[108:111]
	v_mfma_f32_16x16x32_bf16 v[104:107], v[144:147], v[168:171], v[104:107]
	v_mfma_f32_16x16x32_bf16 v[100:103], v[160:163], v[168:171], v[100:103]
	v_mfma_f32_16x16x32_bf16 v[96:99], v[246:249], v[140:143], v[96:99]
	v_mfma_f32_16x16x32_bf16 v[92:95], v[230:233], v[140:143], v[92:95]
	v_mfma_f32_16x16x32_bf16 v[88:91], v[144:147], v[140:143], v[88:91]
	v_mfma_f32_16x16x32_bf16 v[84:87], v[160:163], v[140:143], v[84:87]
	v_mfma_f32_16x16x32_bf16 v[20:23], v[246:249], v[172:175], v[20:23]
	v_mfma_f32_16x16x32_bf16 v[24:27], v[230:233], v[172:175], v[24:27]
	v_mfma_f32_16x16x32_bf16 v[28:31], v[144:147], v[172:175], v[28:31]
	v_mfma_f32_16x16x32_bf16 v[32:35], v[160:163], v[172:175], v[32:35]
	v_mfma_f32_16x16x32_bf16 v[36:39], v[246:249], v[176:179], v[36:39]
	v_mfma_f32_16x16x32_bf16 v[40:43], v[230:233], v[176:179], v[40:43]
	v_mfma_f32_16x16x32_bf16 v[44:47], v[144:147], v[176:179], v[44:47]
	v_mfma_f32_16x16x32_bf16 v[48:51], v[160:163], v[176:179], v[48:51]
	v_mfma_f32_16x16x32_bf16 v[52:55], v[246:249], v[180:183], v[52:55]
	v_mfma_f32_16x16x32_bf16 v[56:59], v[230:233], v[180:183], v[56:59]
	v_mfma_f32_16x16x32_bf16 v[60:63], v[144:147], v[180:183], v[60:63]
	v_mfma_f32_16x16x32_bf16 v[64:67], v[160:163], v[180:183], v[64:67]
	s_barrier
.Lpc_ck1_2:
	ds_read_b128 v[222:225], v251 offset:32768
	ds_read_b128 v[226:229], v251 offset:34816
	ds_read_b128 v[238:241], v251 offset:36864
	ds_read_b128 v[242:245], v251 offset:38912
	ds_read_b128 v[172:175], v250 offset:32768
	ds_read_b128 v[176:179], v250 offset:34816
	ds_read_b128 v[180:183], v250 offset:36864
	ds_read_b128 v[184:187], v250 offset:38912
	ds_read_b128 v[132:135], v250 offset:40960
	ds_read_b128 v[208:211], v250 offset:43008
	v_mfma_f32_16x16x32_bf16 v[80:83], v[246:249], v[148:151], v[80:83]
	v_mfma_f32_16x16x32_bf16 v[76:79], v[230:233], v[148:151], v[76:79]
	v_mfma_f32_16x16x32_bf16 v[72:75], v[144:147], v[148:151], v[72:75]
	v_mfma_f32_16x16x32_bf16 v[68:71], v[160:163], v[148:151], v[68:71]
	v_mfma_f32_16x16x32_bf16 v[4:7], v[246:249], v[152:155], v[4:7]
	v_mfma_f32_16x16x32_bf16 v[8:11], v[230:233], v[152:155], v[8:11]
	v_mfma_f32_16x16x32_bf16 v[12:15], v[144:147], v[152:155], v[12:15]
	v_mfma_f32_16x16x32_bf16 v[16:19], v[160:163], v[152:155], v[16:19]
	ds_read_b128 v[214:217], v250 offset:45056
	ds_read_b128 v[218:221], v250 offset:47104
	ds_read_b128 v[246:249], v137 offset:32768
	ds_read_b128 v[230:233], v137 offset:34816
	ds_read_b128 v[144:147], v137 offset:36864
	s_waitcnt lgkmcnt(14)
	ds_read_b128 v[160:163], v137 offset:38912
	s_waitcnt lgkmcnt(14)
	ds_read_b128 v[164:167], v188 offset:32768
	s_waitcnt lgkmcnt(14)
	ds_read_b128 v[168:171], v188 offset:34816
	s_waitcnt lgkmcnt(14)
	ds_read_b128 v[140:143], v188 offset:36864
	s_waitcnt lgkmcnt(14)
	ds_read_b128 v[148:151], v188 offset:38912
	s_waitcnt lgkmcnt(14)
	ds_read_b128 v[152:155], v188 offset:40960
	v_mfma_f32_16x16x32_bf16 v[128:131], v[222:225], v[172:175], v[128:131]
	v_mfma_f32_16x16x32_bf16 v[124:127], v[226:229], v[172:175], v[124:127]
	v_mfma_f32_16x16x32_bf16 v[120:123], v[238:241], v[172:175], v[120:123]
	v_mfma_f32_16x16x32_bf16 v[116:119], v[242:245], v[172:175], v[116:119]
	s_waitcnt lgkmcnt(14)
	ds_read_b128 v[172:175], v188 offset:43008
	v_mfma_f32_16x16x32_bf16 v[112:115], v[222:225], v[176:179], v[112:115]
	v_mfma_f32_16x16x32_bf16 v[108:111], v[226:229], v[176:179], v[108:111]
	v_mfma_f32_16x16x32_bf16 v[104:107], v[238:241], v[176:179], v[104:107]
	v_mfma_f32_16x16x32_bf16 v[100:103], v[242:245], v[176:179], v[100:103]
	s_waitcnt lgkmcnt(14)
	ds_read_b128 v[176:179], v188 offset:45056
	v_mfma_f32_16x16x32_bf16 v[96:99], v[222:225], v[180:183], v[96:99]
	v_mfma_f32_16x16x32_bf16 v[92:95], v[226:229], v[180:183], v[92:95]
	v_mfma_f32_16x16x32_bf16 v[88:91], v[238:241], v[180:183], v[88:91]
	v_mfma_f32_16x16x32_bf16 v[84:87], v[242:245], v[180:183], v[84:87]
	s_waitcnt lgkmcnt(14)
	ds_read_b128 v[180:183], v188 offset:47104
	v_mfma_f32_16x16x32_bf16 v[80:83], v[222:225], v[184:187], v[80:83]
	v_mfma_f32_16x16x32_bf16 v[76:79], v[226:229], v[184:187], v[76:79]
	v_mfma_f32_16x16x32_bf16 v[72:75], v[238:241], v[184:187], v[72:75]
	v_mfma_f32_16x16x32_bf16 v[68:71], v[242:245], v[184:187], v[68:71]
	v_mfma_f32_16x16x32_bf16 v[4:7], v[222:225], v[132:135], v[4:7]
	v_mfma_f32_16x16x32_bf16 v[8:11], v[226:229], v[132:135], v[8:11]
	v_mfma_f32_16x16x32_bf16 v[12:15], v[238:241], v[132:135], v[12:15]
	v_mfma_f32_16x16x32_bf16 v[16:19], v[242:245], v[132:135], v[16:19]
	s_waitcnt lgkmcnt(0)
	s_barrier
	v_mfma_f32_16x16x32_bf16 v[20:23], v[222:225], v[208:211], v[20:23]
	v_mfma_f32_16x16x32_bf16 v[24:27], v[226:229], v[208:211], v[24:27]
	v_mfma_f32_16x16x32_bf16 v[28:31], v[238:241], v[208:211], v[28:31]
	v_mfma_f32_16x16x32_bf16 v[32:35], v[242:245], v[208:211], v[32:35]
	v_mfma_f32_16x16x32_bf16 v[36:39], v[222:225], v[214:217], v[36:39]
	v_mfma_f32_16x16x32_bf16 v[40:43], v[226:229], v[214:217], v[40:43]
	v_mfma_f32_16x16x32_bf16 v[44:47], v[238:241], v[214:217], v[44:47]
	v_mfma_f32_16x16x32_bf16 v[48:51], v[242:245], v[214:217], v[48:51]
	v_mfma_f32_16x16x32_bf16 v[52:55], v[222:225], v[218:221], v[52:55]
	v_mfma_f32_16x16x32_bf16 v[56:59], v[226:229], v[218:221], v[56:59]
	v_mfma_f32_16x16x32_bf16 v[60:63], v[238:241], v[218:221], v[60:63]
	v_mfma_f32_16x16x32_bf16 v[64:67], v[242:245], v[218:221], v[64:67]
	v_mfma_f32_16x16x32_bf16 v[128:131], v[246:249], v[164:167], v[128:131]
	v_mfma_f32_16x16x32_bf16 v[124:127], v[230:233], v[164:167], v[124:127]
	v_mfma_f32_16x16x32_bf16 v[120:123], v[144:147], v[164:167], v[120:123]
	v_mfma_f32_16x16x32_bf16 v[116:119], v[160:163], v[164:167], v[116:119]
	v_mfma_f32_16x16x32_bf16 v[112:115], v[246:249], v[168:171], v[112:115]
	v_mfma_f32_16x16x32_bf16 v[108:111], v[230:233], v[168:171], v[108:111]
	v_mfma_f32_16x16x32_bf16 v[104:107], v[144:147], v[168:171], v[104:107]
	v_mfma_f32_16x16x32_bf16 v[100:103], v[160:163], v[168:171], v[100:103]
	v_mfma_f32_16x16x32_bf16 v[96:99], v[246:249], v[140:143], v[96:99]
	v_mfma_f32_16x16x32_bf16 v[92:95], v[230:233], v[140:143], v[92:95]
	v_mfma_f32_16x16x32_bf16 v[88:91], v[144:147], v[140:143], v[88:91]
	v_mfma_f32_16x16x32_bf16 v[84:87], v[160:163], v[140:143], v[84:87]
	v_mfma_f32_16x16x32_bf16 v[20:23], v[246:249], v[172:175], v[20:23]
	v_mfma_f32_16x16x32_bf16 v[24:27], v[230:233], v[172:175], v[24:27]
	v_mfma_f32_16x16x32_bf16 v[28:31], v[144:147], v[172:175], v[28:31]
	v_mfma_f32_16x16x32_bf16 v[32:35], v[160:163], v[172:175], v[32:35]
	v_mfma_f32_16x16x32_bf16 v[36:39], v[246:249], v[176:179], v[36:39]
	v_mfma_f32_16x16x32_bf16 v[40:43], v[230:233], v[176:179], v[40:43]
	v_mfma_f32_16x16x32_bf16 v[44:47], v[144:147], v[176:179], v[44:47]
	v_mfma_f32_16x16x32_bf16 v[48:51], v[160:163], v[176:179], v[48:51]
	v_mfma_f32_16x16x32_bf16 v[52:55], v[246:249], v[180:183], v[52:55]
	v_mfma_f32_16x16x32_bf16 v[56:59], v[230:233], v[180:183], v[56:59]
	v_mfma_f32_16x16x32_bf16 v[60:63], v[144:147], v[180:183], v[60:63]
	v_mfma_f32_16x16x32_bf16 v[64:67], v[160:163], v[180:183], v[64:67]
	s_barrier
	s_add_i32 s55, s55, 2
	s_cmp_le_i32 s55, s47
	s_cbranch_scc1 .Lpc_ctop_2
	v_mfma_f32_16x16x32_bf16 v[80:83], v[246:249], v[148:151], v[80:83]
	v_mfma_f32_16x16x32_bf16 v[76:79], v[230:233], v[148:151], v[76:79]
	v_mfma_f32_16x16x32_bf16 v[72:75], v[144:147], v[148:151], v[72:75]
	v_mfma_f32_16x16x32_bf16 v[68:71], v[160:163], v[148:151], v[68:71]
	v_mfma_f32_16x16x32_bf16 v[4:7], v[246:249], v[152:155], v[4:7]
	v_mfma_f32_16x16x32_bf16 v[8:11], v[230:233], v[152:155], v[8:11]
	v_mfma_f32_16x16x32_bf16 v[12:15], v[144:147], v[152:155], v[12:15]
	v_mfma_f32_16x16x32_bf16 v[16:19], v[160:163], v[152:155], v[16:19]
	s_mov_b32 s98, s53
	s_mov_b32 s99, s52
	s_mov_b32 s100, -2
	s_bfe_u32 vcc_lo, s101, 0x10001
	s_lshl_b32 vcc_lo, vcc_lo, 6
	v_add_u32_e32 v194, vcc_lo, v202
	s_branch .LBB0_169
.Lpc_edone_2:
	s_cmp_eq_u32 s100, -2
	s_cbranch_scc0 .Lpc_efin_2
	s_mov_b32 s100, -3
	s_mov_b32 s53, s98
	s_mov_b32 s52, s99
	v_mov_b64_e32 v[128:129], v[4:5]
	v_mov_b64_e32 v[130:131], v[6:7]
	v_mov_b64_e32 v[124:125], v[8:9]
	v_mov_b64_e32 v[126:127], v[10:11]
	v_mov_b64_e32 v[120:121], v[12:13]
	v_mov_b64_e32 v[122:123], v[14:15]
	v_mov_b64_e32 v[116:117], v[16:17]
	v_mov_b64_e32 v[118:119], v[18:19]
	v_mov_b64_e32 v[112:113], v[20:21]
	v_mov_b64_e32 v[114:115], v[22:23]
	v_mov_b64_e32 v[108:109], v[24:25]
	v_mov_b64_e32 v[110:111], v[26:27]
	v_mov_b64_e32 v[104:105], v[28:29]
	v_mov_b64_e32 v[106:107], v[30:31]
	v_mov_b64_e32 v[100:101], v[32:33]
	v_mov_b64_e32 v[102:103], v[34:35]
	v_mov_b64_e32 v[96:97], v[36:37]
	v_mov_b64_e32 v[98:99], v[38:39]
	v_mov_b64_e32 v[92:93], v[40:41]
	v_mov_b64_e32 v[94:95], v[42:43]
	v_mov_b64_e32 v[88:89], v[44:45]
	v_mov_b64_e32 v[90:91], v[46:47]
	v_mov_b64_e32 v[84:85], v[48:49]
	v_mov_b64_e32 v[86:87], v[50:51]
	v_mov_b64_e32 v[80:81], v[52:53]
	v_mov_b64_e32 v[82:83], v[54:55]
	v_mov_b64_e32 v[76:77], v[56:57]
	v_mov_b64_e32 v[78:79], v[58:59]
	v_mov_b64_e32 v[72:73], v[60:61]
	v_mov_b64_e32 v[74:75], v[62:63]
	v_mov_b64_e32 v[68:69], v[64:65]
	v_mov_b64_e32 v[70:71], v[66:67]
	v_add_u32_e32 v194, 0x80, v194
	s_branch .LBB0_169
.Lpc_efin_2:
	s_mov_b32 s100, -1
	s_bfe_u32 s98, s101, 0x20002
	s_lshl_b32 s98, s98, 6
	v_add_u32_e32 v194, s98, v202
	s_cbranch_vccnz .LBB0_191
	s_branch .LBB0_171
.Lpc_prod_2:
.Lpc_ptop_2:
	s_cmp_lt_i32 s55, s47
	s_cbranch_scc1 .Lpc_pcur_2
	s_mov_b32 vcc_lo, 0
	s_cmp_lg_u64 s[30:31], 0
	s_cbranch_scc1 .Lpc_pnext_2
	v_readfirstlane_b32 s40, v144
	v_readfirstlane_b32 s41, v145
	v_readfirstlane_b32 s38, v146
	v_readfirstlane_b32 s39, v147
	s_branch .Lpc_pgo_2
.Lpc_pnext_2:
	v_readfirstlane_b32 s40, v140
	v_readfirstlane_b32 s41, v141
	v_readfirstlane_b32 s38, v142
	v_readfirstlane_b32 s39, v143
	s_branch .Lpc_pgo_2
.Lpc_pcur_2:
	s_mov_b32 vcc_lo, s55
	v_readfirstlane_b32 s40, v144
	v_readfirstlane_b32 s41, v145
	v_readfirstlane_b32 s38, v146
	v_readfirstlane_b32 s39, v147
.Lpc_pgo_2:
	s_nop 0
	s_sub_u32 s40, s40, s98
	s_subb_u32 s41, s41, 0
	s_sub_u32 s38, s38, s99
	s_subb_u32 s39, s39, 0
	s_bfe_u32 vcc_hi, s101, 0x80008
	s_add_u32 vcc_hi, vcc_hi, vcc_lo
	s_add_u32 m0, s47, -1
	s_and_b32 vcc_hi, vcc_hi, m0
	s_lshl_b32 vcc_hi, vcc_hi, 7
	v_add_u32_e32 v20, vcc_hi, v4
	v_add_u32_e32 v21, vcc_hi, v5
	v_add_u32_e32 v22, vcc_hi, v6
	v_add_u32_e32 v23, vcc_hi, v7
	v_add_u32_e32 v24, vcc_hi, v8
	v_add_u32_e32 v25, vcc_hi, v9
	v_add_u32_e32 v26, vcc_hi, v10
	v_add_u32_e32 v27, vcc_hi, v11
	v_add_u32_e32 v28, vcc_hi, v12
	v_add_u32_e32 v29, vcc_hi, v13
	v_add_u32_e32 v30, vcc_hi, v14
	v_add_u32_e32 v31, vcc_hi, v15
	v_add_u32_e32 v32, vcc_hi, v16
	v_add_u32_e32 v33, vcc_hi, v17
	v_add_u32_e32 v34, vcc_hi, v18
	v_add_u32_e32 v35, vcc_hi, v19
	s_add_u32 vcc_lo, vcc_lo, 1
	s_barrier
	s_add_u32 m0, s100, 0x0
	s_nop 0
	global_load_lds_dwordx4 v20, s[40:41]
	s_add_u32 m0, s100, 0x400
	s_nop 0
	global_load_lds_dwordx4 v21, s[40:41]
	s_add_u32 m0, s100, 0x1000
	s_nop 0
	global_load_lds_dwordx4 v22, s[40:41]
	s_add_u32 m0, s100, 0x1400
	s_nop 0
	global_load_lds_dwordx4 v23, s[40:41]
	s_add_u32 m0, s100, 0x2000
	s_nop 0
	global_load_lds_dwordx4 v24, s[40:41]
	s_add_u32 m0, s100, 0x2400
	s_nop 0
	global_load_lds_dwordx4 v25, s[40:41]
	s_add_u32 m0, s100, 0x3000
	s_nop 0
	global_load_lds_dwordx4 v26, s[40:41]
	s_add_u32 m0, s100, 0x3400
	s_nop 0
	global_load_lds_dwordx4 v27, s[40:41]
	s_waitcnt vmcnt(8)
	s_barrier
	s_add_u32 m0, s100, 0x4000
	s_nop 0
	global_load_lds_dwordx4 v28, s[38:39]
	s_add_u32 m0, s100, 0x4400
	s_nop 0
	global_load_lds_dwordx4 v29, s[38:39]
	s_add_u32 m0, s100, 0x5000
	s_nop 0
	global_load_lds_dwordx4 v30, s[38:39]
	s_add_u32 m0, s100, 0x5400
	s_nop 0
	global_load_lds_dwordx4 v31, s[38:39]
	s_add_u32 m0, s100, 0x6000
	s_nop 0
	global_load_lds_dwordx4 v32, s[38:39]
	s_add_u32 m0, s100, 0x6400
	s_nop 0
	global_load_lds_dwordx4 v33, s[38:39]
	s_add_u32 m0, s100, 0x7000
	s_nop 0
	global_load_lds_dwordx4 v34, s[38:39]
	s_add_u32 m0, s100, 0x7400
	s_nop 0
	global_load_lds_dwordx4 v35, s[38:39]
	s_bfe_u32 vcc_hi, s101, 0x80008
	s_add_u32 vcc_hi, vcc_hi, vcc_lo
	s_add_u32 m0, s47, -1
	s_and_b32 vcc_hi, vcc_hi, m0
	s_lshl_b32 vcc_hi, vcc_hi, 7
	v_add_u32_e32 v20, vcc_hi, v4
	v_add_u32_e32 v21, vcc_hi, v5
	v_add_u32_e32 v22, vcc_hi, v6
	v_add_u32_e32 v23, vcc_hi, v7
	v_add_u32_e32 v24, vcc_hi, v8
	v_add_u32_e32 v25, vcc_hi, v9
	v_add_u32_e32 v26, vcc_hi, v10
	v_add_u32_e32 v27, vcc_hi, v11
	v_add_u32_e32 v28, vcc_hi, v12
	v_add_u32_e32 v29, vcc_hi, v13
	v_add_u32_e32 v30, vcc_hi, v14
	v_add_u32_e32 v31, vcc_hi, v15
	v_add_u32_e32 v32, vcc_hi, v16
	v_add_u32_e32 v33, vcc_hi, v17
	v_add_u32_e32 v34, vcc_hi, v18
	v_add_u32_e32 v35, vcc_hi, v19
	s_add_u32 vcc_lo, vcc_lo, 1
	s_barrier
	s_add_u32 m0, s100, 0x8000
	s_nop 0
	global_load_lds_dwordx4 v20, s[40:41]
	s_add_u32 m0, s100, 0x8400
	s_nop 0
	global_load_lds_dwordx4 v21, s[40:41]
	s_add_u32 m0, s100, 0x9000
	s_nop 0
	global_load_lds_dwordx4 v22, s[40:41]
	s_add_u32 m0, s100, 0x9400
	s_nop 0
	global_load_lds_dwordx4 v23, s[40:41]
	s_add_u32 m0, s100, 0xa000
	s_nop 0
	global_load_lds_dwordx4 v24, s[40:41]
	s_add_u32 m0, s100, 0xa400
	s_nop 0
	global_load_lds_dwordx4 v25, s[40:41]
	s_add_u32 m0, s100, 0xb000
	s_nop 0
	global_load_lds_dwordx4 v26, s[40:41]
	s_add_u32 m0, s100, 0xb400
	s_nop 0
	global_load_lds_dwordx4 v27, s[40:41]
	s_waitcnt vmcnt(8)
	s_barrier
	s_add_u32 m0, s100, 0xc000
	s_nop 0
	global_load_lds_dwordx4 v28, s[38:39]
	s_add_u32 m0, s100, 0xc400
	s_nop 0
	global_load_lds_dwordx4 v29, s[38:39]
	s_add_u32 m0, s100, 0xd000
	s_nop 0
	global_load_lds_dwordx4 v30, s[38:39]
	s_add_u32 m0, s100, 0xd400
	s_nop 0
	global_load_lds_dwordx4 v31, s[38:39]
	s_add_u32 m0, s100, 0xe000
	s_nop 0
	global_load_lds_dwordx4 v32, s[38:39]
	s_add_u32 m0, s100, 0xe400
	s_nop 0
	global_load_lds_dwordx4 v33, s[38:39]
	s_add_u32 m0, s100, 0xf000
	s_nop 0
	global_load_lds_dwordx4 v34, s[38:39]
	s_add_u32 m0, s100, 0xf400
	s_nop 0
	global_load_lds_dwordx4 v35, s[38:39]
	s_add_u32 s34, s34, 0x100
	s_addc_u32 s35, s35, 0
	s_add_i32 s55, s55, 2
	s_cmp_le_i32 s55, s47
	s_cbranch_scc1 .Lpc_ptop_2
	s_movk_i32 s55, 0x4000
	s_mov_b32 s53, s1
	s_mov_b32 s52, s3
	s_and_b64 vcc, exec, s[26:27]
	v_mov_b64_e32 v[146:147], v[142:143]
	v_mov_b64_e32 v[144:145], v[140:141]
	s_cbranch_vccz .Lpc_pnd_2
	s_waitcnt vmcnt(0)
	s_branch .LBB0_191
.Lpc_pnd_2:
	s_branch .LBB0_171

.LBB0_245:
	s_andn2_b64 vcc, exec, s[2:3]
	s_cbranch_vccnz .LBB0_276
	s_waitcnt vmcnt(0)
	v_mov_b32_e32 v74, v194
	s_movk_i32 s22, 0x400
	s_movk_i32 s24, 0x400
	s_movk_i32 s2, 0x400
	v_lshlrev_b32_e32 v0, 3, v74
	v_ashrrev_i32_e32 v3, 3, v74
	v_and_b32_e32 v0, 56, v0
	v_lshrrev_b32_e32 v132, 4, v74
	v_xor_b32_e32 v132, v132, v74
	v_and_b32_e32 v132, 7, v132
	v_lshlrev_b32_e32 v0, 3, v132
	v_mov_b32_e32 v1, v2
	s_ashr_i32 s40, s2, 6
	s_ashr_i32 s41, s2, 9
	v_mad_i64_i32 v[4:5], s[2:3], s22, v3, v[0:1]
	v_mad_i64_i32 v[6:7], s[2:3], s24, v3, v[0:1]
	v_readlane_b32 s47, v254, 35
	s_mul_hi_i32 s3, s22, s47
	s_mul_i32 s2, s22, s47
	s_ashr_i32 s23, s22, 31
	s_ashr_i32 s25, s24, 31
	s_lshl_b64 s[2:3], s[2:3], 1
	s_add_u32 s2, s76, s2
	s_addc_u32 s3, s77, s3
	v_lshlrev_b64 v[68:69], 1, v[4:5]
	v_readlane_b32 s46, v254, 33
	v_lshl_add_u64 v[0:1], s[2:3], 0, v[68:69]
	s_mul_hi_i32 s3, s24, s46
	s_mul_i32 s2, s24, s46
	s_lshl_b64 s[26:27], s[2:3], 1
	s_add_u32 s2, s0, s26
	s_addc_u32 s3, s1, s27
	v_lshlrev_b64 v[70:71], 1, v[6:7]
	v_lshl_add_u64 v[138:139], s[2:3], 0, v[70:71]
	s_lshl_b64 s[2:3], s[22:23], 6
	s_waitcnt vmcnt(0)
	v_lshl_add_u64 v[28:29], v[0:1], 0, s[2:3]
	s_lshl_b64 s[20:21], s[24:25], 6
	s_waitcnt vmcnt(0)
	v_lshl_add_u64 v[36:37], v[28:29], 0, s[2:3]
	s_waitcnt vmcnt(0)
	v_lshl_add_u64 v[56:57], v[138:139], 0, s[20:21]
	v_lshl_add_u64 v[40:41], v[36:37], 0, s[2:3]
	s_waitcnt vmcnt(0)
	v_lshl_add_u64 v[60:61], v[56:57], 0, s[20:21]
	s_waitcnt vmcnt(0)
	v_lshl_add_u64 v[64:65], v[60:61], 0, s[20:21]
	v_lshrrev_b32_e32 v8, 6, v194
	v_lshlrev_b32_e32 v8, 10, v8
	s_mov_b64 s[98:99], 0x80
	v_readfirstlane_b32 s100, v8
	s_add_u32 m0, s100, 0x0
	s_nop 0
	global_load_lds_dwordx4 v[0:1], off
	s_add_u32 m0, s100, 0x1000
	s_nop 0
	global_load_lds_dwordx4 v[28:29], off
	s_add_u32 m0, s100, 0x2000
	s_nop 0
	global_load_lds_dwordx4 v[36:37], off
	s_add_u32 m0, s100, 0x3000
	s_nop 0
	global_load_lds_dwordx4 v[40:41], off
	s_add_u32 m0, s100, 0x4000
	s_nop 0
	global_load_lds_dwordx4 v[138:139], off
	s_add_u32 m0, s100, 0x5000
	s_nop 0
	global_load_lds_dwordx4 v[56:57], off
	s_add_u32 m0, s100, 0x6000
	s_nop 0
	global_load_lds_dwordx4 v[60:61], off
	s_add_u32 m0, s100, 0x7000
	s_nop 0
	global_load_lds_dwordx4 v[64:65], off
	v_lshlrev_b32_e32 v72, 7, v3
	v_lshrrev_b32_e32 v3, 1, v3
	v_xor_b32_e32 v3, v3, v74
	v_lshl_add_u64 v[70:71], s[0:1], 0, v[70:71]
	v_readlane_b32 s0, v254, 34
	v_lshlrev_b32_e32 v3, 4, v3
	s_movk_i32 s6, 0x70
	v_lshl_add_u64 v[68:69], s[76:77], 0, v[68:69]
	s_mul_hi_i32 s1, s22, s0
	s_mul_i32 s0, s22, s0
	v_and_or_b32 v3, v3, s6, v72
	v_lshl_add_u64 v[72:73], s[0:1], 1, v[68:69]
	v_readlane_b32 s0, v254, 31
	s_mul_hi_i32 s1, s41, s0
	s_mul_i32 s0, s41, s0
	v_readlane_b32 s6, v254, 32
	s_lshl_b64 s[0:1], s[0:1], 1
	s_mul_hi_i32 s25, s24, s6
	s_mul_i32 s24, s24, s6
	v_lshl_add_u64 v[140:141], v[72:73], 0, s[0:1]
	v_lshl_add_u64 v[72:73], s[24:25], 1, v[70:71]
	v_lshl_add_u64 v[142:143], v[72:73], 0, s[0:1]
	s_mul_hi_i32 s1, s22, s54
	s_mul_i32 s0, s22, s54
	v_lshrrev_b32_e32 v75, 4, v74
	v_bfe_u32 v76, v74, 4, 2
	v_lshl_add_u64 v[144:145], s[0:1], 1, v[68:69]
	v_bfe_u32 v68, v74, 1, 3
	v_lshl_add_u64 v[146:147], v[70:71], 0, s[26:27]
	v_bitop3_b32 v69, v75, v68, 3 bitop3:0x6c
	v_lshlrev_b32_e32 v70, 6, v74
	v_lshlrev_b32_e32 v71, 7, v74
	v_bitop3_b32 v68, v76, v68, 4 bitop3:0x36
	v_lshlrev_b32_e32 v69, 4, v69
	v_and_b32_e32 v70, 0xffffe000, v70
	v_and_b32_e32 v72, 0x780, v71
	v_and_b32_e32 v71, 0x2000, v71
	v_lshlrev_b32_e32 v68, 4, v68
	v_or_b32_e32 v73, v69, v70
	v_or_b32_e32 v69, v69, v71
	v_or_b32_e32 v70, v68, v70
	v_or_b32_e32 v68, v68, v71
	s_mov_b32 s42, 0
	v_add_u32_e32 v137, v73, v72
	v_add_u32_e32 v192, v69, v72
	v_add_u32_e32 v193, v70, v72
	v_add_u32_e32 v214, v68, v72
	s_mov_b32 s43, s40
	s_mov_b32 s44, 0
	s_mov_b32 s45, 0
	v_and_b32_e32 v4, 15, v194
	v_lshrrev_b32_e32 v5, 1, v4
	v_bfe_u32 v6, v194, 4, 2
	v_xor_b32_e32 v5, v5, v6
	v_lshlrev_b32_e32 v5, 4, v5
	v_lshl_or_b32 v5, v4, 7, v5
	v_lshrrev_b32_e32 v6, 7, v194
	v_lshl_or_b32 v4, v6, 13, v5
	v_bfe_u32 v6, v194, 6, 1
	v_lshl_or_b32 v6, v6, 13, v5
	v_or_b32_e32 v6, 0x4000, v6
	v_xor_b32_e32 v5, 64, v4
	v_xor_b32_e32 v7, 64, v6
	s_waitcnt vmcnt(0) lgkmcnt(0)
	s_barrier
	s_branch .LBB0_249

.LBB0_255:
	s_cmp_lg_u32 s42, 2
	s_cselect_b64 s[22:23], -1, 0
	s_cmp_eq_u32 s42, 2
	s_cselect_b64 s[0:1], -1, 0
	s_cmp_lt_i32 s49, 1
	s_cbranch_scc1 .LBB0_272
	v_lshl_add_u64 v[152:153], v[0:1], 0, s[2:3]
	v_lshl_add_u64 v[158:159], v[138:139], 0, s[20:21]
	v_lshl_add_u64 v[164:165], v[150:151], 0, s[2:3]
	v_lshl_add_u64 v[170:171], v[148:149], 0, s[20:21]
	v_lshl_add_u64 v[154:155], v[152:153], 0, s[2:3]
	v_lshl_add_u64 v[160:161], v[158:159], 0, s[20:21]
	v_lshl_add_u64 v[166:167], v[164:165], 0, s[2:3]
	v_lshl_add_u64 v[172:173], v[170:171], 0, s[20:21]
	v_mov_b32_e32 v68, 0
	v_lshl_add_u64 v[156:157], v[154:155], 0, s[2:3]
	v_lshl_add_u64 v[162:163], v[160:161], 0, s[20:21]
	v_lshl_add_u64 v[168:169], v[166:167], 0, s[2:3]
	v_lshl_add_u64 v[174:175], v[172:173], 0, s[20:21]
	s_mov_b64 s[24:25], 0x80
	s_mov_b32 s52, 2
	v_mov_b32_e32 v69, v68
	v_mov_b32_e32 v70, v68
	v_mov_b32_e32 v71, v68
	v_mov_b32_e32 v72, v68
	v_mov_b32_e32 v73, v68
	v_mov_b32_e32 v74, v68
	v_mov_b32_e32 v75, v68
	v_mov_b32_e32 v76, v68
	v_mov_b32_e32 v77, v68
	v_mov_b32_e32 v78, v68
	v_mov_b32_e32 v79, v68
	v_mov_b32_e32 v80, v68
	v_mov_b32_e32 v81, v68
	v_mov_b32_e32 v82, v68
	v_mov_b32_e32 v83, v68
	v_mov_b32_e32 v84, v68
	v_mov_b32_e32 v85, v68
	v_mov_b32_e32 v86, v68
	v_mov_b32_e32 v87, v68
	v_mov_b32_e32 v88, v68
	v_mov_b32_e32 v89, v68
	v_mov_b32_e32 v90, v68
	v_mov_b32_e32 v91, v68
	v_mov_b32_e32 v92, v68
	v_mov_b32_e32 v93, v68
	v_mov_b32_e32 v94, v68
	v_mov_b32_e32 v95, v68
	v_mov_b32_e32 v96, v68
	v_mov_b32_e32 v97, v68
	v_mov_b32_e32 v98, v68
	v_mov_b32_e32 v99, v68
	v_mov_b32_e32 v100, v68
	v_mov_b32_e32 v101, v68
	v_mov_b32_e32 v102, v68
	v_mov_b32_e32 v103, v68
	v_mov_b32_e32 v104, v68
	v_mov_b32_e32 v105, v68
	v_mov_b32_e32 v106, v68
	v_mov_b32_e32 v107, v68
	v_mov_b32_e32 v108, v68
	v_mov_b32_e32 v109, v68
	v_mov_b32_e32 v110, v68
	v_mov_b32_e32 v111, v68
	v_mov_b32_e32 v116, v68
	v_mov_b32_e32 v117, v68
	v_mov_b32_e32 v118, v68
	v_mov_b32_e32 v119, v68
	v_mov_b32_e32 v112, v68
	v_mov_b32_e32 v113, v68
	v_mov_b32_e32 v114, v68
	v_mov_b32_e32 v115, v68
	v_mov_b32_e32 v120, v68
	v_mov_b32_e32 v121, v68
	v_mov_b32_e32 v122, v68
	v_mov_b32_e32 v123, v68
	v_mov_b32_e32 v124, v68
	v_mov_b32_e32 v125, v68
	v_mov_b32_e32 v126, v68
	v_mov_b32_e32 v127, v68
	v_mov_b32_e32 v128, v68
	v_mov_b32_e32 v129, v68
	v_mov_b32_e32 v130, v68
	v_mov_b32_e32 v131, v68
	s_branch .LBB0_258

.Lgd_body0_6:
	s_cmp_lt_i32 s52, s49
	s_cselect_b64 s[30:31], -1, 0
	s_add_u32 m0, s100, 0x8000
	s_nop 0
	global_load_lds_dwordx4 v[176:177], off
	s_add_u32 m0, s100, 0x9000
	s_nop 0
	global_load_lds_dwordx4 v[178:179], off
	s_add_u32 m0, s100, 0xa000
	s_nop 0
	global_load_lds_dwordx4 v[180:181], off
	s_add_u32 m0, s100, 0xb000
	s_nop 0
	global_load_lds_dwordx4 v[182:183], off
	s_waitcnt lgkmcnt(7)
	ds_read_b128 v[40:43], v7
	ds_read_b128 v[44:47], v5
	ds_read_b128 v[48:51], v7 offset:2048
	ds_read_b128 v[52:55], v7 offset:4096
	ds_read_b128 v[56:59], v7 offset:6144
	ds_read_b128 v[60:63], v5 offset:2048
	ds_read_b128 v[64:67], v5 offset:4096
	ds_read_b128 v[132:135], v5 offset:6144
	s_add_u32 m0, s100, 0xc000
	s_waitcnt lgkmcnt(14)
	v_mfma_f32_16x16x32_bf16 v[128:131], v[8:11], v[12:15], v[128:131]
	global_load_lds_dwordx4 v[184:185], off
	s_waitcnt lgkmcnt(13)
	v_mfma_f32_16x16x32_bf16 v[124:127], v[16:19], v[12:15], v[124:127]
	s_waitcnt lgkmcnt(12)
	v_mfma_f32_16x16x32_bf16 v[120:123], v[20:23], v[12:15], v[120:123]
	s_waitcnt lgkmcnt(11)
	v_mfma_f32_16x16x32_bf16 v[112:115], v[24:27], v[12:15], v[112:115]
	s_add_u32 m0, s100, 0xd000
	s_waitcnt lgkmcnt(10)
	v_mfma_f32_16x16x32_bf16 v[116:119], v[8:11], v[28:31], v[116:119]
	global_load_lds_dwordx4 v[186:187], off
	v_mfma_f32_16x16x32_bf16 v[108:111], v[16:19], v[28:31], v[108:111]
	v_mfma_f32_16x16x32_bf16 v[104:107], v[20:23], v[28:31], v[104:107]
	v_mfma_f32_16x16x32_bf16 v[100:103], v[24:27], v[28:31], v[100:103]
	s_add_u32 m0, s100, 0xe000
	s_waitcnt lgkmcnt(9)
	v_mfma_f32_16x16x32_bf16 v[96:99], v[8:11], v[32:35], v[96:99]
	global_load_lds_dwordx4 v[188:189], off
	v_mfma_f32_16x16x32_bf16 v[92:95], v[16:19], v[32:35], v[92:95]
	v_mfma_f32_16x16x32_bf16 v[88:91], v[20:23], v[32:35], v[88:91]
	v_mfma_f32_16x16x32_bf16 v[84:87], v[24:27], v[32:35], v[84:87]
	s_add_u32 m0, s100, 0xf000
	s_waitcnt lgkmcnt(8)
	v_mfma_f32_16x16x32_bf16 v[80:83], v[8:11], v[36:39], v[80:83]
	global_load_lds_dwordx4 v[190:191], off
	v_mfma_f32_16x16x32_bf16 v[76:79], v[16:19], v[36:39], v[76:79]
	v_mfma_f32_16x16x32_bf16 v[72:75], v[20:23], v[36:39], v[72:75]
	v_mfma_f32_16x16x32_bf16 v[68:71], v[24:27], v[36:39], v[68:71]
	s_waitcnt lgkmcnt(6)
	v_mfma_f32_16x16x32_bf16 v[128:131], v[40:43], v[44:47], v[128:131]
	s_waitcnt lgkmcnt(5)
	v_mfma_f32_16x16x32_bf16 v[124:127], v[48:51], v[44:47], v[124:127]
	s_waitcnt lgkmcnt(4)
	v_mfma_f32_16x16x32_bf16 v[120:123], v[52:55], v[44:47], v[120:123]
	s_waitcnt lgkmcnt(3)
	v_mfma_f32_16x16x32_bf16 v[112:115], v[56:59], v[44:47], v[112:115]
	s_waitcnt lgkmcnt(2)
	v_mfma_f32_16x16x32_bf16 v[116:119], v[40:43], v[60:63], v[116:119]
	v_mfma_f32_16x16x32_bf16 v[108:111], v[48:51], v[60:63], v[108:111]
	v_mfma_f32_16x16x32_bf16 v[104:107], v[52:55], v[60:63], v[104:107]
	v_mfma_f32_16x16x32_bf16 v[100:103], v[56:59], v[60:63], v[100:103]
	s_and_b64 vcc, exec, s[30:31]
	s_cbranch_vccnz .Lgd_cur_6
	s_and_b64 vcc, exec, s[22:23]
	s_cbranch_vccnz .Lgd_next_6
	v_mov_b64_e32 v[176:177], v[150:151]
	v_mov_b64_e32 v[178:179], v[164:165]
	v_mov_b64_e32 v[180:181], v[166:167]
	v_mov_b64_e32 v[182:183], v[168:169]
	v_mov_b64_e32 v[184:185], v[148:149]
	v_mov_b64_e32 v[186:187], v[170:171]
	v_mov_b64_e32 v[188:189], v[172:173]
	v_mov_b64_e32 v[190:191], v[174:175]
	s_branch .Lgd_go_6

.Lgd_go_6:
	s_waitcnt vmcnt(0) lgkmcnt(0)
	s_barrier
	ds_read_b128 v[8:11], v6 offset:32768
	ds_read_b128 v[12:15], v4 offset:32768
	ds_read_b128 v[16:19], v6 offset:34816
	ds_read_b128 v[20:23], v6 offset:36864
	ds_read_b128 v[24:27], v6 offset:38912
	ds_read_b128 v[28:31], v4 offset:34816
	ds_read_b128 v[32:35], v4 offset:36864
	ds_read_b128 v[36:39], v4 offset:38912
	v_mfma_f32_16x16x32_bf16 v[96:99], v[40:43], v[64:67], v[96:99]
	v_mfma_f32_16x16x32_bf16 v[92:95], v[48:51], v[64:67], v[92:95]
	v_mfma_f32_16x16x32_bf16 v[88:91], v[52:55], v[64:67], v[88:91]
	v_mfma_f32_16x16x32_bf16 v[84:87], v[56:59], v[64:67], v[84:87]
	v_mfma_f32_16x16x32_bf16 v[80:83], v[40:43], v[132:135], v[80:83]
	v_mfma_f32_16x16x32_bf16 v[76:79], v[48:51], v[132:135], v[76:79]
	v_mfma_f32_16x16x32_bf16 v[72:75], v[52:55], v[132:135], v[72:75]
	v_mfma_f32_16x16x32_bf16 v[68:71], v[56:59], v[132:135], v[68:71]
	s_add_u32 m0, s100, 0x0
	s_nop 0
	global_load_lds_dwordx4 v[176:177], off
	s_add_u32 m0, s100, 0x1000
	s_nop 0
	global_load_lds_dwordx4 v[178:179], off
	s_add_u32 m0, s100, 0x2000
	s_nop 0
	global_load_lds_dwordx4 v[180:181], off
	s_add_u32 m0, s100, 0x3000
	s_nop 0
	global_load_lds_dwordx4 v[182:183], off
	s_waitcnt lgkmcnt(7)
	ds_read_b128 v[40:43], v7 offset:32768
	ds_read_b128 v[44:47], v5 offset:32768
	ds_read_b128 v[48:51], v7 offset:34816
	ds_read_b128 v[52:55], v7 offset:36864
	ds_read_b128 v[56:59], v7 offset:38912
	ds_read_b128 v[60:63], v5 offset:34816
	ds_read_b128 v[64:67], v5 offset:36864
	ds_read_b128 v[132:135], v5 offset:38912
	s_add_u32 m0, s100, 0x4000
	s_waitcnt lgkmcnt(14)
	v_mfma_f32_16x16x32_bf16 v[128:131], v[8:11], v[12:15], v[128:131]
	global_load_lds_dwordx4 v[184:185], off
	s_waitcnt lgkmcnt(13)
	v_mfma_f32_16x16x32_bf16 v[124:127], v[16:19], v[12:15], v[124:127]
	s_waitcnt lgkmcnt(12)
	v_mfma_f32_16x16x32_bf16 v[120:123], v[20:23], v[12:15], v[120:123]
	s_waitcnt lgkmcnt(11)
	v_mfma_f32_16x16x32_bf16 v[112:115], v[24:27], v[12:15], v[112:115]
	s_add_u32 m0, s100, 0x5000
	s_waitcnt lgkmcnt(10)
	v_mfma_f32_16x16x32_bf16 v[116:119], v[8:11], v[28:31], v[116:119]
	global_load_lds_dwordx4 v[186:187], off
	v_mfma_f32_16x16x32_bf16 v[108:111], v[16:19], v[28:31], v[108:111]
	v_mfma_f32_16x16x32_bf16 v[104:107], v[20:23], v[28:31], v[104:107]
	v_mfma_f32_16x16x32_bf16 v[100:103], v[24:27], v[28:31], v[100:103]
	s_add_u32 m0, s100, 0x6000
	s_waitcnt lgkmcnt(9)
	v_mfma_f32_16x16x32_bf16 v[96:99], v[8:11], v[32:35], v[96:99]
	global_load_lds_dwordx4 v[188:189], off
	v_mfma_f32_16x16x32_bf16 v[92:95], v[16:19], v[32:35], v[92:95]
	v_mfma_f32_16x16x32_bf16 v[88:91], v[20:23], v[32:35], v[88:91]
	v_mfma_f32_16x16x32_bf16 v[84:87], v[24:27], v[32:35], v[84:87]
	s_add_u32 m0, s100, 0x7000
	s_waitcnt lgkmcnt(8)
	v_mfma_f32_16x16x32_bf16 v[80:83], v[8:11], v[36:39], v[80:83]
	global_load_lds_dwordx4 v[190:191], off
	v_mfma_f32_16x16x32_bf16 v[76:79], v[16:19], v[36:39], v[76:79]
	v_mfma_f32_16x16x32_bf16 v[72:75], v[20:23], v[36:39], v[72:75]
	v_mfma_f32_16x16x32_bf16 v[68:71], v[24:27], v[36:39], v[68:71]
	s_waitcnt lgkmcnt(6)
	v_mfma_f32_16x16x32_bf16 v[128:131], v[40:43], v[44:47], v[128:131]
	s_waitcnt lgkmcnt(5)
	v_mfma_f32_16x16x32_bf16 v[124:127], v[48:51], v[44:47], v[124:127]
	s_waitcnt lgkmcnt(4)
	v_mfma_f32_16x16x32_bf16 v[120:123], v[52:55], v[44:47], v[120:123]
	s_waitcnt lgkmcnt(3)
	v_mfma_f32_16x16x32_bf16 v[112:115], v[56:59], v[44:47], v[112:115]
	s_waitcnt lgkmcnt(2)
	v_mfma_f32_16x16x32_bf16 v[116:119], v[40:43], v[60:63], v[116:119]
	v_mfma_f32_16x16x32_bf16 v[108:111], v[48:51], v[60:63], v[108:111]
	v_mfma_f32_16x16x32_bf16 v[104:107], v[52:55], v[60:63], v[104:107]
	v_mfma_f32_16x16x32_bf16 v[100:103], v[56:59], v[60:63], v[100:103]
	s_add_u32 s24, s24, 0x100
	s_addc_u32 s25, s25, 0
	s_add_i32 s52, s52, 2
	v_lshl_add_u64 v[176:177], v[150:151], 0, s[24:25]
	v_lshl_add_u64 v[178:179], v[164:165], 0, s[24:25]
	v_lshl_add_u64 v[180:181], v[166:167], 0, s[24:25]
	v_lshl_add_u64 v[182:183], v[168:169], 0, s[24:25]
	v_lshl_add_u64 v[184:185], v[148:149], 0, s[24:25]
	v_lshl_add_u64 v[186:187], v[170:171], 0, s[24:25]
	v_lshl_add_u64 v[188:189], v[172:173], 0, s[24:25]
	v_lshl_add_u64 v[190:191], v[174:175], 0, s[24:25]
	s_and_b64 vcc, exec, s[30:31]
	s_waitcnt vmcnt(0) lgkmcnt(0)
	s_barrier
	s_cbranch_vccnz .Lgd_top_6
	v_mfma_f32_16x16x32_bf16 v[96:99], v[40:43], v[64:67], v[96:99]
	v_mfma_f32_16x16x32_bf16 v[92:95], v[48:51], v[64:67], v[92:95]
	v_mfma_f32_16x16x32_bf16 v[88:91], v[52:55], v[64:67], v[88:91]
	v_mfma_f32_16x16x32_bf16 v[84:87], v[56:59], v[64:67], v[84:87]
	v_mfma_f32_16x16x32_bf16 v[80:83], v[40:43], v[132:135], v[80:83]
	v_mfma_f32_16x16x32_bf16 v[76:79], v[48:51], v[132:135], v[76:79]
	v_mfma_f32_16x16x32_bf16 v[72:75], v[52:55], v[132:135], v[72:75]
	v_mfma_f32_16x16x32_bf16 v[68:71], v[56:59], v[132:135], v[68:71]
	s_branch .LBB0_273

.LBB0_295:
	s_or_b64 exec, exec, s[2:3]
	v_readlane_b32 s6, v253, 13
	s_waitcnt vmcnt(1)
	v_mov_b32_e32 v68, v194
	s_movk_i32 s0, 0x400
	s_movk_i32 s2, 0x400
	s_movk_i32 s1, 0x400
	v_readlane_b32 s7, v253, 14
	s_load_dword s3, s[6:7], 0x10
	s_load_dword s22, s[6:7], 0x0
	s_waitcnt lgkmcnt(0)
	s_lshr_b32 s3, s3, 16
	s_cmp_lg_u32 s3, 0
	s_cselect_b64 s[20:21], -1, 0
	s_cmp_lg_u64 s[20:21], 0
	s_addc_u32 s3, s22, 0
	s_lshr_b32 s46, s3, 3
	v_readlane_b32 s3, v254, 36
	s_mul_i32 s52, s46, s3
	v_readlane_b32 s3, v254, 30
	s_add_i32 s52, s52, s3
	s_cmpk_gt_i32 s52, 0x10ff
	s_cbranch_scc1 .LBB0_319
	v_readlane_b32 s6, v254, 63
	s_ashr_i32 s47, s1, 6
	v_readlane_b32 s7, v255, 0
	s_and_b64 s[20:21], s[6:7], exec
	s_mov_b32 s1, 0x2080000
	v_readlane_b32 s8, v252, 37
	s_cselect_b32 s1, s1, 0xc40000
	v_readlane_b32 s16, v252, 45
	v_readlane_b32 s17, v252, 46
	s_add_u32 s24, s16, s1
	s_addc_u32 s25, s17, 0
	s_ashr_i32 s1, s52, 31
	s_lshr_b32 s1, s1, 24
	v_readlane_b32 s20, v252, 49
	s_add_i32 s1, s52, s1
	s_ashr_i32 s1, s1, 8
	s_lshl_b32 s20, s52, 7
	v_lshlrev_b32_e32 v0, 3, v68
	v_readlane_b32 s21, v252, 50
	v_ashrrev_i32_e32 v3, 3, v68
	s_lshl_b32 s3, s1, 10
	s_and_b32 s20, s20, 0x380
	v_and_b32_e32 v0, 56, v0
	v_lshrrev_b32_e32 v132, 4, v68
	v_xor_b32_e32 v132, v132, v68
	v_and_b32_e32 v132, 7, v132
	v_lshlrev_b32_e32 v0, 3, v132
	v_mov_b32_e32 v1, v2
	s_or_b32 s55, s3, s20
	s_lshl_b32 s1, s1, 12
	s_lshl_b32 s3, s52, 4
	v_mad_i64_i32 v[4:5], s[20:21], s0, v3, v[0:1]
	v_mad_i64_i32 v[0:1], s[20:21], s2, v3, v[0:1]
	s_sub_i32 s1, s3, s1
	s_mul_hi_i32 s21, s55, s0
	s_mul_i32 s20, s55, s0
	s_and_b32 s53, s1, 0xffffff80
	s_ashr_i32 s1, s0, 31
	s_ashr_i32 s3, s2, 31
	s_lshl_b64 s[20:21], s[20:21], 1
	s_add_u32 s20, s76, s20
	s_addc_u32 s21, s77, s21
	v_lshlrev_b64 v[70:71], 1, v[4:5]
	v_lshl_add_u64 v[144:145], s[20:21], 0, v[70:71]
	s_mul_hi_i32 s21, s53, s2
	s_mul_i32 s20, s53, s2
	s_lshl_b64 s[20:21], s[20:21], 1
	s_add_u32 s20, s24, s20
	s_addc_u32 s21, s25, s21
	s_waitcnt vmcnt(0)
	v_lshlrev_b64 v[72:73], 1, v[0:1]
	v_readlane_b32 s22, v252, 51
	v_readlane_b32 s23, v252, 52
	v_lshl_add_u64 v[146:147], s[20:21], 0, v[72:73]
	s_lshl_b64 s[20:21], s[0:1], 6
	v_lshl_add_u64 v[0:1], v[144:145], 0, s[20:21]
	s_lshl_b64 s[22:23], s[2:3], 6
	s_waitcnt vmcnt(0)
	v_lshl_add_u64 v[36:37], v[0:1], 0, s[20:21]
	s_waitcnt vmcnt(0)
	v_lshl_add_u64 v[56:57], v[146:147], 0, s[22:23]
	v_lshl_add_u64 v[40:41], v[36:37], 0, s[20:21]
	s_waitcnt vmcnt(0)
	v_lshl_add_u64 v[60:61], v[56:57], 0, s[22:23]
	s_waitcnt vmcnt(0)
	v_lshl_add_u64 v[64:65], v[60:61], 0, s[22:23]
	s_bfe_u32 s100, s101, 0x20002
	s_lshl_b32 s100, s100, 10
	s_bfe_u32 vcc_lo, s101, 0x80008
	s_add_u32 vcc_lo, vcc_lo, 0
	s_add_u32 vcc_hi, s47, -1
	s_and_b32 vcc_lo, vcc_lo, vcc_hi
	s_lshl_b32 vcc_lo, vcc_lo, 7
	s_mov_b32 vcc_hi, 0
	v_lshl_add_u64 v[20:21], v[144:145], 0, vcc
	s_add_u32 m0, s100, 0x0
	s_nop 0
	global_load_lds_dwordx4 v[20:21], off
	v_lshl_add_u64 v[20:21], v[0:1], 0, vcc
	s_add_u32 m0, s100, 0x1000
	s_nop 0
	global_load_lds_dwordx4 v[20:21], off
	v_lshl_add_u64 v[20:21], v[36:37], 0, vcc
	s_add_u32 m0, s100, 0x2000
	s_nop 0
	global_load_lds_dwordx4 v[20:21], off
	v_lshl_add_u64 v[20:21], v[40:41], 0, vcc
	s_add_u32 m0, s100, 0x3000
	s_nop 0
	global_load_lds_dwordx4 v[20:21], off
	v_lshl_add_u64 v[20:21], v[146:147], 0, vcc
	s_add_u32 m0, s100, 0x4000
	s_nop 0
	global_load_lds_dwordx4 v[20:21], off
	v_lshl_add_u64 v[20:21], v[56:57], 0, vcc
	s_add_u32 m0, s100, 0x5000
	s_nop 0
	global_load_lds_dwordx4 v[20:21], off
	v_lshl_add_u64 v[20:21], v[60:61], 0, vcc
	s_add_u32 m0, s100, 0x6000
	s_nop 0
	global_load_lds_dwordx4 v[20:21], off
	v_lshl_add_u64 v[20:21], v[64:65], 0, vcc
	s_add_u32 m0, s100, 0x7000
	s_nop 0
	global_load_lds_dwordx4 v[20:21], off
	s_bfe_u32 vcc_lo, s101, 0x80008
	s_add_u32 vcc_lo, vcc_lo, 1
	s_add_u32 vcc_hi, s47, -1
	s_and_b32 vcc_lo, vcc_lo, vcc_hi
	s_lshl_b32 vcc_lo, vcc_lo, 7
	s_mov_b32 vcc_hi, 0
	v_lshl_add_u64 v[20:21], v[144:145], 0, vcc
	s_add_u32 m0, s100, 0x8000
	s_nop 0
	global_load_lds_dwordx4 v[20:21], off
	v_lshl_add_u64 v[20:21], v[0:1], 0, vcc
	s_add_u32 m0, s100, 0x9000
	s_nop 0
	global_load_lds_dwordx4 v[20:21], off
	v_lshl_add_u64 v[20:21], v[36:37], 0, vcc
	s_add_u32 m0, s100, 0xa000
	s_nop 0
	global_load_lds_dwordx4 v[20:21], off
	v_lshl_add_u64 v[20:21], v[40:41], 0, vcc
	s_add_u32 m0, s100, 0xb000
	s_nop 0
	global_load_lds_dwordx4 v[20:21], off
	v_lshl_add_u64 v[20:21], v[146:147], 0, vcc
	s_add_u32 m0, s100, 0xc000
	s_nop 0
	global_load_lds_dwordx4 v[20:21], off
	v_lshl_add_u64 v[20:21], v[56:57], 0, vcc
	s_add_u32 m0, s100, 0xd000
	s_nop 0
	global_load_lds_dwordx4 v[20:21], off
	v_lshl_add_u64 v[20:21], v[60:61], 0, vcc
	s_add_u32 m0, s100, 0xe000
	s_nop 0
	global_load_lds_dwordx4 v[20:21], off
	v_lshl_add_u64 v[20:21], v[64:65], 0, vcc
	s_add_u32 m0, s100, 0xf000
	s_nop 0
	global_load_lds_dwordx4 v[20:21], off
	v_lshrrev_b32_e32 v1, 1, v3
	v_xor_b32_e32 v1, v1, v68
	v_lshlrev_b32_e32 v0, 7, v3
	v_lshlrev_b32_e32 v1, 4, v1
	s_movk_i32 s1, 0x70
	v_lshrrev_b32_e32 v69, 4, v68
	v_bfe_u32 v74, v68, 4, 2
	v_and_or_b32 v3, v1, s1, v0
	v_lshl_add_u64 v[0:1], s[76:77], 0, v[70:71]
	v_bfe_u32 v70, v68, 1, 3
	v_bitop3_b32 v69, v69, v70, 3 bitop3:0x6c
	v_lshlrev_b32_e32 v71, 6, v68
	v_lshlrev_b32_e32 v68, 7, v68
	v_bitop3_b32 v70, v74, v70, 4 bitop3:0x36
	v_lshl_add_u64 v[138:139], s[24:25], 0, v[72:73]
	v_lshlrev_b32_e32 v69, 4, v69
	v_and_b32_e32 v71, 0xffffe000, v71
	v_and_b32_e32 v72, 0x780, v68
	v_and_b32_e32 v68, 0x2000, v68
	v_lshlrev_b32_e32 v70, 4, v70
	s_cmp_gt_i32 s47, 0
	v_or_b32_e32 v73, v69, v71
	v_or_b32_e32 v69, v69, v68
	v_or_b32_e32 v71, v70, v71
	v_or_b32_e32 v68, v70, v68
	s_mov_b32 s49, 0
	s_cselect_b64 s[24:25], -1, 0
	v_add_u32_e32 v137, v73, v72
	v_add_u32_e32 v188, v69, v72
	v_add_u32_e32 v189, v71, v72
	v_add_u32_e32 v190, v68, v72
	s_mov_b32 s1, 0
	s_mov_b32 s3, 0
	v_readlane_b32 s9, v252, 38
	v_readlane_b32 s10, v252, 39
	v_readlane_b32 s11, v252, 40
	v_readlane_b32 s12, v252, 41
	v_readlane_b32 s13, v252, 42
	v_readlane_b32 s14, v252, 43
	v_readlane_b32 s15, v252, 44
	v_readlane_b32 s18, v252, 47
	v_readlane_b32 s19, v252, 48
	s_bfe_u32 vcc_lo, s101, 0x10001
	v_and_b32_e32 v20, 15, v194
	v_lshrrev_b32_e32 v21, 1, v20
	v_bfe_u32 v22, v194, 4, 2
	v_xor_b32_e32 v21, v21, v22
	v_lshlrev_b32_e32 v21, 4, v21
	v_lshl_or_b32 v250, v20, 7, v21
	v_mov_b32_e32 v22, vcc_lo
	v_lshl_or_b32 v22, v22, 13, v250
	v_or_b32_e32 v251, 0x4000, v22
	v_and_b32_e32 v20, 63, v194
	v_mov_b32_e32 v21, vcc_lo
	v_lshlrev_b32_e32 v21, 4, v21
	v_lshrrev_b32_e32 v22, 3, v20
	v_add_u32_e32 v21, v21, v22
	v_lshrrev_b32_e32 v22, 4, v20
	v_and_b32_e32 v23, 7, v20
	v_xor_b32_e32 v24, v23, v22
	v_lshlrev_b32_e32 v24, 4, v24
	v_or_b32_e32 v22, 4, v22
	v_xor_b32_e32 v25, v23, v22
	v_lshlrev_b32_e32 v25, 4, v25
	s_lshl_b32 s98, s0, 1
	s_lshl_b32 s99, s2, 1
	v_add_u32_e32 v26, 0, v21
	v_mad_u32_u24 v4, v26, s98, v24
	v_add_u32_e32 v26, 8, v21
	v_mad_u32_u24 v5, v26, s98, v25
	v_add_u32_e32 v26, 32, v21
	v_mad_u32_u24 v6, v26, s98, v24
	v_add_u32_e32 v26, 40, v21
	v_mad_u32_u24 v7, v26, s98, v25
	v_add_u32_e32 v26, 64, v21
	v_mad_u32_u24 v8, v26, s98, v24
	v_add_u32_e32 v26, 72, v21
	v_mad_u32_u24 v9, v26, s98, v25
	v_add_u32_e32 v26, 96, v21
	v_mad_u32_u24 v10, v26, s98, v24
	v_add_u32_e32 v26, 104, v21
	v_mad_u32_u24 v11, v26, s98, v25
	v_add_u32_e32 v26, 0, v21
	v_mad_u32_u24 v12, v26, s99, v24
	v_add_u32_e32 v26, 8, v21
	v_mad_u32_u24 v13, v26, s99, v25
	v_add_u32_e32 v26, 32, v21
	v_mad_u32_u24 v14, v26, s99, v24
	v_add_u32_e32 v26, 40, v21
	v_mad_u32_u24 v15, v26, s99, v25
	v_add_u32_e32 v26, 64, v21
	v_mad_u32_u24 v16, v26, s99, v24
	v_add_u32_e32 v26, 72, v21
	v_mad_u32_u24 v17, v26, s99, v25
	v_add_u32_e32 v26, 96, v21
	v_mad_u32_u24 v18, v26, s99, v24
	v_add_u32_e32 v26, 104, v21
	v_mad_u32_u24 v19, v26, s99, v25
	s_bfe_u32 vcc_hi, s101, 0x20002
	s_lshl_b32 vcc_hi, vcc_hi, 3
	s_mul_i32 s98, s98, vcc_hi
	s_mul_i32 s99, s99, vcc_hi
	s_lshl_b32 vcc_hi, vcc_hi, 3
	s_and_b32 vcc_hi, vcc_hi, 0x70
	s_add_u32 s98, s98, vcc_hi
	s_add_u32 s99, s99, vcc_hi
	s_lshl_b32 s100, vcc_lo, 11
	s_bitcmp1_b32 s101, 0
	s_cselect_b32 s100, -1, s100
	s_waitcnt vmcnt(0) lgkmcnt(0)
	s_barrier
	s_branch .LBB0_299

.LBB0_298:
	v_mov_b32_e32 v132, v194
	v_mov_b32_e32 v133, v194
	v_and_b32_e32 v145, 64, v202
	v_and_b32_e32 v134, 64, v133
	v_ashrrev_i32_e32 v133, 1, v133
	v_and_b32_e32 v135, 15, v132
	v_and_b32_e32 v133, 0xffffffc0, v133
	v_add3_u32 v144, v135, s55, v133
	v_xor_b32_e32 v135, 16, v202
	v_add_u32_e32 v145, 64, v145
	v_mul_f32_e32 v128, 0xbfb8aa3b, v128
	v_mul_f32_e32 v112, 0xbfb8aa3b, v112
	v_mul_f32_e32 v113, 0xbfb8aa3b, v113
	v_mul_f32_e32 v108, 0xbfb8aa3b, v108
	v_mul_f32_e32 v109, 0xbfb8aa3b, v109
	v_mul_f32_e32 v96, 0xbfb8aa3b, v96
	v_mul_f32_e32 v97, 0xbfb8aa3b, v97
	v_mul_f32_e32 v92, 0xbfb8aa3b, v92
	v_mul_f32_e32 v93, 0xbfb8aa3b, v93
	v_mul_f32_e32 v80, 0xbfb8aa3b, v80
	v_mul_f32_e32 v81, 0xbfb8aa3b, v81
	v_mul_f32_e32 v76, 0xbfb8aa3b, v76
	v_mul_f32_e32 v77, 0xbfb8aa3b, v77
	v_cmp_lt_i32_e32 vcc, v135, v145
	v_exp_f32_e32 v145, v128
	v_mul_f32_e32 v128, 0xbfb8aa3b, v129
	v_mul_f32_e32 v130, 0xbfb8aa3b, v130
	v_mul_f32_e32 v131, 0xbfb8aa3b, v131
	v_mul_f32_e32 v124, 0xbfb8aa3b, v124
	v_mul_f32_e32 v125, 0xbfb8aa3b, v125
	v_mul_f32_e32 v126, 0xbfb8aa3b, v126
	v_mul_f32_e32 v127, 0xbfb8aa3b, v127
	v_exp_f32_e32 v112, v112
	v_exp_f32_e32 v113, v113
	v_exp_f32_e32 v108, v108
	v_exp_f32_e32 v109, v109
	v_mul_f32_e32 v106, 0xbfb8aa3b, v106
	v_mul_f32_e32 v107, 0xbfb8aa3b, v107
	v_mul_f32_e32 v100, 0xbfb8aa3b, v100
	v_mul_f32_e32 v101, 0xbfb8aa3b, v101
	v_exp_f32_e32 v96, v96
	v_exp_f32_e32 v97, v97
	v_exp_f32_e32 v92, v92
	v_exp_f32_e32 v93, v93
	v_mul_f32_e32 v90, 0xbfb8aa3b, v90
	v_mul_f32_e32 v91, 0xbfb8aa3b, v91
	v_mul_f32_e32 v84, 0xbfb8aa3b, v84
	v_mul_f32_e32 v85, 0xbfb8aa3b, v85
	v_exp_f32_e32 v80, v80
	v_exp_f32_e32 v81, v81
	v_exp_f32_e32 v76, v76
	v_exp_f32_e32 v77, v77
	v_mul_f32_e32 v74, 0xbfb8aa3b, v74
	v_mul_f32_e32 v75, 0xbfb8aa3b, v75
	v_mul_f32_e32 v68, 0xbfb8aa3b, v68
	v_mul_f32_e32 v69, 0xbfb8aa3b, v69
	v_exp_f32_e32 v129, v128
	v_exp_f32_e32 v130, v130
	v_exp_f32_e32 v131, v131
	v_exp_f32_e32 v124, v124
	v_exp_f32_e32 v125, v125
	v_exp_f32_e32 v126, v126
	v_exp_f32_e32 v127, v127
	v_mul_f32_e32 v116, 0xbfb8aa3b, v116
	v_mul_f32_e32 v117, 0xbfb8aa3b, v117
	v_mul_f32_e32 v110, 0xbfb8aa3b, v110
	v_mul_f32_e32 v111, 0xbfb8aa3b, v111
	v_exp_f32_e32 v106, v106
	v_exp_f32_e32 v107, v107
	v_exp_f32_e32 v100, v100
	v_exp_f32_e32 v101, v101
	v_mul_f32_e32 v102, 0xbfb8aa3b, v102
	v_mul_f32_e32 v103, 0xbfb8aa3b, v103
	v_mul_f32_e32 v94, 0xbfb8aa3b, v94
	v_mul_f32_e32 v95, 0xbfb8aa3b, v95
	v_exp_f32_e32 v90, v90
	v_exp_f32_e32 v91, v91
	v_exp_f32_e32 v84, v84
	v_exp_f32_e32 v85, v85
	v_mul_f32_e32 v86, 0xbfb8aa3b, v86
	v_mul_f32_e32 v87, 0xbfb8aa3b, v87
	v_mul_f32_e32 v78, 0xbfb8aa3b, v78
	v_mul_f32_e32 v79, 0xbfb8aa3b, v79
	v_exp_f32_e32 v74, v74
	v_exp_f32_e32 v75, v75
	v_exp_f32_e32 v68, v68
	v_exp_f32_e32 v69, v69
	v_mul_f32_e32 v70, 0xbfb8aa3b, v70
	v_mul_f32_e32 v71, 0xbfb8aa3b, v71
	v_mul_f32_e32 v120, 0xbfb8aa3b, v120
	v_mul_f32_e32 v121, 0xbfb8aa3b, v121
	v_exp_f32_e32 v116, v116
	v_exp_f32_e32 v117, v117
	v_exp_f32_e32 v110, v110
	v_exp_f32_e32 v111, v111
	v_exp_f32_e32 v102, v102
	v_exp_f32_e32 v103, v103
	v_exp_f32_e32 v94, v94
	v_exp_f32_e32 v95, v95
	v_exp_f32_e32 v86, v86
	v_exp_f32_e32 v87, v87
	v_exp_f32_e32 v78, v78
	v_exp_f32_e32 v79, v79
	v_exp_f32_e32 v70, v70
	v_exp_f32_e32 v71, v71
	v_and_b32_e32 v133, 16, v132
	v_cndmask_b32_e32 v135, v202, v135, vcc
	v_lshrrev_b32_e32 v132, 2, v132
	v_exp_f32_e32 v120, v120
	v_exp_f32_e32 v121, v121
	v_lshlrev_b32_e32 v146, 2, v135
	v_and_b32_e32 v132, 8, v132
	v_add_u32_e32 v135, s53, v133
	v_add_f32_e32 v112, 1.0, v112
	v_add_f32_e32 v113, 1.0, v113
	v_mul_f32_e32 v114, 0xbfb8aa3b, v114
	v_mul_f32_e32 v115, 0xbfb8aa3b, v115
	v_add_f32_e32 v108, 1.0, v108
	v_add_f32_e32 v109, 1.0, v109
	v_add_f32_e32 v96, 1.0, v96
	v_add_f32_e32 v97, 1.0, v97
	v_mul_f32_e32 v98, 0xbfb8aa3b, v98
	v_mul_f32_e32 v99, 0xbfb8aa3b, v99
	v_add_f32_e32 v92, 1.0, v92
	v_add_f32_e32 v93, 1.0, v93
	v_add_f32_e32 v80, 1.0, v80
	v_add_f32_e32 v81, 1.0, v81
	v_mul_f32_e32 v82, 0xbfb8aa3b, v82
	v_mul_f32_e32 v83, 0xbfb8aa3b, v83
	v_add_f32_e32 v76, 1.0, v76
	v_add_f32_e32 v77, 1.0, v77
	v_add3_u32 v128, v135, v134, v132
	v_add_f32_e32 v132, 1.0, v145
	v_add_f32_e32 v129, 1.0, v129
	v_add_f32_e32 v130, 1.0, v130
	v_add_f32_e32 v131, 1.0, v131
	v_add_f32_e32 v124, 1.0, v124
	v_add_f32_e32 v125, 1.0, v125
	v_add_f32_e32 v126, 1.0, v126
	v_add_f32_e32 v127, 1.0, v127
	v_mul_f32_e32 v122, 0xbfb8aa3b, v122
	v_mul_f32_e32 v123, 0xbfb8aa3b, v123
	v_mul_f32_e32 v118, 0xbfb8aa3b, v118
	v_mul_f32_e32 v119, 0xbfb8aa3b, v119
	v_rcp_f32_e32 v112, v112
	v_exp_f32_e32 v114, v114
	v_exp_f32_e32 v115, v115
	v_rcp_f32_e32 v113, v113
	v_rcp_f32_e32 v108, v108
	v_rcp_f32_e32 v109, v109
	v_mul_f32_e32 v104, 0xbfb8aa3b, v104
	v_mul_f32_e32 v105, 0xbfb8aa3b, v105
	v_add_f32_e32 v106, 1.0, v106
	v_add_f32_e32 v107, 1.0, v107
	v_add_f32_e32 v100, 1.0, v100
	v_add_f32_e32 v101, 1.0, v101
	v_rcp_f32_e32 v96, v96
	v_exp_f32_e32 v98, v98
	v_exp_f32_e32 v99, v99
	v_rcp_f32_e32 v97, v97
	v_rcp_f32_e32 v92, v92
	v_rcp_f32_e32 v93, v93
	v_mul_f32_e32 v88, 0xbfb8aa3b, v88
	v_mul_f32_e32 v89, 0xbfb8aa3b, v89
	v_add_f32_e32 v90, 1.0, v90
	v_add_f32_e32 v91, 1.0, v91
	v_add_f32_e32 v84, 1.0, v84
	v_add_f32_e32 v85, 1.0, v85
	v_rcp_f32_e32 v80, v80
	v_exp_f32_e32 v82, v82
	v_exp_f32_e32 v83, v83
	v_rcp_f32_e32 v81, v81
	v_rcp_f32_e32 v76, v76
	v_rcp_f32_e32 v77, v77
	v_mul_f32_e32 v72, 0xbfb8aa3b, v72
	v_mul_f32_e32 v73, 0xbfb8aa3b, v73
	v_add_f32_e32 v74, 1.0, v74
	v_add_f32_e32 v75, 1.0, v75
	v_add_f32_e32 v68, 1.0, v68
	v_add_f32_e32 v69, 1.0, v69
	v_rcp_f32_e32 v132, v132
	v_rcp_f32_e32 v129, v129
	v_rcp_f32_e32 v130, v130
	v_rcp_f32_e32 v131, v131
	v_rcp_f32_e32 v124, v124
	v_rcp_f32_e32 v125, v125
	v_rcp_f32_e32 v126, v126
	v_rcp_f32_e32 v127, v127
	v_exp_f32_e32 v122, v122
	v_exp_f32_e32 v123, v123
	v_add_f32_e32 v116, 1.0, v116
	v_add_f32_e32 v117, 1.0, v117
	v_exp_f32_e32 v118, v118
	v_exp_f32_e32 v119, v119
	v_add_f32_e32 v110, 1.0, v110
	v_add_f32_e32 v111, 1.0, v111
	v_exp_f32_e32 v104, v104
	v_exp_f32_e32 v105, v105
	v_rcp_f32_e32 v106, v106
	v_rcp_f32_e32 v107, v107
	v_rcp_f32_e32 v100, v100
	v_rcp_f32_e32 v101, v101
	v_add_f32_e32 v102, 1.0, v102
	v_add_f32_e32 v103, 1.0, v103
	v_add_f32_e32 v94, 1.0, v94
	v_add_f32_e32 v95, 1.0, v95
	v_exp_f32_e32 v88, v88
	v_exp_f32_e32 v89, v89
	v_rcp_f32_e32 v90, v90
	v_rcp_f32_e32 v91, v91
	v_rcp_f32_e32 v84, v84
	v_rcp_f32_e32 v85, v85
	v_add_f32_e32 v86, 1.0, v86
	v_add_f32_e32 v87, 1.0, v87
	v_add_f32_e32 v78, 1.0, v78
	v_add_f32_e32 v79, 1.0, v79
	v_exp_f32_e32 v72, v72
	v_exp_f32_e32 v73, v73
	v_rcp_f32_e32 v74, v74
	v_rcp_f32_e32 v75, v75
	v_rcp_f32_e32 v68, v68
	v_rcp_f32_e32 v69, v69
	v_add_f32_e32 v70, 1.0, v70
	v_add_f32_e32 v71, 1.0, v71
	v_add_f32_e32 v120, 1.0, v120
	v_add_f32_e32 v121, 1.0, v121
	v_rcp_f32_e32 v116, v116
	v_rcp_f32_e32 v117, v117
	v_rcp_f32_e32 v110, v110
	v_rcp_f32_e32 v111, v111
	v_rcp_f32_e32 v102, v102
	v_rcp_f32_e32 v103, v103
	v_rcp_f32_e32 v94, v94
	v_rcp_f32_e32 v95, v95
	v_rcp_f32_e32 v86, v86
	v_rcp_f32_e32 v87, v87
	v_rcp_f32_e32 v78, v78
	v_rcp_f32_e32 v79, v79
	v_rcp_f32_e32 v70, v70
	v_rcp_f32_e32 v71, v71
	v_rcp_f32_e32 v120, v120
	v_rcp_f32_e32 v121, v121
	v_cmp_eq_u32_e32 vcc, 0, v133
	v_add_f32_e32 v114, 1.0, v114
	v_add_f32_e32 v115, 1.0, v115
	v_cvt_pk_bf16_f32 v112, v112, v113
	v_cvt_pk_bf16_f32 v108, v108, v109
	v_add_f32_e32 v98, 1.0, v98
	v_add_f32_e32 v99, 1.0, v99
	v_cvt_pk_bf16_f32 v96, v96, v97
	v_cvt_pk_bf16_f32 v92, v92, v93
	v_add_f32_e32 v82, 1.0, v82
	v_add_f32_e32 v83, 1.0, v83
	v_cvt_pk_bf16_f32 v80, v80, v81
	v_cvt_pk_bf16_f32 v76, v76, v77
	v_cvt_pk_bf16_f32 v129, v132, v129
	v_cvt_pk_bf16_f32 v130, v130, v131
	v_cvt_pk_bf16_f32 v124, v124, v125
	v_cvt_pk_bf16_f32 v125, v126, v127
	v_add_f32_e32 v122, 1.0, v122
	v_add_f32_e32 v123, 1.0, v123
	v_add_f32_e32 v118, 1.0, v118
	v_add_f32_e32 v119, 1.0, v119
	v_rcp_f32_e32 v114, v114
	v_rcp_f32_e32 v115, v115
	v_add_f32_e32 v104, 1.0, v104
	v_add_f32_e32 v105, 1.0, v105
	v_cvt_pk_bf16_f32 v106, v106, v107
	v_cvt_pk_bf16_f32 v107, v100, v101
	v_cndmask_b32_e32 v101, v112, v108, vcc
	v_rcp_f32_e32 v98, v98
	v_rcp_f32_e32 v99, v99
	v_add_f32_e32 v88, 1.0, v88
	v_add_f32_e32 v89, 1.0, v89
	v_cvt_pk_bf16_f32 v90, v90, v91
	v_cvt_pk_bf16_f32 v91, v84, v85
	v_cndmask_b32_e32 v85, v96, v92, vcc
	v_rcp_f32_e32 v82, v82
	v_rcp_f32_e32 v83, v83
	v_add_f32_e32 v72, 1.0, v72
	v_add_f32_e32 v73, 1.0, v73
	v_cvt_pk_bf16_f32 v74, v74, v75
	v_cvt_pk_bf16_f32 v75, v68, v69
	v_cndmask_b32_e32 v69, v80, v76, vcc
	v_rcp_f32_e32 v122, v122
	v_rcp_f32_e32 v123, v123
	v_rcp_f32_e32 v118, v118
	v_rcp_f32_e32 v119, v119
	v_cvt_pk_bf16_f32 v131, v116, v117
	v_cndmask_b32_e32 v116, v129, v124, vcc
	v_cndmask_b32_e32 v117, v130, v125, vcc
	v_cvt_pk_bf16_f32 v109, v110, v111
	v_rcp_f32_e32 v104, v104
	v_rcp_f32_e32 v105, v105
	v_cvt_pk_bf16_f32 v111, v102, v103
	ds_bpermute_b32 v103, v146, v101
	v_cvt_pk_bf16_f32 v93, v94, v95
	v_rcp_f32_e32 v88, v88
	v_rcp_f32_e32 v89, v89
	v_cvt_pk_bf16_f32 v95, v86, v87
	ds_bpermute_b32 v87, v146, v85
	v_cvt_pk_bf16_f32 v77, v78, v79
	v_rcp_f32_e32 v72, v72
	v_rcp_f32_e32 v73, v73
	v_cvt_pk_bf16_f32 v79, v70, v71
	ds_bpermute_b32 v71, v146, v69
	v_cvt_pk_bf16_f32 v126, v120, v121
	ds_bpermute_b32 v120, v146, v116
	ds_bpermute_b32 v121, v146, v117
	v_add_u32_e32 v100, 16, v144
	v_add_u32_e32 v84, 32, v144
	v_add_u32_e32 v68, 48, v144
	v_ashrrev_i32_e32 v145, 31, v144
	v_cvt_pk_bf16_f32 v113, v114, v115
	v_ashrrev_i32_e32 v101, 31, v100
	v_cvt_pk_bf16_f32 v97, v98, v99
	v_ashrrev_i32_e32 v85, 31, v84
	v_cvt_pk_bf16_f32 v81, v82, v83
	v_ashrrev_i32_e32 v69, 31, v68
	v_cvt_pk_bf16_f32 v127, v122, v123
	v_cvt_pk_bf16_f32 v132, v118, v119
	v_lshlrev_b64 v[116:117], 13, v[144:145]
	v_cvt_pk_bf16_f32 v110, v104, v105
	v_cndmask_b32_e32 v102, v113, v109, vcc
	v_lshlrev_b64 v[100:101], 13, v[100:101]
	v_cvt_pk_bf16_f32 v94, v88, v89
	v_cndmask_b32_e32 v86, v97, v93, vcc
	v_lshlrev_b64 v[84:85], 13, v[84:85]
	v_cvt_pk_bf16_f32 v78, v72, v73
	v_cndmask_b32_e32 v70, v81, v77, vcc
	v_lshlrev_b64 v[68:69], 13, v[68:69]
	v_lshl_add_u64 v[122:123], s[78:79], 0, v[116:117]
	v_cndmask_b32_e32 v116, v126, v131, vcc
	v_cndmask_b32_e32 v117, v127, v132, vcc
	ds_bpermute_b32 v114, v146, v102
	v_lshl_add_u64 v[104:105], s[78:79], 0, v[100:101]
	s_waitcnt lgkmcnt(5)
	v_cndmask_b32_e32 v100, v103, v112, vcc
	v_cndmask_b32_e32 v102, v108, v103, vcc
	v_cndmask_b32_e32 v103, v110, v107, vcc
	v_cndmask_b32_e32 v108, v106, v111, vcc
	ds_bpermute_b32 v98, v146, v86
	v_lshl_add_u64 v[88:89], s[78:79], 0, v[84:85]
	s_waitcnt lgkmcnt(5)
	v_cndmask_b32_e32 v84, v87, v96, vcc
	v_cndmask_b32_e32 v86, v92, v87, vcc
	v_cndmask_b32_e32 v87, v94, v91, vcc
	v_cndmask_b32_e32 v92, v90, v95, vcc
	ds_bpermute_b32 v82, v146, v70
	v_lshl_add_u64 v[72:73], s[78:79], 0, v[68:69]
	s_waitcnt lgkmcnt(5)
	v_cndmask_b32_e32 v68, v71, v80, vcc
	v_cndmask_b32_e32 v70, v76, v71, vcc
	v_cndmask_b32_e32 v71, v78, v75, vcc
	v_cndmask_b32_e32 v76, v74, v79, vcc
	s_waitcnt lgkmcnt(4)
	v_cndmask_b32_e32 v118, v120, v129, vcc
	s_waitcnt lgkmcnt(3)
	v_cndmask_b32_e32 v119, v121, v130, vcc
	v_cndmask_b32_e32 v120, v124, v120, vcc
	v_cndmask_b32_e32 v121, v125, v121, vcc
	ds_bpermute_b32 v124, v146, v116
	ds_bpermute_b32 v125, v146, v117
	ds_bpermute_b32 v112, v146, v103
	ds_bpermute_b32 v108, v146, v108
	ds_bpermute_b32 v96, v146, v87
	ds_bpermute_b32 v92, v146, v92
	ds_bpermute_b32 v80, v146, v71
	ds_bpermute_b32 v76, v146, v76
	v_ashrrev_i32_e32 v129, 31, v128
	v_lshlrev_b64 v[116:117], 1, v[128:129]
	v_lshl_add_u64 v[122:123], v[122:123], 0, v[116:117]
	s_waitcnt lgkmcnt(10)
	v_cndmask_b32_e32 v101, v114, v113, vcc
	v_cndmask_b32_e32 v103, v109, v114, vcc
	v_lshl_add_u64 v[104:105], v[104:105], 0, v[116:117]
	s_waitcnt lgkmcnt(9)
	v_cndmask_b32_e32 v85, v98, v97, vcc
	v_cndmask_b32_e32 v87, v93, v98, vcc
	v_lshl_add_u64 v[88:89], v[88:89], 0, v[116:117]
	s_waitcnt lgkmcnt(8)
	v_cndmask_b32_e32 v69, v82, v81, vcc
	v_cndmask_b32_e32 v71, v77, v82, vcc
	v_lshl_add_u64 v[72:73], v[72:73], 0, v[116:117]
	global_store_dwordx4 v[122:123], v[118:121], off
	global_store_dwordx4 v[104:105], v[100:103], off
	global_store_dwordx4 v[88:89], v[84:87], off
	s_waitcnt lgkmcnt(7)
	v_cndmask_b32_e32 v118, v124, v126, vcc
	s_waitcnt lgkmcnt(6)
	v_cndmask_b32_e32 v119, v125, v127, vcc
	v_cndmask_b32_e32 v120, v131, v124, vcc
	v_cndmask_b32_e32 v121, v132, v125, vcc
	s_waitcnt lgkmcnt(5)
	v_cndmask_b32_e32 v100, v112, v110, vcc
	s_waitcnt lgkmcnt(4)
	v_cndmask_b32_e32 v101, v108, v106, vcc
	v_cndmask_b32_e32 v102, v107, v112, vcc
	v_cndmask_b32_e32 v103, v111, v108, vcc
	s_waitcnt lgkmcnt(3)
	v_cndmask_b32_e32 v84, v96, v94, vcc
	s_waitcnt lgkmcnt(2)
	v_cndmask_b32_e32 v85, v92, v90, vcc
	v_cndmask_b32_e32 v86, v91, v96, vcc
	v_cndmask_b32_e32 v87, v95, v92, vcc
	global_store_dwordx4 v[72:73], v[68:71], off
	s_mov_b32 s55, s49
	s_mov_b32 s53, s1
	s_waitcnt lgkmcnt(1)
	v_cndmask_b32_e32 v68, v80, v78, vcc
	s_waitcnt lgkmcnt(0)
	v_cndmask_b32_e32 v69, v76, v74, vcc
	v_cndmask_b32_e32 v70, v75, v80, vcc
	v_cndmask_b32_e32 v71, v79, v76, vcc
	s_and_b64 vcc, exec, s[26:27]
	v_mov_b64_e32 v[146:147], v[142:143]
	v_mov_b64_e32 v[144:145], v[140:141]
	global_store_dwordx4 v[122:123], v[118:121], off offset:64
	global_store_dwordx4 v[104:105], v[100:103], off offset:64
	global_store_dwordx4 v[88:89], v[84:87], off offset:64
	global_store_dwordx4 v[72:73], v[68:71], off offset:64
	s_branch .Lpc_edone_3

.LBB0_301:
	s_mul_hi_i32 s35, s49, s0
	s_mul_i32 s34, s49, s0
	v_lshl_add_u64 v[140:141], s[34:35], 1, v[0:1]
	s_mul_hi_i32 s35, s1, s2
	s_mul_i32 s34, s1, s2
	v_lshl_add_u64 v[142:143], s[34:35], 1, v[138:139]
	s_andn2_b64 vcc, exec, s[24:25]
	s_cbranch_vccnz .LBB0_318
	v_lshl_add_u64 v[148:149], v[140:141], 0, s[20:21]
	v_lshl_add_u64 v[154:155], v[142:143], 0, s[22:23]
	v_lshl_add_u64 v[160:161], v[144:145], 0, s[20:21]
	v_lshl_add_u64 v[166:167], v[146:147], 0, s[22:23]
	v_lshl_add_u64 v[150:151], v[148:149], 0, s[20:21]
	v_lshl_add_u64 v[156:157], v[154:155], 0, s[22:23]
	v_lshl_add_u64 v[162:163], v[160:161], 0, s[20:21]
	v_lshl_add_u64 v[168:169], v[166:167], 0, s[22:23]
	v_mov_b32_e32 v68, 0
	v_lshl_add_u64 v[152:153], v[150:151], 0, s[20:21]
	v_lshl_add_u64 v[158:159], v[156:157], 0, s[22:23]
	v_lshl_add_u64 v[164:165], v[162:163], 0, s[20:21]
	v_lshl_add_u64 v[170:171], v[168:169], 0, s[22:23]
	s_mov_b64 s[34:35], 0x100
	s_mov_b32 s96, 2
	v_mov_b32_e32 v69, v68
	v_mov_b32_e32 v70, v68
	v_mov_b32_e32 v71, v68
	v_mov_b32_e32 v72, v68
	v_mov_b32_e32 v73, v68
	v_mov_b32_e32 v74, v68
	v_mov_b32_e32 v75, v68
	v_mov_b32_e32 v76, v68
	v_mov_b32_e32 v77, v68
	v_mov_b32_e32 v78, v68
	v_mov_b32_e32 v79, v68
	v_mov_b32_e32 v80, v68
	v_mov_b32_e32 v81, v68
	v_mov_b32_e32 v82, v68
	v_mov_b32_e32 v83, v68
	v_mov_b32_e32 v84, v68
	v_mov_b32_e32 v85, v68
	v_mov_b32_e32 v86, v68
	v_mov_b32_e32 v87, v68
	v_mov_b32_e32 v88, v68
	v_mov_b32_e32 v89, v68
	v_mov_b32_e32 v90, v68
	v_mov_b32_e32 v91, v68
	v_mov_b32_e32 v92, v68
	v_mov_b32_e32 v93, v68
	v_mov_b32_e32 v94, v68
	v_mov_b32_e32 v95, v68
	v_mov_b32_e32 v96, v68
	v_mov_b32_e32 v97, v68
	v_mov_b32_e32 v98, v68
	v_mov_b32_e32 v99, v68
	v_mov_b32_e32 v100, v68
	v_mov_b32_e32 v101, v68
	v_mov_b32_e32 v102, v68
	v_mov_b32_e32 v103, v68
	v_mov_b32_e32 v104, v68
	v_mov_b32_e32 v105, v68
	v_mov_b32_e32 v106, v68
	v_mov_b32_e32 v107, v68
	v_mov_b32_e32 v108, v68
	v_mov_b32_e32 v109, v68
	v_mov_b32_e32 v110, v68
	v_mov_b32_e32 v111, v68
	v_mov_b32_e32 v112, v68
	v_mov_b32_e32 v113, v68
	v_mov_b32_e32 v114, v68
	v_mov_b32_e32 v115, v68
	v_mov_b32_e32 v116, v68
	v_mov_b32_e32 v117, v68
	v_mov_b32_e32 v118, v68
	v_mov_b32_e32 v119, v68
	v_mov_b32_e32 v120, v68
	v_mov_b32_e32 v121, v68
	v_mov_b32_e32 v122, v68
	v_mov_b32_e32 v123, v68
	v_mov_b32_e32 v124, v68
	v_mov_b32_e32 v125, v68
	v_mov_b32_e32 v126, v68
	v_mov_b32_e32 v127, v68
	v_mov_b32_e32 v128, v68
	v_mov_b32_e32 v129, v68
	v_mov_b32_e32 v130, v68
	v_mov_b32_e32 v131, v68
	s_branch .LBB0_304

.Lpc_ck1_3:
	ds_read_b128 v[222:225], v251 offset:32768
	ds_read_b128 v[226:229], v251 offset:34816
	ds_read_b128 v[238:241], v251 offset:36864
	ds_read_b128 v[242:245], v251 offset:38912
	ds_read_b128 v[172:175], v250 offset:32768
	ds_read_b128 v[176:179], v250 offset:34816
	ds_read_b128 v[180:183], v250 offset:36864
	ds_read_b128 v[184:187], v250 offset:38912
	ds_read_b128 v[132:135], v250 offset:40960
	ds_read_b128 v[208:211], v250 offset:43008
	v_mfma_f32_16x16x32_bf16 v[80:83], v[246:249], v[148:151], v[80:83]
	v_mfma_f32_16x16x32_bf16 v[76:79], v[230:233], v[148:151], v[76:79]
	v_mfma_f32_16x16x32_bf16 v[72:75], v[144:147], v[148:151], v[72:75]
	v_mfma_f32_16x16x32_bf16 v[68:71], v[160:163], v[148:151], v[68:71]
	v_mfma_f32_16x16x32_bf16 v[4:7], v[246:249], v[152:155], v[4:7]
	v_mfma_f32_16x16x32_bf16 v[8:11], v[230:233], v[152:155], v[8:11]
	v_mfma_f32_16x16x32_bf16 v[12:15], v[144:147], v[152:155], v[12:15]
	v_mfma_f32_16x16x32_bf16 v[16:19], v[160:163], v[152:155], v[16:19]
	ds_read_b128 v[214:217], v250 offset:45056
	ds_read_b128 v[218:221], v250 offset:47104
	ds_read_b128 v[246:249], v137 offset:32768
	ds_read_b128 v[230:233], v137 offset:34816
	ds_read_b128 v[144:147], v137 offset:36864
	s_waitcnt lgkmcnt(14)
	ds_read_b128 v[160:163], v137 offset:38912
	s_waitcnt lgkmcnt(14)
	ds_read_b128 v[164:167], v188 offset:32768
	s_waitcnt lgkmcnt(14)
	ds_read_b128 v[168:171], v188 offset:34816
	s_waitcnt lgkmcnt(14)
	ds_read_b128 v[140:143], v188 offset:36864
	s_waitcnt lgkmcnt(14)
	ds_read_b128 v[148:151], v188 offset:38912
	s_waitcnt lgkmcnt(14)
	ds_read_b128 v[152:155], v188 offset:40960
	v_mfma_f32_16x16x32_bf16 v[128:131], v[222:225], v[172:175], v[128:131]
	v_mfma_f32_16x16x32_bf16 v[124:127], v[226:229], v[172:175], v[124:127]
	v_mfma_f32_16x16x32_bf16 v[120:123], v[238:241], v[172:175], v[120:123]
	v_mfma_f32_16x16x32_bf16 v[116:119], v[242:245], v[172:175], v[116:119]
	s_waitcnt lgkmcnt(14)
	ds_read_b128 v[172:175], v188 offset:43008
	v_mfma_f32_16x16x32_bf16 v[112:115], v[222:225], v[176:179], v[112:115]
	v_mfma_f32_16x16x32_bf16 v[108:111], v[226:229], v[176:179], v[108:111]
	v_mfma_f32_16x16x32_bf16 v[104:107], v[238:241], v[176:179], v[104:107]
	v_mfma_f32_16x16x32_bf16 v[100:103], v[242:245], v[176:179], v[100:103]
	s_waitcnt lgkmcnt(14)
	ds_read_b128 v[176:179], v188 offset:45056
	v_mfma_f32_16x16x32_bf16 v[96:99], v[222:225], v[180:183], v[96:99]
	v_mfma_f32_16x16x32_bf16 v[92:95], v[226:229], v[180:183], v[92:95]
	v_mfma_f32_16x16x32_bf16 v[88:91], v[238:241], v[180:183], v[88:91]
	v_mfma_f32_16x16x32_bf16 v[84:87], v[242:245], v[180:183], v[84:87]
	s_waitcnt lgkmcnt(14)
	ds_read_b128 v[180:183], v188 offset:47104
	v_mfma_f32_16x16x32_bf16 v[80:83], v[222:225], v[184:187], v[80:83]
	v_mfma_f32_16x16x32_bf16 v[76:79], v[226:229], v[184:187], v[76:79]
	v_mfma_f32_16x16x32_bf16 v[72:75], v[238:241], v[184:187], v[72:75]
	v_mfma_f32_16x16x32_bf16 v[68:71], v[242:245], v[184:187], v[68:71]
	v_mfma_f32_16x16x32_bf16 v[4:7], v[222:225], v[132:135], v[4:7]
	v_mfma_f32_16x16x32_bf16 v[8:11], v[226:229], v[132:135], v[8:11]
	v_mfma_f32_16x16x32_bf16 v[12:15], v[238:241], v[132:135], v[12:15]
	v_mfma_f32_16x16x32_bf16 v[16:19], v[242:245], v[132:135], v[16:19]
	s_waitcnt lgkmcnt(0)
	s_barrier
	v_mfma_f32_16x16x32_bf16 v[20:23], v[222:225], v[208:211], v[20:23]
	v_mfma_f32_16x16x32_bf16 v[24:27], v[226:229], v[208:211], v[24:27]
	v_mfma_f32_16x16x32_bf16 v[28:31], v[238:241], v[208:211], v[28:31]
	v_mfma_f32_16x16x32_bf16 v[32:35], v[242:245], v[208:211], v[32:35]
	v_mfma_f32_16x16x32_bf16 v[36:39], v[222:225], v[214:217], v[36:39]
	v_mfma_f32_16x16x32_bf16 v[40:43], v[226:229], v[214:217], v[40:43]
	v_mfma_f32_16x16x32_bf16 v[44:47], v[238:241], v[214:217], v[44:47]
	v_mfma_f32_16x16x32_bf16 v[48:51], v[242:245], v[214:217], v[48:51]
	v_mfma_f32_16x16x32_bf16 v[52:55], v[222:225], v[218:221], v[52:55]
	v_mfma_f32_16x16x32_bf16 v[56:59], v[226:229], v[218:221], v[56:59]
	v_mfma_f32_16x16x32_bf16 v[60:63], v[238:241], v[218:221], v[60:63]
	v_mfma_f32_16x16x32_bf16 v[64:67], v[242:245], v[218:221], v[64:67]
	v_mfma_f32_16x16x32_bf16 v[128:131], v[246:249], v[164:167], v[128:131]
	v_mfma_f32_16x16x32_bf16 v[124:127], v[230:233], v[164:167], v[124:127]
	v_mfma_f32_16x16x32_bf16 v[120:123], v[144:147], v[164:167], v[120:123]
	v_mfma_f32_16x16x32_bf16 v[116:119], v[160:163], v[164:167], v[116:119]
	v_mfma_f32_16x16x32_bf16 v[112:115], v[246:249], v[168:171], v[112:115]
	v_mfma_f32_16x16x32_bf16 v[108:111], v[230:233], v[168:171], v[108:111]
	v_mfma_f32_16x16x32_bf16 v[104:107], v[144:147], v[168:171], v[104:107]
	v_mfma_f32_16x16x32_bf16 v[100:103], v[160:163], v[168:171], v[100:103]
	v_mfma_f32_16x16x32_bf16 v[96:99], v[246:249], v[140:143], v[96:99]
	v_mfma_f32_16x16x32_bf16 v[92:95], v[230:233], v[140:143], v[92:95]
	v_mfma_f32_16x16x32_bf16 v[88:91], v[144:147], v[140:143], v[88:91]
	v_mfma_f32_16x16x32_bf16 v[84:87], v[160:163], v[140:143], v[84:87]
	v_mfma_f32_16x16x32_bf16 v[20:23], v[246:249], v[172:175], v[20:23]
	v_mfma_f32_16x16x32_bf16 v[24:27], v[230:233], v[172:175], v[24:27]
	v_mfma_f32_16x16x32_bf16 v[28:31], v[144:147], v[172:175], v[28:31]
	v_mfma_f32_16x16x32_bf16 v[32:35], v[160:163], v[172:175], v[32:35]
	v_mfma_f32_16x16x32_bf16 v[36:39], v[246:249], v[176:179], v[36:39]
	v_mfma_f32_16x16x32_bf16 v[40:43], v[230:233], v[176:179], v[40:43]
	v_mfma_f32_16x16x32_bf16 v[44:47], v[144:147], v[176:179], v[44:47]
	v_mfma_f32_16x16x32_bf16 v[48:51], v[160:163], v[176:179], v[48:51]
	v_mfma_f32_16x16x32_bf16 v[52:55], v[246:249], v[180:183], v[52:55]
	v_mfma_f32_16x16x32_bf16 v[56:59], v[230:233], v[180:183], v[56:59]
	v_mfma_f32_16x16x32_bf16 v[60:63], v[144:147], v[180:183], v[60:63]
	v_mfma_f32_16x16x32_bf16 v[64:67], v[160:163], v[180:183], v[64:67]
	s_barrier
	s_add_i32 s96, s96, 2
	s_cmp_le_i32 s96, s47
	s_cbranch_scc1 .Lpc_ctop_3
	v_mfma_f32_16x16x32_bf16 v[80:83], v[246:249], v[148:151], v[80:83]
	v_mfma_f32_16x16x32_bf16 v[76:79], v[230:233], v[148:151], v[76:79]
	v_mfma_f32_16x16x32_bf16 v[72:75], v[144:147], v[148:151], v[72:75]
	v_mfma_f32_16x16x32_bf16 v[68:71], v[160:163], v[148:151], v[68:71]
	v_mfma_f32_16x16x32_bf16 v[4:7], v[246:249], v[152:155], v[4:7]
	v_mfma_f32_16x16x32_bf16 v[8:11], v[230:233], v[152:155], v[8:11]
	v_mfma_f32_16x16x32_bf16 v[12:15], v[144:147], v[152:155], v[12:15]
	v_mfma_f32_16x16x32_bf16 v[16:19], v[160:163], v[152:155], v[16:19]
	s_mov_b32 s98, s55
	s_mov_b32 s99, s53
	s_mov_b32 s100, -2
	s_bfe_u32 vcc_lo, s101, 0x10001
	s_lshl_b32 vcc_lo, vcc_lo, 6
	v_add_u32_e32 v194, vcc_lo, v202
	s_branch .LBB0_297
.Lpc_edone_3:
	s_cmp_eq_u32 s100, -2
	s_cbranch_scc0 .Lpc_efin_3
	s_mov_b32 s100, -3
	s_mov_b32 s55, s98
	s_mov_b32 s53, s99
	v_mov_b64_e32 v[128:129], v[4:5]
	v_mov_b64_e32 v[130:131], v[6:7]
	v_mov_b64_e32 v[124:125], v[8:9]
	v_mov_b64_e32 v[126:127], v[10:11]
	v_mov_b64_e32 v[120:121], v[12:13]
	v_mov_b64_e32 v[122:123], v[14:15]
	v_mov_b64_e32 v[116:117], v[16:17]
	v_mov_b64_e32 v[118:119], v[18:19]
	v_mov_b64_e32 v[112:113], v[20:21]
	v_mov_b64_e32 v[114:115], v[22:23]
	v_mov_b64_e32 v[108:109], v[24:25]
	v_mov_b64_e32 v[110:111], v[26:27]
	v_mov_b64_e32 v[104:105], v[28:29]
	v_mov_b64_e32 v[106:107], v[30:31]
	v_mov_b64_e32 v[100:101], v[32:33]
	v_mov_b64_e32 v[102:103], v[34:35]
	v_mov_b64_e32 v[96:97], v[36:37]
	v_mov_b64_e32 v[98:99], v[38:39]
	v_mov_b64_e32 v[92:93], v[40:41]
	v_mov_b64_e32 v[94:95], v[42:43]
	v_mov_b64_e32 v[88:89], v[44:45]
	v_mov_b64_e32 v[90:91], v[46:47]
	v_mov_b64_e32 v[84:85], v[48:49]
	v_mov_b64_e32 v[86:87], v[50:51]
	v_mov_b64_e32 v[80:81], v[52:53]
	v_mov_b64_e32 v[82:83], v[54:55]
	v_mov_b64_e32 v[76:77], v[56:57]
	v_mov_b64_e32 v[78:79], v[58:59]
	v_mov_b64_e32 v[72:73], v[60:61]
	v_mov_b64_e32 v[74:75], v[62:63]
	v_mov_b64_e32 v[68:69], v[64:65]
	v_mov_b64_e32 v[70:71], v[66:67]
	v_add_u32_e32 v194, 0x80, v194
	s_branch .LBB0_297

.Lpc_prod_3:
.Lpc_ptop_3:
	s_cmp_lt_i32 s96, s47
	s_cbranch_scc1 .Lpc_pcur_3
	s_mov_b32 vcc_lo, 0
	s_cmp_lg_u64 s[30:31], 0
	s_cbranch_scc1 .Lpc_pnext_3
	v_readfirstlane_b32 s40, v144
	v_readfirstlane_b32 s41, v145
	v_readfirstlane_b32 s38, v146
	v_readfirstlane_b32 s39, v147
	s_branch .Lpc_pgo_3

.Lpc_pcur_3:
	s_mov_b32 vcc_lo, s96
	v_readfirstlane_b32 s40, v144
	v_readfirstlane_b32 s41, v145
	v_readfirstlane_b32 s38, v146
	v_readfirstlane_b32 s39, v147
.Lpc_pgo_3:
	s_nop 0
	s_sub_u32 s40, s40, s98
	s_subb_u32 s41, s41, 0
	s_sub_u32 s38, s38, s99
	s_subb_u32 s39, s39, 0
	s_bfe_u32 vcc_hi, s101, 0x80008
	s_add_u32 vcc_hi, vcc_hi, vcc_lo
	s_add_u32 m0, s47, -1
	s_and_b32 vcc_hi, vcc_hi, m0
	s_lshl_b32 vcc_hi, vcc_hi, 7
	v_add_u32_e32 v20, vcc_hi, v4
	v_add_u32_e32 v21, vcc_hi, v5
	v_add_u32_e32 v22, vcc_hi, v6
	v_add_u32_e32 v23, vcc_hi, v7
	v_add_u32_e32 v24, vcc_hi, v8
	v_add_u32_e32 v25, vcc_hi, v9
	v_add_u32_e32 v26, vcc_hi, v10
	v_add_u32_e32 v27, vcc_hi, v11
	v_add_u32_e32 v28, vcc_hi, v12
	v_add_u32_e32 v29, vcc_hi, v13
	v_add_u32_e32 v30, vcc_hi, v14
	v_add_u32_e32 v31, vcc_hi, v15
	v_add_u32_e32 v32, vcc_hi, v16
	v_add_u32_e32 v33, vcc_hi, v17
	v_add_u32_e32 v34, vcc_hi, v18
	v_add_u32_e32 v35, vcc_hi, v19
	s_add_u32 vcc_lo, vcc_lo, 1
	s_barrier
	s_add_u32 m0, s100, 0x0
	s_nop 0
	global_load_lds_dwordx4 v20, s[40:41]
	s_add_u32 m0, s100, 0x400
	s_nop 0
	global_load_lds_dwordx4 v21, s[40:41]
	s_add_u32 m0, s100, 0x1000
	s_nop 0
	global_load_lds_dwordx4 v22, s[40:41]
	s_add_u32 m0, s100, 0x1400
	s_nop 0
	global_load_lds_dwordx4 v23, s[40:41]
	s_add_u32 m0, s100, 0x2000
	s_nop 0
	global_load_lds_dwordx4 v24, s[40:41]
	s_add_u32 m0, s100, 0x2400
	s_nop 0
	global_load_lds_dwordx4 v25, s[40:41]
	s_add_u32 m0, s100, 0x3000
	s_nop 0
	global_load_lds_dwordx4 v26, s[40:41]
	s_add_u32 m0, s100, 0x3400
	s_nop 0
	global_load_lds_dwordx4 v27, s[40:41]
	s_waitcnt vmcnt(8)
	s_barrier
	s_add_u32 m0, s100, 0x4000
	s_nop 0
	global_load_lds_dwordx4 v28, s[38:39]
	s_add_u32 m0, s100, 0x4400
	s_nop 0
	global_load_lds_dwordx4 v29, s[38:39]
	s_add_u32 m0, s100, 0x5000
	s_nop 0
	global_load_lds_dwordx4 v30, s[38:39]
	s_add_u32 m0, s100, 0x5400
	s_nop 0
	global_load_lds_dwordx4 v31, s[38:39]
	s_add_u32 m0, s100, 0x6000
	s_nop 0
	global_load_lds_dwordx4 v32, s[38:39]
	s_add_u32 m0, s100, 0x6400
	s_nop 0
	global_load_lds_dwordx4 v33, s[38:39]
	s_add_u32 m0, s100, 0x7000
	s_nop 0
	global_load_lds_dwordx4 v34, s[38:39]
	s_add_u32 m0, s100, 0x7400
	s_nop 0
	global_load_lds_dwordx4 v35, s[38:39]
	s_bfe_u32 vcc_hi, s101, 0x80008
	s_add_u32 vcc_hi, vcc_hi, vcc_lo
	s_add_u32 m0, s47, -1
	s_and_b32 vcc_hi, vcc_hi, m0
	s_lshl_b32 vcc_hi, vcc_hi, 7
	v_add_u32_e32 v20, vcc_hi, v4
	v_add_u32_e32 v21, vcc_hi, v5
	v_add_u32_e32 v22, vcc_hi, v6
	v_add_u32_e32 v23, vcc_hi, v7
	v_add_u32_e32 v24, vcc_hi, v8
	v_add_u32_e32 v25, vcc_hi, v9
	v_add_u32_e32 v26, vcc_hi, v10
	v_add_u32_e32 v27, vcc_hi, v11
	v_add_u32_e32 v28, vcc_hi, v12
	v_add_u32_e32 v29, vcc_hi, v13
	v_add_u32_e32 v30, vcc_hi, v14
	v_add_u32_e32 v31, vcc_hi, v15
	v_add_u32_e32 v32, vcc_hi, v16
	v_add_u32_e32 v33, vcc_hi, v17
	v_add_u32_e32 v34, vcc_hi, v18
	v_add_u32_e32 v35, vcc_hi, v19
	s_add_u32 vcc_lo, vcc_lo, 1
	s_barrier
	s_add_u32 m0, s100, 0x8000
	s_nop 0
	global_load_lds_dwordx4 v20, s[40:41]
	s_add_u32 m0, s100, 0x8400
	s_nop 0
	global_load_lds_dwordx4 v21, s[40:41]
	s_add_u32 m0, s100, 0x9000
	s_nop 0
	global_load_lds_dwordx4 v22, s[40:41]
	s_add_u32 m0, s100, 0x9400
	s_nop 0
	global_load_lds_dwordx4 v23, s[40:41]
	s_add_u32 m0, s100, 0xa000
	s_nop 0
	global_load_lds_dwordx4 v24, s[40:41]
	s_add_u32 m0, s100, 0xa400
	s_nop 0
	global_load_lds_dwordx4 v25, s[40:41]
	s_add_u32 m0, s100, 0xb000
	s_nop 0
	global_load_lds_dwordx4 v26, s[40:41]
	s_add_u32 m0, s100, 0xb400
	s_nop 0
	global_load_lds_dwordx4 v27, s[40:41]
	s_waitcnt vmcnt(8)
	s_barrier
	s_add_u32 m0, s100, 0xc000
	s_nop 0
	global_load_lds_dwordx4 v28, s[38:39]
	s_add_u32 m0, s100, 0xc400
	s_nop 0
	global_load_lds_dwordx4 v29, s[38:39]
	s_add_u32 m0, s100, 0xd000
	s_nop 0
	global_load_lds_dwordx4 v30, s[38:39]
	s_add_u32 m0, s100, 0xd400
	s_nop 0
	global_load_lds_dwordx4 v31, s[38:39]
	s_add_u32 m0, s100, 0xe000
	s_nop 0
	global_load_lds_dwordx4 v32, s[38:39]
	s_add_u32 m0, s100, 0xe400
	s_nop 0
	global_load_lds_dwordx4 v33, s[38:39]
	s_add_u32 m0, s100, 0xf000
	s_nop 0
	global_load_lds_dwordx4 v34, s[38:39]
	s_add_u32 m0, s100, 0xf400
	s_nop 0
	global_load_lds_dwordx4 v35, s[38:39]
	s_add_u32 s34, s34, 0x100
	s_addc_u32 s35, s35, 0
	s_add_i32 s96, s96, 2
	s_cmp_le_i32 s96, s47
	s_cbranch_scc1 .Lpc_ptop_3
	s_mov_b32 s97, s5
	s_movk_i32 s96, 0x43ff
	s_mov_b32 s55, s49
	s_mov_b32 s53, s1
	s_and_b64 vcc, exec, s[26:27]
	v_mov_b64_e32 v[146:147], v[142:143]
	v_mov_b64_e32 v[144:145], v[140:141]
	s_cbranch_vccz .Lpc_pnd_3
	s_waitcnt vmcnt(0)
	s_branch .LBB0_319

.LBB0_319:
	s_nop 0
	v_mov_b32_e32 v68, v194
	s_movk_i32 s0, 0x200
	s_movk_i32 s2, 0x200
	s_movk_i32 s1, 0x200
	s_cmpk_gt_i32 s52, 0x21f
	s_cbranch_scc1 .LBB0_342
	v_readlane_b32 s6, v254, 63
	s_ashr_i32 s47, s1, 6
	v_readlane_b32 s7, v255, 0
	s_and_b64 s[20:21], s[6:7], exec
	s_cselect_b32 s1, 0x80000, 0
	s_add_u32 s24, s74, s1
	s_addc_u32 s25, s75, 0
	s_ashr_i32 s1, s52, 31
	s_lshr_b32 s1, s1, 27
	s_add_i32 s1, s52, s1
	s_ashr_i32 s1, s1, 5
	s_lshl_b32 s20, s52, 7
	v_lshlrev_b32_e32 v0, 3, v68
	v_ashrrev_i32_e32 v3, 3, v68
	s_lshl_b32 s3, s1, 10
	s_and_b32 s20, s20, 0x380
	v_and_b32_e32 v0, 56, v0
	v_lshrrev_b32_e32 v132, 4, v68
	v_xor_b32_e32 v132, v132, v68
	v_and_b32_e32 v132, 7, v132
	v_lshlrev_b32_e32 v0, 3, v132
	v_mov_b32_e32 v1, v2
	s_or_b32 s53, s3, s20
	s_lshl_b32 s1, s1, 9
	s_lshl_b32 s3, s52, 4
	v_mad_i64_i32 v[4:5], s[20:21], s0, v3, v[0:1]
	v_mad_i64_i32 v[0:1], s[20:21], s2, v3, v[0:1]
	s_sub_i32 s1, s3, s1
	s_mul_hi_i32 s21, s0, s53
	s_mul_i32 s20, s0, s53
	s_and_b32 s52, s1, 0xffffff80
	s_ashr_i32 s1, s0, 31
	s_ashr_i32 s3, s2, 31
	s_lshl_b64 s[20:21], s[20:21], 1
	s_add_u32 s20, s82, s20
	s_addc_u32 s21, s83, s21
	v_lshlrev_b64 v[70:71], 1, v[4:5]
	v_lshl_add_u64 v[144:145], s[20:21], 0, v[70:71]
	s_mul_hi_i32 s21, s2, s52
	s_mul_i32 s20, s2, s52
	s_lshl_b64 s[20:21], s[20:21], 1
	s_add_u32 s20, s24, s20
	s_addc_u32 s21, s25, s21
	s_waitcnt vmcnt(0)
	v_lshlrev_b64 v[72:73], 1, v[0:1]
	v_lshl_add_u64 v[146:147], s[20:21], 0, v[72:73]
	s_lshl_b64 s[20:21], s[0:1], 6
	v_lshl_add_u64 v[0:1], v[144:145], 0, s[20:21]
	s_lshl_b64 s[22:23], s[2:3], 6
	s_waitcnt vmcnt(0)
	v_lshl_add_u64 v[36:37], v[0:1], 0, s[20:21]
	s_waitcnt vmcnt(0)
	v_lshl_add_u64 v[56:57], v[146:147], 0, s[22:23]
	v_lshl_add_u64 v[40:41], v[36:37], 0, s[20:21]
	s_waitcnt vmcnt(0)
	v_lshl_add_u64 v[60:61], v[56:57], 0, s[22:23]
	s_waitcnt vmcnt(0)
	v_lshl_add_u64 v[64:65], v[60:61], 0, s[22:23]
	s_bfe_u32 s100, s101, 0x20002
	s_lshl_b32 s100, s100, 10
	s_bfe_u32 vcc_lo, s101, 0x80008
	s_add_u32 vcc_lo, vcc_lo, 0
	s_add_u32 vcc_hi, s47, -1
	s_and_b32 vcc_lo, vcc_lo, vcc_hi
	s_lshl_b32 vcc_lo, vcc_lo, 7
	s_mov_b32 vcc_hi, 0
	v_lshl_add_u64 v[20:21], v[144:145], 0, vcc
	s_add_u32 m0, s100, 0x0
	s_nop 0
	global_load_lds_dwordx4 v[20:21], off
	v_lshl_add_u64 v[20:21], v[0:1], 0, vcc
	s_add_u32 m0, s100, 0x1000
	s_nop 0
	global_load_lds_dwordx4 v[20:21], off
	v_lshl_add_u64 v[20:21], v[36:37], 0, vcc
	s_add_u32 m0, s100, 0x2000
	s_nop 0
	global_load_lds_dwordx4 v[20:21], off
	v_lshl_add_u64 v[20:21], v[40:41], 0, vcc
	s_add_u32 m0, s100, 0x3000
	s_nop 0
	global_load_lds_dwordx4 v[20:21], off
	v_lshl_add_u64 v[20:21], v[146:147], 0, vcc
	s_add_u32 m0, s100, 0x4000
	s_nop 0
	global_load_lds_dwordx4 v[20:21], off
	v_lshl_add_u64 v[20:21], v[56:57], 0, vcc
	s_add_u32 m0, s100, 0x5000
	s_nop 0
	global_load_lds_dwordx4 v[20:21], off
	v_lshl_add_u64 v[20:21], v[60:61], 0, vcc
	s_add_u32 m0, s100, 0x6000
	s_nop 0
	global_load_lds_dwordx4 v[20:21], off
	v_lshl_add_u64 v[20:21], v[64:65], 0, vcc
	s_add_u32 m0, s100, 0x7000
	s_nop 0
	global_load_lds_dwordx4 v[20:21], off
	s_bfe_u32 vcc_lo, s101, 0x80008
	s_add_u32 vcc_lo, vcc_lo, 1
	s_add_u32 vcc_hi, s47, -1
	s_and_b32 vcc_lo, vcc_lo, vcc_hi
	s_lshl_b32 vcc_lo, vcc_lo, 7
	s_mov_b32 vcc_hi, 0
	v_lshl_add_u64 v[20:21], v[144:145], 0, vcc
	s_add_u32 m0, s100, 0x8000
	s_nop 0
	global_load_lds_dwordx4 v[20:21], off
	v_lshl_add_u64 v[20:21], v[0:1], 0, vcc
	s_add_u32 m0, s100, 0x9000
	s_nop 0
	global_load_lds_dwordx4 v[20:21], off
	v_lshl_add_u64 v[20:21], v[36:37], 0, vcc
	s_add_u32 m0, s100, 0xa000
	s_nop 0
	global_load_lds_dwordx4 v[20:21], off
	v_lshl_add_u64 v[20:21], v[40:41], 0, vcc
	s_add_u32 m0, s100, 0xb000
	s_nop 0
	global_load_lds_dwordx4 v[20:21], off
	v_lshl_add_u64 v[20:21], v[146:147], 0, vcc
	s_add_u32 m0, s100, 0xc000
	s_nop 0
	global_load_lds_dwordx4 v[20:21], off
	v_lshl_add_u64 v[20:21], v[56:57], 0, vcc
	s_add_u32 m0, s100, 0xd000
	s_nop 0
	global_load_lds_dwordx4 v[20:21], off
	v_lshl_add_u64 v[20:21], v[60:61], 0, vcc
	s_add_u32 m0, s100, 0xe000
	s_nop 0
	global_load_lds_dwordx4 v[20:21], off
	v_lshl_add_u64 v[20:21], v[64:65], 0, vcc
	s_add_u32 m0, s100, 0xf000
	s_nop 0
	global_load_lds_dwordx4 v[20:21], off
	v_lshrrev_b32_e32 v1, 1, v3
	v_xor_b32_e32 v1, v1, v68
	v_lshlrev_b32_e32 v0, 7, v3
	v_lshlrev_b32_e32 v1, 4, v1
	s_movk_i32 s1, 0x70
	v_lshrrev_b32_e32 v69, 4, v68
	v_bfe_u32 v74, v68, 4, 2
	v_and_or_b32 v3, v1, s1, v0
	v_lshl_add_u64 v[0:1], s[82:83], 0, v[70:71]
	v_bfe_u32 v70, v68, 1, 3
	v_bitop3_b32 v69, v69, v70, 3 bitop3:0x6c
	v_lshlrev_b32_e32 v71, 6, v68
	v_lshlrev_b32_e32 v68, 7, v68
	v_bitop3_b32 v70, v74, v70, 4 bitop3:0x36
	v_lshl_add_u64 v[138:139], s[24:25], 0, v[72:73]
	v_lshlrev_b32_e32 v69, 4, v69
	v_and_b32_e32 v71, 0xffffe000, v71
	v_and_b32_e32 v72, 0x780, v68
	v_and_b32_e32 v68, 0x2000, v68
	v_lshlrev_b32_e32 v70, 4, v70
	s_cmp_gt_i32 s47, 0
	v_or_b32_e32 v73, v69, v71
	v_or_b32_e32 v69, v69, v68
	v_or_b32_e32 v71, v70, v71
	v_or_b32_e32 v68, v70, v68
	s_mov_b32 s49, 0
	s_cselect_b64 s[24:25], -1, 0
	v_add_u32_e32 v137, v73, v72
	v_add_u32_e32 v188, v69, v72
	v_add_u32_e32 v189, v71, v72
	v_add_u32_e32 v190, v68, v72
	s_mov_b32 s1, 0
	s_mov_b32 s3, 0
	s_bfe_u32 vcc_lo, s101, 0x10001
	v_and_b32_e32 v20, 15, v194
	v_lshrrev_b32_e32 v21, 1, v20
	v_bfe_u32 v22, v194, 4, 2
	v_xor_b32_e32 v21, v21, v22
	v_lshlrev_b32_e32 v21, 4, v21
	v_lshl_or_b32 v250, v20, 7, v21
	v_mov_b32_e32 v22, vcc_lo
	v_lshl_or_b32 v22, v22, 13, v250
	v_or_b32_e32 v251, 0x4000, v22
	v_and_b32_e32 v20, 63, v194
	v_mov_b32_e32 v21, vcc_lo
	v_lshlrev_b32_e32 v21, 4, v21
	v_lshrrev_b32_e32 v22, 3, v20
	v_add_u32_e32 v21, v21, v22
	v_lshrrev_b32_e32 v22, 4, v20
	v_and_b32_e32 v23, 7, v20
	v_xor_b32_e32 v24, v23, v22
	v_lshlrev_b32_e32 v24, 4, v24
	v_or_b32_e32 v22, 4, v22
	v_xor_b32_e32 v25, v23, v22
	v_lshlrev_b32_e32 v25, 4, v25
	s_lshl_b32 s98, s0, 1
	s_lshl_b32 s99, s2, 1
	v_add_u32_e32 v26, 0, v21
	v_mad_u32_u24 v4, v26, s98, v24
	v_add_u32_e32 v26, 8, v21
	v_mad_u32_u24 v5, v26, s98, v25
	v_add_u32_e32 v26, 32, v21
	v_mad_u32_u24 v6, v26, s98, v24
	v_add_u32_e32 v26, 40, v21
	v_mad_u32_u24 v7, v26, s98, v25
	v_add_u32_e32 v26, 64, v21
	v_mad_u32_u24 v8, v26, s98, v24
	v_add_u32_e32 v26, 72, v21
	v_mad_u32_u24 v9, v26, s98, v25
	v_add_u32_e32 v26, 96, v21
	v_mad_u32_u24 v10, v26, s98, v24
	v_add_u32_e32 v26, 104, v21
	v_mad_u32_u24 v11, v26, s98, v25
	v_add_u32_e32 v26, 0, v21
	v_mad_u32_u24 v12, v26, s99, v24
	v_add_u32_e32 v26, 8, v21
	v_mad_u32_u24 v13, v26, s99, v25
	v_add_u32_e32 v26, 32, v21
	v_mad_u32_u24 v14, v26, s99, v24
	v_add_u32_e32 v26, 40, v21
	v_mad_u32_u24 v15, v26, s99, v25
	v_add_u32_e32 v26, 64, v21
	v_mad_u32_u24 v16, v26, s99, v24
	v_add_u32_e32 v26, 72, v21
	v_mad_u32_u24 v17, v26, s99, v25
	v_add_u32_e32 v26, 96, v21
	v_mad_u32_u24 v18, v26, s99, v24
	v_add_u32_e32 v26, 104, v21
	v_mad_u32_u24 v19, v26, s99, v25
	s_bfe_u32 vcc_hi, s101, 0x20002
	s_lshl_b32 vcc_hi, vcc_hi, 3
	s_mul_i32 s98, s98, vcc_hi
	s_mul_i32 s99, s99, vcc_hi
	s_lshl_b32 vcc_hi, vcc_hi, 3
	s_and_b32 vcc_hi, vcc_hi, 0x70
	s_add_u32 s98, s98, vcc_hi
	s_add_u32 s99, s99, vcc_hi
	s_lshl_b32 s100, vcc_lo, 11
	s_bitcmp1_b32 s101, 0
	s_cselect_b32 s100, -1, s100
	s_waitcnt vmcnt(0) lgkmcnt(0)
	s_barrier
	s_branch .LBB0_323

.LBB0_322:
	v_mov_b32_e32 v152, v194
	v_mov_b32_e32 v132, v194
	v_mul_f32_e32 v157, 0xbfb8aa3b, v124
	v_and_b32_e32 v133, 64, v132
	v_ashrrev_i32_e32 v132, 1, v132
	v_and_b32_e32 v134, 15, v152
	v_and_b32_e32 v132, 0xffffffc0, v132
	v_lshrrev_b32_e32 v153, 2, v152
	v_add3_u32 v144, v134, s53, v132
	v_and_b32_e32 v132, 12, v153
	v_add_u32_e32 v154, s52, v133
	v_add_u32_e32 v132, v154, v132
	v_ashrrev_i32_e32 v145, 31, v144
	v_lshlrev_b64 v[134:135], 10, v[144:145]
	v_ashrrev_i32_e32 v133, 31, v132
	v_lshl_add_u64 v[134:135], s[82:83], 0, v[134:135]
	v_lshlrev_b64 v[146:147], 1, v[132:133]
	v_lshl_add_u64 v[132:133], v[134:135], 0, v[146:147]
	global_load_dwordx2 v[134:135], v[132:133], off
	global_load_dwordx2 v[148:149], v[132:133], off offset:32
	global_load_dwordx2 v[150:151], v[132:133], off offset:64
	v_mul_f32_e32 v158, 0xbfb8aa3b, v125
	global_load_dwordx2 v[124:125], v[132:133], off offset:96
	v_exp_f32_e32 v132, v157
	v_exp_f32_e32 v133, v158
	v_and_b32_e32 v156, 64, v202
	v_mul_f32_e32 v128, 0xbfb8aa3b, v128
	v_mul_f32_e32 v129, 0xbfb8aa3b, v129
	v_mul_f32_e32 v131, 0xbfb8aa3b, v131
	v_mul_f32_e32 v120, 0xbfb8aa3b, v120
	v_mul_f32_e32 v122, 0xbfb8aa3b, v122
	v_and_b32_e32 v162, 16, v152
	v_xor_b32_e32 v155, 16, v202
	v_mul_f32_e32 v126, 0xbfb8aa3b, v126
	v_mul_f32_e32 v130, 0xbfb8aa3b, v130
	v_mul_f32_e32 v160, 0xbfb8aa3b, v123
	v_add_u32_e32 v123, 64, v156
	v_exp_f32_e32 v128, v128
	v_exp_f32_e32 v129, v129
	v_exp_f32_e32 v131, v131
	v_exp_f32_e32 v157, v120
	v_exp_f32_e32 v161, v122
	v_and_or_b32 v122, v153, 8, v162
	v_mul_f32_e32 v127, 0xbfb8aa3b, v127
	v_exp_f32_e32 v156, v126
	v_exp_f32_e32 v130, v130
	v_cmp_lt_i32_e32 vcc, v155, v123
	v_add_u32_e32 v126, v122, v154
	v_add_f32_e32 v122, 1.0, v132
	v_add_f32_e32 v123, 1.0, v133
	v_exp_f32_e32 v127, v127
	v_rcp_f32_e32 v122, v122
	v_rcp_f32_e32 v123, v123
	v_mul_f32_e32 v121, 0xbfb8aa3b, v121
	v_cndmask_b32_e32 v120, v202, v155, vcc
	v_add_f32_e32 v133, 1.0, v128
	v_add_f32_e32 v152, 1.0, v129
	v_add_f32_e32 v154, 1.0, v131
	v_add_f32_e32 v155, 1.0, v157
	v_exp_f32_e32 v121, v121
	v_add_f32_e32 v153, 1.0, v130
	v_rcp_f32_e32 v130, v133
	v_rcp_f32_e32 v131, v152
	v_rcp_f32_e32 v133, v154
	v_rcp_f32_e32 v152, v155
	v_add_f32_e32 v127, 1.0, v127
	v_rcp_f32_e32 v129, v127
	v_add_f32_e32 v132, 1.0, v156
	v_add_f32_e32 v121, 1.0, v121
	v_rcp_f32_e32 v128, v132
	v_rcp_f32_e32 v132, v153
	v_rcp_f32_e32 v153, v121
	v_add_f32_e32 v121, 1.0, v161
	v_mul_f32_e32 v116, 0xbfb8aa3b, v116
	v_mul_f32_e32 v117, 0xbfb8aa3b, v117
	v_mul_f32_e32 v118, 0xbfb8aa3b, v118
	v_mul_f32_e32 v119, 0xbfb8aa3b, v119
	v_exp_f32_e32 v118, v118
	v_exp_f32_e32 v119, v119
	v_cmp_eq_u32_e32 vcc, 0, v162
	v_lshlrev_b32_e32 v120, 2, v120
	v_add_f32_e32 v118, 1.0, v118
	v_add_f32_e32 v119, 1.0, v119
	v_rcp_f32_e32 v118, v118
	v_rcp_f32_e32 v119, v119
	v_mul_f32_e32 v112, 0xbfb8aa3b, v112
	v_mul_f32_e32 v113, 0xbfb8aa3b, v113
	v_exp_f32_e32 v112, v112
	v_exp_f32_e32 v113, v113
	v_mul_f32_e32 v108, 0xbfb8aa3b, v108
	v_mul_f32_e32 v109, 0xbfb8aa3b, v109
	v_add_f32_e32 v112, 1.0, v112
	v_add_f32_e32 v113, 1.0, v113
	v_rcp_f32_e32 v112, v112
	v_rcp_f32_e32 v113, v113
	v_mul_f32_e32 v110, 0xbfb8aa3b, v110
	v_mul_f32_e32 v111, 0xbfb8aa3b, v111
	v_exp_f32_e32 v110, v110
	s_waitcnt vmcnt(3)
	v_lshlrev_b32_e32 v154, 16, v134
	v_and_b32_e32 v155, 0xffff0000, v134
	v_pk_mul_f32 v[122:123], v[122:123], v[154:155]
	s_waitcnt vmcnt(2)
	v_lshlrev_b32_e32 v156, 16, v148
	v_cvt_pk_bf16_f32 v127, v122, v123
	v_exp_f32_e32 v123, v160
	v_rcp_f32_e32 v122, v121
	v_and_b32_e32 v157, 0xffff0000, v148
	v_lshlrev_b32_e32 v134, 16, v135
	v_add_f32_e32 v121, 1.0, v123
	v_rcp_f32_e32 v123, v121
	v_and_b32_e32 v135, 0xffff0000, v135
	v_pk_mul_f32 v[130:131], v[130:131], v[156:157]
	s_waitcnt vmcnt(1)
	v_lshlrev_b32_e32 v158, 16, v150
	v_and_b32_e32 v159, 0xffff0000, v150
	v_pk_mul_f32 v[128:129], v[128:129], v[134:135]
	v_cvt_pk_bf16_f32 v135, v130, v131
	v_lshlrev_b32_e32 v130, 16, v151
	v_and_b32_e32 v131, 0xffff0000, v151
	v_cvt_pk_bf16_f32 v134, v128, v129
	v_pk_mul_f32 v[128:129], v[152:153], v[158:159]
	v_pk_mul_f32 v[122:123], v[122:123], v[130:131]
	v_cvt_pk_bf16_f32 v121, v128, v129
	v_cvt_pk_bf16_f32 v128, v122, v123
	v_exp_f32_e32 v122, v116
	v_exp_f32_e32 v123, v117
	v_lshlrev_b32_e32 v148, 16, v149
	v_and_b32_e32 v149, 0xffff0000, v149
	v_add_f32_e32 v117, 1.0, v122
	v_add_f32_e32 v123, 1.0, v123
	v_rcp_f32_e32 v122, v117
	v_rcp_f32_e32 v123, v123
	v_pk_mul_f32 v[132:133], v[132:133], v[148:149]
	s_waitcnt vmcnt(0)
	v_lshlrev_b32_e32 v116, 16, v124
	v_and_b32_e32 v117, 0xffff0000, v124
	v_cvt_pk_bf16_f32 v132, v132, v133
	v_pk_mul_f32 v[116:117], v[122:123], v[116:117]
	v_lshlrev_b32_e32 v122, 16, v125
	v_cvt_pk_bf16_f32 v129, v116, v117
	v_cndmask_b32_e32 v117, v134, v132, vcc
	v_and_b32_e32 v123, 0xffff0000, v125
	ds_bpermute_b32 v125, v120, v117
	v_cndmask_b32_e32 v116, v127, v135, vcc
	v_pk_mul_f32 v[118:119], v[118:119], v[122:123]
	ds_bpermute_b32 v124, v120, v116
	v_cvt_pk_bf16_f32 v130, v118, v119
	v_lshlrev_b64 v[116:117], 12, v[144:145]
	v_lshl_add_u64 v[118:119], s[80:81], 0, v[116:117]
	v_cndmask_b32_e32 v116, v121, v129, vcc
	v_cndmask_b32_e32 v117, v128, v130, vcc
	s_waitcnt lgkmcnt(1)
	v_cndmask_b32_e32 v123, v125, v134, vcc
	v_cndmask_b32_e32 v125, v132, v125, vcc
	ds_bpermute_b32 v131, v120, v116
	ds_bpermute_b32 v132, v120, v117
	s_waitcnt lgkmcnt(2)
	v_cndmask_b32_e32 v122, v124, v127, vcc
	v_ashrrev_i32_e32 v127, 31, v126
	v_lshlrev_b64 v[116:117], 1, v[126:127]
	v_cndmask_b32_e32 v124, v135, v124, vcc
	v_lshl_add_u64 v[118:119], v[118:119], 0, v[116:117]
	global_store_dwordx4 v[118:119], v[122:125], off offset:3072
	v_exp_f32_e32 v111, v111
	v_add_f32_e32 v110, 1.0, v110
	s_waitcnt lgkmcnt(1)
	v_cndmask_b32_e32 v122, v131, v121, vcc
	s_waitcnt lgkmcnt(0)
	v_cndmask_b32_e32 v123, v132, v128, vcc
	v_cndmask_b32_e32 v124, v129, v131, vcc
	v_cndmask_b32_e32 v125, v130, v132, vcc
	global_store_dwordx4 v[118:119], v[122:125], off offset:3136
	v_add_u32_e32 v118, 16, v144
	v_ashrrev_i32_e32 v119, 31, v118
	v_lshlrev_b64 v[122:123], 10, v[118:119]
	v_lshl_add_u64 v[122:123], s[82:83], 0, v[122:123]
	v_lshl_add_u64 v[122:123], v[122:123], 0, v[146:147]
	global_load_dwordx2 v[124:125], v[122:123], off
	global_load_dwordx2 v[126:127], v[122:123], off offset:32
	global_load_dwordx2 v[128:129], v[122:123], off offset:64
	s_nop 0
	global_load_dwordx2 v[122:123], v[122:123], off offset:96
	v_add_f32_e32 v111, 1.0, v111
	v_rcp_f32_e32 v110, v110
	v_rcp_f32_e32 v111, v111
	v_mul_f32_e32 v104, 0xbfb8aa3b, v104
	v_mul_f32_e32 v105, 0xbfb8aa3b, v105
	v_mul_f32_e32 v106, 0xbfb8aa3b, v106
	v_mul_f32_e32 v107, 0xbfb8aa3b, v107
	v_exp_f32_e32 v106, v106
	v_exp_f32_e32 v107, v107
	v_mul_f32_e32 v100, 0xbfb8aa3b, v100
	v_mul_f32_e32 v101, 0xbfb8aa3b, v101
	v_add_f32_e32 v106, 1.0, v106
	v_add_f32_e32 v107, 1.0, v107
	v_rcp_f32_e32 v106, v106
	v_rcp_f32_e32 v107, v107
	v_mul_f32_e32 v114, 0xbfb8aa3b, v114
	v_mul_f32_e32 v115, 0xbfb8aa3b, v115
	v_exp_f32_e32 v114, v114
	v_exp_f32_e32 v115, v115
	v_mul_f32_e32 v102, 0xbfb8aa3b, v102
	v_mul_f32_e32 v103, 0xbfb8aa3b, v103
	v_exp_f32_e32 v102, v102
	v_exp_f32_e32 v103, v103
	v_add_f32_e32 v114, 1.0, v114
	v_add_f32_e32 v115, 1.0, v115
	v_rcp_f32_e32 v114, v114
	v_rcp_f32_e32 v115, v115
	v_add_f32_e32 v102, 1.0, v102
	v_add_f32_e32 v103, 1.0, v103
	v_rcp_f32_e32 v102, v102
	v_rcp_f32_e32 v103, v103
	v_mul_f32_e32 v96, 0xbfb8aa3b, v96
	v_mul_f32_e32 v97, 0xbfb8aa3b, v97
	v_mul_f32_e32 v98, 0xbfb8aa3b, v98
	v_mul_f32_e32 v99, 0xbfb8aa3b, v99
	v_exp_f32_e32 v98, v98
	v_exp_f32_e32 v99, v99
	v_mul_f32_e32 v92, 0xbfb8aa3b, v92
	v_mul_f32_e32 v93, 0xbfb8aa3b, v93
	v_add_f32_e32 v98, 1.0, v98
	v_add_f32_e32 v99, 1.0, v99
	v_rcp_f32_e32 v98, v98
	v_rcp_f32_e32 v99, v99
	v_mul_f32_e32 v94, 0xbfb8aa3b, v94
	v_mul_f32_e32 v95, 0xbfb8aa3b, v95
	v_exp_f32_e32 v94, v94
	v_exp_f32_e32 v95, v95
	v_mul_f32_e32 v88, 0xbfb8aa3b, v88
	v_mul_f32_e32 v89, 0xbfb8aa3b, v89
	v_add_f32_e32 v94, 1.0, v94
	v_add_f32_e32 v95, 1.0, v95
	v_rcp_f32_e32 v94, v94
	v_rcp_f32_e32 v95, v95
	v_mul_f32_e32 v90, 0xbfb8aa3b, v90
	v_mul_f32_e32 v91, 0xbfb8aa3b, v91
	v_exp_f32_e32 v90, v90
	v_exp_f32_e32 v91, v91
	v_mul_f32_e32 v84, 0xbfb8aa3b, v84
	v_mul_f32_e32 v85, 0xbfb8aa3b, v85
	v_add_f32_e32 v90, 1.0, v90
	v_add_f32_e32 v91, 1.0, v91
	v_rcp_f32_e32 v90, v90
	v_rcp_f32_e32 v91, v91
	v_mul_f32_e32 v86, 0xbfb8aa3b, v86
	v_mul_f32_e32 v87, 0xbfb8aa3b, v87
	v_exp_f32_e32 v86, v86
	v_exp_f32_e32 v87, v87
	v_mul_f32_e32 v80, 0xbfb8aa3b, v80
	v_mul_f32_e32 v81, 0xbfb8aa3b, v81
	v_add_f32_e32 v86, 1.0, v86
	v_add_f32_e32 v87, 1.0, v87
	v_rcp_f32_e32 v86, v86
	v_rcp_f32_e32 v87, v87
	v_mul_f32_e32 v82, 0xbfb8aa3b, v82
	v_mul_f32_e32 v83, 0xbfb8aa3b, v83
	v_exp_f32_e32 v82, v82
	s_waitcnt vmcnt(3)
	v_lshlrev_b32_e32 v130, 16, v124
	v_and_b32_e32 v131, 0xffff0000, v124
	v_pk_mul_f32 v[112:113], v[112:113], v[130:131]
	v_lshlrev_b32_e32 v124, 16, v125
	v_cvt_pk_bf16_f32 v121, v112, v113
	v_exp_f32_e32 v112, v108
	v_exp_f32_e32 v113, v109
	s_waitcnt vmcnt(2)
	v_lshlrev_b32_e32 v108, 16, v126
	v_and_b32_e32 v125, 0xffff0000, v125
	v_add_f32_e32 v109, 1.0, v112
	v_add_f32_e32 v113, 1.0, v113
	v_rcp_f32_e32 v112, v109
	v_rcp_f32_e32 v113, v113
	v_and_b32_e32 v109, 0xffff0000, v126
	v_pk_mul_f32 v[114:115], v[114:115], v[124:125]
	v_exp_f32_e32 v83, v83
	v_pk_mul_f32 v[108:109], v[112:113], v[108:109]
	v_lshlrev_b32_e32 v112, 16, v127
	v_and_b32_e32 v113, 0xffff0000, v127
	v_pk_mul_f32 v[110:111], v[110:111], v[112:113]
	v_cvt_pk_bf16_f32 v112, v108, v109
	v_exp_f32_e32 v108, v104
	v_exp_f32_e32 v109, v105
	s_waitcnt vmcnt(1)
	v_lshlrev_b32_e32 v104, 16, v128
	v_cvt_pk_bf16_f32 v114, v114, v115
	v_add_f32_e32 v105, 1.0, v108
	v_add_f32_e32 v109, 1.0, v109
	v_rcp_f32_e32 v108, v105
	v_rcp_f32_e32 v109, v109
	v_and_b32_e32 v105, 0xffff0000, v128
	v_cvt_pk_bf16_f32 v110, v110, v111
	v_add_f32_e32 v82, 1.0, v82
	v_pk_mul_f32 v[104:105], v[108:109], v[104:105]
	v_lshlrev_b32_e32 v108, 16, v129
	v_and_b32_e32 v109, 0xffff0000, v129
	v_pk_mul_f32 v[106:107], v[106:107], v[108:109]
	v_cvt_pk_bf16_f32 v108, v104, v105
	v_exp_f32_e32 v104, v100
	v_exp_f32_e32 v105, v101
	s_waitcnt vmcnt(0)
	v_lshlrev_b32_e32 v100, 16, v122
	v_cvt_pk_bf16_f32 v106, v106, v107
	v_add_f32_e32 v101, 1.0, v104
	v_add_f32_e32 v105, 1.0, v105
	v_rcp_f32_e32 v104, v101
	v_rcp_f32_e32 v105, v105
	v_and_b32_e32 v101, 0xffff0000, v122
	v_add_f32_e32 v83, 1.0, v83
	v_rcp_f32_e32 v82, v82
	v_pk_mul_f32 v[100:101], v[104:105], v[100:101]
	v_lshlrev_b32_e32 v104, 16, v123
	v_cvt_pk_bf16_f32 v107, v100, v101
	v_cndmask_b32_e32 v100, v121, v112, vcc
	ds_bpermute_b32 v109, v120, v100
	v_and_b32_e32 v105, 0xffff0000, v123
	v_pk_mul_f32 v[102:103], v[102:103], v[104:105]
	v_cndmask_b32_e32 v101, v114, v110, vcc
	ds_bpermute_b32 v111, v120, v101
	v_cvt_pk_bf16_f32 v113, v102, v103
	v_lshlrev_b64 v[100:101], 12, v[118:119]
	v_lshl_add_u64 v[104:105], s[80:81], 0, v[100:101]
	s_waitcnt lgkmcnt(1)
	v_cndmask_b32_e32 v100, v109, v121, vcc
	v_cndmask_b32_e32 v102, v112, v109, vcc
	v_cndmask_b32_e32 v103, v108, v107, vcc
	v_cndmask_b32_e32 v109, v106, v113, vcc
	ds_bpermute_b32 v112, v120, v103
	ds_bpermute_b32 v109, v120, v109
	s_waitcnt lgkmcnt(2)
	v_cndmask_b32_e32 v101, v111, v114, vcc
	v_cndmask_b32_e32 v103, v110, v111, vcc
	v_lshl_add_u64 v[104:105], v[104:105], 0, v[116:117]
	global_store_dwordx4 v[104:105], v[100:103], off offset:3072
	v_exp_f32_e32 v110, v96
	v_exp_f32_e32 v111, v97
	s_waitcnt lgkmcnt(1)
	v_cndmask_b32_e32 v100, v112, v108, vcc
	s_waitcnt lgkmcnt(0)
	v_cndmask_b32_e32 v101, v109, v106, vcc
	v_cndmask_b32_e32 v102, v107, v112, vcc
	v_cndmask_b32_e32 v103, v113, v109, vcc
	global_store_dwordx4 v[104:105], v[100:103], off offset:3136
	v_add_f32_e32 v97, 1.0, v110
	v_rcp_f32_e32 v110, v97
	v_add_u32_e32 v100, 32, v144
	v_ashrrev_i32_e32 v101, 31, v100
	v_lshlrev_b64 v[102:103], 10, v[100:101]
	v_lshl_add_u64 v[102:103], s[82:83], 0, v[102:103]
	v_lshl_add_u64 v[102:103], v[102:103], 0, v[146:147]
	global_load_dwordx2 v[104:105], v[102:103], off
	global_load_dwordx2 v[106:107], v[102:103], off offset:32
	global_load_dwordx2 v[108:109], v[102:103], off offset:64
	s_nop 0
	global_load_dwordx2 v[102:103], v[102:103], off offset:96
	v_rcp_f32_e32 v83, v83
	v_mul_f32_e32 v76, 0xbfb8aa3b, v76
	v_mul_f32_e32 v77, 0xbfb8aa3b, v77
	v_mul_f32_e32 v78, 0xbfb8aa3b, v78
	v_mul_f32_e32 v79, 0xbfb8aa3b, v79
	v_exp_f32_e32 v78, v78
	v_exp_f32_e32 v79, v79
	v_mul_f32_e32 v72, 0xbfb8aa3b, v72
	v_mul_f32_e32 v73, 0xbfb8aa3b, v73
	v_add_f32_e32 v78, 1.0, v78
	v_add_f32_e32 v79, 1.0, v79
	v_rcp_f32_e32 v78, v78
	v_rcp_f32_e32 v79, v79
	v_mul_f32_e32 v74, 0xbfb8aa3b, v74
	v_mul_f32_e32 v75, 0xbfb8aa3b, v75
	v_exp_f32_e32 v74, v74
	v_exp_f32_e32 v75, v75
	v_mul_f32_e32 v68, 0xbfb8aa3b, v68
	v_mul_f32_e32 v69, 0xbfb8aa3b, v69
	v_add_f32_e32 v74, 1.0, v74
	v_add_f32_e32 v75, 1.0, v75
	v_rcp_f32_e32 v74, v74
	v_rcp_f32_e32 v75, v75
	v_mul_f32_e32 v70, 0xbfb8aa3b, v70
	v_mul_f32_e32 v71, 0xbfb8aa3b, v71
	v_exp_f32_e32 v70, v70
	v_exp_f32_e32 v71, v71
	s_mov_b32 s53, s49
	s_mov_b32 s52, s1
	v_add_f32_e32 v70, 1.0, v70
	v_add_f32_e32 v71, 1.0, v71
	v_rcp_f32_e32 v70, v70
	v_rcp_f32_e32 v71, v71
	s_waitcnt vmcnt(3)
	v_lshlrev_b32_e32 v96, 16, v104
	v_and_b32_e32 v97, 0xffff0000, v104
	v_add_f32_e32 v104, 1.0, v111
	v_rcp_f32_e32 v111, v104
	v_lshlrev_b32_e32 v104, 16, v105
	v_and_b32_e32 v105, 0xffff0000, v105
	v_pk_mul_f32 v[98:99], v[98:99], v[104:105]
	v_pk_mul_f32 v[96:97], v[110:111], v[96:97]
	v_cvt_pk_bf16_f32 v98, v98, v99
	v_cvt_pk_bf16_f32 v104, v96, v97
	v_exp_f32_e32 v96, v92
	v_exp_f32_e32 v97, v93
	s_waitcnt vmcnt(2)
	v_lshlrev_b32_e32 v92, 16, v106
	v_add_f32_e32 v93, 1.0, v96
	v_add_f32_e32 v97, 1.0, v97
	v_rcp_f32_e32 v96, v93
	v_rcp_f32_e32 v97, v97
	v_and_b32_e32 v93, 0xffff0000, v106
	v_pk_mul_f32 v[92:93], v[96:97], v[92:93]
	v_lshlrev_b32_e32 v96, 16, v107
	v_and_b32_e32 v97, 0xffff0000, v107
	v_pk_mul_f32 v[94:95], v[94:95], v[96:97]
	v_cvt_pk_bf16_f32 v96, v92, v93
	v_exp_f32_e32 v92, v88
	v_exp_f32_e32 v93, v89
	s_waitcnt vmcnt(1)
	v_lshlrev_b32_e32 v88, 16, v108
	v_cvt_pk_bf16_f32 v94, v94, v95
	v_add_f32_e32 v89, 1.0, v92
	v_add_f32_e32 v93, 1.0, v93
	v_rcp_f32_e32 v92, v89
	v_rcp_f32_e32 v93, v93
	v_and_b32_e32 v89, 0xffff0000, v108
	v_pk_mul_f32 v[88:89], v[92:93], v[88:89]
	v_lshlrev_b32_e32 v92, 16, v109
	v_and_b32_e32 v93, 0xffff0000, v109
	v_pk_mul_f32 v[90:91], v[90:91], v[92:93]
	v_cvt_pk_bf16_f32 v92, v88, v89
	v_exp_f32_e32 v88, v84
	v_exp_f32_e32 v89, v85
	s_waitcnt vmcnt(0)
	v_lshlrev_b32_e32 v84, 16, v102
	v_cvt_pk_bf16_f32 v90, v90, v91
	v_add_f32_e32 v85, 1.0, v88
	v_add_f32_e32 v89, 1.0, v89
	v_rcp_f32_e32 v88, v85
	v_rcp_f32_e32 v89, v89
	v_and_b32_e32 v85, 0xffff0000, v102
	v_pk_mul_f32 v[84:85], v[88:89], v[84:85]
	s_nop 0
	v_cvt_pk_bf16_f32 v91, v84, v85
	v_cndmask_b32_e32 v84, v104, v96, vcc
	ds_bpermute_b32 v93, v120, v84
	v_lshlrev_b32_e32 v88, 16, v103
	v_and_b32_e32 v89, 0xffff0000, v103
	v_pk_mul_f32 v[86:87], v[86:87], v[88:89]
	v_cndmask_b32_e32 v85, v98, v94, vcc
	ds_bpermute_b32 v95, v120, v85
	v_cvt_pk_bf16_f32 v97, v86, v87
	v_lshlrev_b64 v[84:85], 12, v[100:101]
	v_lshl_add_u64 v[88:89], s[80:81], 0, v[84:85]
	s_waitcnt lgkmcnt(1)
	v_cndmask_b32_e32 v84, v93, v104, vcc
	v_cndmask_b32_e32 v86, v96, v93, vcc
	v_cndmask_b32_e32 v87, v92, v91, vcc
	v_cndmask_b32_e32 v93, v90, v97, vcc
	ds_bpermute_b32 v96, v120, v87
	ds_bpermute_b32 v93, v120, v93
	s_waitcnt lgkmcnt(2)
	v_cndmask_b32_e32 v85, v95, v98, vcc
	v_cndmask_b32_e32 v87, v94, v95, vcc
	v_lshl_add_u64 v[88:89], v[88:89], 0, v[116:117]
	global_store_dwordx4 v[88:89], v[84:87], off offset:3072
	v_exp_f32_e32 v94, v80
	v_exp_f32_e32 v95, v81
	s_waitcnt lgkmcnt(1)
	v_cndmask_b32_e32 v84, v96, v92, vcc
	s_waitcnt lgkmcnt(0)
	v_cndmask_b32_e32 v85, v93, v90, vcc
	v_cndmask_b32_e32 v86, v91, v96, vcc
	v_cndmask_b32_e32 v87, v97, v93, vcc
	global_store_dwordx4 v[88:89], v[84:87], off offset:3136
	v_add_f32_e32 v81, 1.0, v94
	v_rcp_f32_e32 v94, v81
	v_add_u32_e32 v84, 48, v144
	v_ashrrev_i32_e32 v85, 31, v84
	v_lshlrev_b64 v[86:87], 10, v[84:85]
	v_lshl_add_u64 v[86:87], s[82:83], 0, v[86:87]
	v_lshl_add_u64 v[86:87], v[86:87], 0, v[146:147]
	global_load_dwordx2 v[88:89], v[86:87], off
	global_load_dwordx2 v[90:91], v[86:87], off offset:32
	global_load_dwordx2 v[92:93], v[86:87], off offset:64
	s_nop 0
	global_load_dwordx2 v[86:87], v[86:87], off offset:96
	v_mov_b64_e32 v[146:147], v[142:143]
	v_mov_b64_e32 v[144:145], v[140:141]
	s_waitcnt vmcnt(3)
	v_lshlrev_b32_e32 v80, 16, v88
	v_and_b32_e32 v81, 0xffff0000, v88
	v_add_f32_e32 v88, 1.0, v95
	v_rcp_f32_e32 v95, v88
	v_lshlrev_b32_e32 v88, 16, v89
	v_and_b32_e32 v89, 0xffff0000, v89
	v_pk_mul_f32 v[82:83], v[82:83], v[88:89]
	v_pk_mul_f32 v[80:81], v[94:95], v[80:81]
	v_cvt_pk_bf16_f32 v82, v82, v83
	v_cvt_pk_bf16_f32 v88, v80, v81
	v_exp_f32_e32 v80, v76
	v_exp_f32_e32 v81, v77
	s_waitcnt vmcnt(2)
	v_lshlrev_b32_e32 v76, 16, v90
	v_add_f32_e32 v77, 1.0, v80
	v_add_f32_e32 v81, 1.0, v81
	v_rcp_f32_e32 v80, v77
	v_rcp_f32_e32 v81, v81
	v_and_b32_e32 v77, 0xffff0000, v90
	v_pk_mul_f32 v[76:77], v[80:81], v[76:77]
	v_lshlrev_b32_e32 v80, 16, v91
	v_and_b32_e32 v81, 0xffff0000, v91
	v_pk_mul_f32 v[78:79], v[78:79], v[80:81]
	v_cvt_pk_bf16_f32 v80, v76, v77
	v_exp_f32_e32 v76, v72
	v_exp_f32_e32 v77, v73
	s_waitcnt vmcnt(1)
	v_lshlrev_b32_e32 v72, 16, v92
	v_cvt_pk_bf16_f32 v78, v78, v79
	v_add_f32_e32 v73, 1.0, v76
	v_add_f32_e32 v77, 1.0, v77
	v_rcp_f32_e32 v76, v73
	v_rcp_f32_e32 v77, v77
	v_and_b32_e32 v73, 0xffff0000, v92
	v_pk_mul_f32 v[72:73], v[76:77], v[72:73]
	v_lshlrev_b32_e32 v76, 16, v93
	v_and_b32_e32 v77, 0xffff0000, v93
	v_pk_mul_f32 v[74:75], v[74:75], v[76:77]
	v_cvt_pk_bf16_f32 v76, v72, v73
	v_exp_f32_e32 v72, v68
	v_exp_f32_e32 v73, v69
	s_waitcnt vmcnt(0)
	v_lshlrev_b32_e32 v68, 16, v86
	v_cvt_pk_bf16_f32 v74, v74, v75
	v_add_f32_e32 v69, 1.0, v72
	v_add_f32_e32 v73, 1.0, v73
	v_rcp_f32_e32 v72, v69
	v_rcp_f32_e32 v73, v73
	v_and_b32_e32 v69, 0xffff0000, v86
	v_pk_mul_f32 v[68:69], v[72:73], v[68:69]
	s_nop 0
	v_cvt_pk_bf16_f32 v75, v68, v69
	v_cndmask_b32_e32 v68, v88, v80, vcc
	ds_bpermute_b32 v77, v120, v68
	v_lshlrev_b32_e32 v72, 16, v87
	v_and_b32_e32 v73, 0xffff0000, v87
	v_pk_mul_f32 v[70:71], v[70:71], v[72:73]
	v_cndmask_b32_e32 v69, v82, v78, vcc
	ds_bpermute_b32 v79, v120, v69
	v_cvt_pk_bf16_f32 v81, v70, v71
	v_lshlrev_b64 v[68:69], 12, v[84:85]
	v_lshl_add_u64 v[72:73], s[80:81], 0, v[68:69]
	s_waitcnt lgkmcnt(1)
	v_cndmask_b32_e32 v68, v77, v88, vcc
	v_cndmask_b32_e32 v70, v80, v77, vcc
	v_cndmask_b32_e32 v71, v76, v75, vcc
	v_cndmask_b32_e32 v77, v74, v81, vcc
	ds_bpermute_b32 v80, v120, v71
	ds_bpermute_b32 v77, v120, v77
	s_waitcnt lgkmcnt(2)
	v_cndmask_b32_e32 v69, v79, v82, vcc
	v_cndmask_b32_e32 v71, v78, v79, vcc
	v_lshl_add_u64 v[72:73], v[72:73], 0, v[116:117]
	global_store_dwordx4 v[72:73], v[68:71], off offset:3072
	s_waitcnt lgkmcnt(1)
	s_nop 0
	v_cndmask_b32_e32 v68, v80, v76, vcc
	s_waitcnt lgkmcnt(0)
	v_cndmask_b32_e32 v69, v77, v74, vcc
	v_cndmask_b32_e32 v70, v75, v80, vcc
	v_cndmask_b32_e32 v71, v81, v77, vcc
	s_and_b64 vcc, exec, s[26:27]
	global_store_dwordx4 v[72:73], v[68:71], off offset:3136
	s_branch .Lpc_edone_4

.LBB0_325:
	s_mul_hi_i32 s35, s49, s0
	s_mul_i32 s34, s49, s0
	v_lshl_add_u64 v[140:141], s[34:35], 1, v[0:1]
	s_mul_hi_i32 s35, s1, s2
	s_mul_i32 s34, s1, s2
	v_lshl_add_u64 v[142:143], s[34:35], 1, v[138:139]
	s_andn2_b64 vcc, exec, s[24:25]
	s_cbranch_vccnz .LBB0_321
	v_lshl_add_u64 v[148:149], v[140:141], 0, s[20:21]
	v_lshl_add_u64 v[154:155], v[142:143], 0, s[22:23]
	v_lshl_add_u64 v[160:161], v[144:145], 0, s[20:21]
	v_lshl_add_u64 v[166:167], v[146:147], 0, s[22:23]
	v_lshl_add_u64 v[150:151], v[148:149], 0, s[20:21]
	v_lshl_add_u64 v[156:157], v[154:155], 0, s[22:23]
	v_lshl_add_u64 v[162:163], v[160:161], 0, s[20:21]
	v_lshl_add_u64 v[168:169], v[166:167], 0, s[22:23]
	v_mov_b32_e32 v68, 0
	v_lshl_add_u64 v[152:153], v[150:151], 0, s[20:21]
	v_lshl_add_u64 v[158:159], v[156:157], 0, s[22:23]
	v_lshl_add_u64 v[164:165], v[162:163], 0, s[20:21]
	v_lshl_add_u64 v[170:171], v[168:169], 0, s[22:23]
	s_mov_b64 s[34:35], 0x100
	s_mov_b32 s55, 2
	v_mov_b32_e32 v69, v68
	v_mov_b32_e32 v70, v68
	v_mov_b32_e32 v71, v68
	v_mov_b32_e32 v72, v68
	v_mov_b32_e32 v73, v68
	v_mov_b32_e32 v74, v68
	v_mov_b32_e32 v75, v68
	v_mov_b32_e32 v76, v68
	v_mov_b32_e32 v77, v68
	v_mov_b32_e32 v78, v68
	v_mov_b32_e32 v79, v68
	v_mov_b32_e32 v80, v68
	v_mov_b32_e32 v81, v68
	v_mov_b32_e32 v82, v68
	v_mov_b32_e32 v83, v68
	v_mov_b32_e32 v84, v68
	v_mov_b32_e32 v85, v68
	v_mov_b32_e32 v86, v68
	v_mov_b32_e32 v87, v68
	v_mov_b32_e32 v88, v68
	v_mov_b32_e32 v89, v68
	v_mov_b32_e32 v90, v68
	v_mov_b32_e32 v91, v68
	v_mov_b32_e32 v92, v68
	v_mov_b32_e32 v93, v68
	v_mov_b32_e32 v94, v68
	v_mov_b32_e32 v95, v68
	v_mov_b32_e32 v96, v68
	v_mov_b32_e32 v97, v68
	v_mov_b32_e32 v98, v68
	v_mov_b32_e32 v99, v68
	v_mov_b32_e32 v100, v68
	v_mov_b32_e32 v101, v68
	v_mov_b32_e32 v102, v68
	v_mov_b32_e32 v103, v68
	v_mov_b32_e32 v104, v68
	v_mov_b32_e32 v105, v68
	v_mov_b32_e32 v106, v68
	v_mov_b32_e32 v107, v68
	v_mov_b32_e32 v108, v68
	v_mov_b32_e32 v109, v68
	v_mov_b32_e32 v110, v68
	v_mov_b32_e32 v111, v68
	v_mov_b32_e32 v112, v68
	v_mov_b32_e32 v113, v68
	v_mov_b32_e32 v114, v68
	v_mov_b32_e32 v115, v68
	v_mov_b32_e32 v116, v68
	v_mov_b32_e32 v117, v68
	v_mov_b32_e32 v118, v68
	v_mov_b32_e32 v119, v68
	v_mov_b32_e32 v120, v68
	v_mov_b32_e32 v121, v68
	v_mov_b32_e32 v122, v68
	v_mov_b32_e32 v123, v68
	v_mov_b32_e32 v128, v68
	v_mov_b32_e32 v129, v68
	v_mov_b32_e32 v130, v68
	v_mov_b32_e32 v131, v68
	v_mov_b32_e32 v124, v68
	v_mov_b32_e32 v125, v68
	v_mov_b32_e32 v126, v68
	v_mov_b32_e32 v127, v68
	s_branch .LBB0_328
.LBB0_328:
	s_cmp_ge_i32 s100, 0
	s_cbranch_scc1 .Lpc_prod_4
	v_mov_b64_e32 v[4:5], 0
	v_mov_b64_e32 v[6:7], 0
	v_mov_b64_e32 v[8:9], 0
	v_mov_b64_e32 v[10:11], 0
	v_mov_b64_e32 v[12:13], 0
	v_mov_b64_e32 v[14:15], 0
	v_mov_b64_e32 v[16:17], 0
	v_mov_b64_e32 v[18:19], 0
	v_mov_b64_e32 v[20:21], 0
	v_mov_b64_e32 v[22:23], 0
	v_mov_b64_e32 v[24:25], 0
	v_mov_b64_e32 v[26:27], 0
	v_mov_b64_e32 v[28:29], 0
	v_mov_b64_e32 v[30:31], 0
	v_mov_b64_e32 v[32:33], 0
	v_mov_b64_e32 v[34:35], 0
	v_mov_b64_e32 v[36:37], 0
	v_mov_b64_e32 v[38:39], 0
	v_mov_b64_e32 v[40:41], 0
	v_mov_b64_e32 v[42:43], 0
	v_mov_b64_e32 v[44:45], 0
	v_mov_b64_e32 v[46:47], 0
	v_mov_b64_e32 v[48:49], 0
	v_mov_b64_e32 v[50:51], 0
	v_mov_b64_e32 v[52:53], 0
	v_mov_b64_e32 v[54:55], 0
	v_mov_b64_e32 v[56:57], 0
	v_mov_b64_e32 v[58:59], 0
	v_mov_b64_e32 v[60:61], 0
	v_mov_b64_e32 v[62:63], 0
	v_mov_b64_e32 v[64:65], 0
	v_mov_b64_e32 v[66:67], 0
	v_xor_b32_e32 v188, 64, v250
	v_xor_b32_e32 v137, 64, v251
	ds_read_b128 v[222:225], v251
	ds_read_b128 v[238:241], v251 offset:2048
	ds_read_b128 v[242:245], v251 offset:4096
	ds_read_b128 v[246:249], v251 offset:6144
	ds_read_b128 v[172:175], v250
	ds_read_b128 v[176:179], v250 offset:2048
	ds_read_b128 v[180:183], v250 offset:4096
	ds_read_b128 v[184:187], v250 offset:6144
	ds_read_b128 v[132:135], v250 offset:8192
	ds_read_b128 v[208:211], v250 offset:10240
	ds_read_b128 v[214:217], v250 offset:12288
	ds_read_b128 v[218:221], v250 offset:14336
	ds_read_b128 v[226:229], v137
	ds_read_b128 v[230:233], v137 offset:2048
	ds_read_b128 v[144:147], v137 offset:4096
	s_waitcnt lgkmcnt(14)
	ds_read_b128 v[160:163], v137 offset:6144
	s_waitcnt lgkmcnt(14)
	ds_read_b128 v[164:167], v188
	s_waitcnt lgkmcnt(14)
	ds_read_b128 v[168:171], v188 offset:2048
	s_waitcnt lgkmcnt(14)
	ds_read_b128 v[140:143], v188 offset:4096
	s_waitcnt lgkmcnt(14)
	ds_read_b128 v[148:151], v188 offset:6144
	s_waitcnt lgkmcnt(14)
	ds_read_b128 v[152:155], v188 offset:8192
	v_mfma_f32_16x16x32_bf16 v[124:127], v[222:225], v[172:175], v[124:127]
	v_mfma_f32_16x16x32_bf16 v[128:131], v[238:241], v[172:175], v[128:131]
	v_mfma_f32_16x16x32_bf16 v[120:123], v[242:245], v[172:175], v[120:123]
	v_mfma_f32_16x16x32_bf16 v[116:119], v[246:249], v[172:175], v[116:119]
	s_waitcnt lgkmcnt(14)
	ds_read_b128 v[172:175], v188 offset:10240
	v_mfma_f32_16x16x32_bf16 v[112:115], v[222:225], v[176:179], v[112:115]
	v_mfma_f32_16x16x32_bf16 v[108:111], v[238:241], v[176:179], v[108:111]
	v_mfma_f32_16x16x32_bf16 v[104:107], v[242:245], v[176:179], v[104:107]
	v_mfma_f32_16x16x32_bf16 v[100:103], v[246:249], v[176:179], v[100:103]
	s_waitcnt lgkmcnt(14)
	ds_read_b128 v[176:179], v188 offset:12288
	v_mfma_f32_16x16x32_bf16 v[96:99], v[222:225], v[180:183], v[96:99]
	v_mfma_f32_16x16x32_bf16 v[92:95], v[238:241], v[180:183], v[92:95]
	v_mfma_f32_16x16x32_bf16 v[88:91], v[242:245], v[180:183], v[88:91]
	v_mfma_f32_16x16x32_bf16 v[84:87], v[246:249], v[180:183], v[84:87]
	s_waitcnt lgkmcnt(14)
	ds_read_b128 v[180:183], v188 offset:14336
	v_mfma_f32_16x16x32_bf16 v[80:83], v[222:225], v[184:187], v[80:83]
	v_mfma_f32_16x16x32_bf16 v[76:79], v[238:241], v[184:187], v[76:79]
	v_mfma_f32_16x16x32_bf16 v[72:75], v[242:245], v[184:187], v[72:75]
	v_mfma_f32_16x16x32_bf16 v[68:71], v[246:249], v[184:187], v[68:71]
	v_mfma_f32_16x16x32_bf16 v[4:7], v[222:225], v[132:135], v[4:7]
	v_mfma_f32_16x16x32_bf16 v[8:11], v[238:241], v[132:135], v[8:11]
	v_mfma_f32_16x16x32_bf16 v[12:15], v[242:245], v[132:135], v[12:15]
	v_mfma_f32_16x16x32_bf16 v[16:19], v[246:249], v[132:135], v[16:19]
	s_waitcnt lgkmcnt(0)
	s_barrier
	v_mfma_f32_16x16x32_bf16 v[20:23], v[222:225], v[208:211], v[20:23]
	v_mfma_f32_16x16x32_bf16 v[24:27], v[238:241], v[208:211], v[24:27]
	v_mfma_f32_16x16x32_bf16 v[28:31], v[242:245], v[208:211], v[28:31]
	v_mfma_f32_16x16x32_bf16 v[32:35], v[246:249], v[208:211], v[32:35]
	v_mfma_f32_16x16x32_bf16 v[36:39], v[222:225], v[214:217], v[36:39]
	v_mfma_f32_16x16x32_bf16 v[40:43], v[238:241], v[214:217], v[40:43]
	v_mfma_f32_16x16x32_bf16 v[44:47], v[242:245], v[214:217], v[44:47]
	v_mfma_f32_16x16x32_bf16 v[48:51], v[246:249], v[214:217], v[48:51]
	v_mfma_f32_16x16x32_bf16 v[52:55], v[222:225], v[218:221], v[52:55]
	v_mfma_f32_16x16x32_bf16 v[56:59], v[238:241], v[218:221], v[56:59]
	v_mfma_f32_16x16x32_bf16 v[60:63], v[242:245], v[218:221], v[60:63]
	v_mfma_f32_16x16x32_bf16 v[64:67], v[246:249], v[218:221], v[64:67]
	v_mfma_f32_16x16x32_bf16 v[124:127], v[226:229], v[164:167], v[124:127]
	v_mfma_f32_16x16x32_bf16 v[128:131], v[230:233], v[164:167], v[128:131]
	v_mfma_f32_16x16x32_bf16 v[120:123], v[144:147], v[164:167], v[120:123]
	v_mfma_f32_16x16x32_bf16 v[116:119], v[160:163], v[164:167], v[116:119]
	v_mfma_f32_16x16x32_bf16 v[112:115], v[226:229], v[168:171], v[112:115]
	v_mfma_f32_16x16x32_bf16 v[108:111], v[230:233], v[168:171], v[108:111]
	v_mfma_f32_16x16x32_bf16 v[104:107], v[144:147], v[168:171], v[104:107]
	v_mfma_f32_16x16x32_bf16 v[100:103], v[160:163], v[168:171], v[100:103]
	v_mfma_f32_16x16x32_bf16 v[96:99], v[226:229], v[140:143], v[96:99]
	v_mfma_f32_16x16x32_bf16 v[92:95], v[230:233], v[140:143], v[92:95]
	v_mfma_f32_16x16x32_bf16 v[88:91], v[144:147], v[140:143], v[88:91]
	v_mfma_f32_16x16x32_bf16 v[84:87], v[160:163], v[140:143], v[84:87]
	v_mfma_f32_16x16x32_bf16 v[20:23], v[226:229], v[172:175], v[20:23]
	v_mfma_f32_16x16x32_bf16 v[24:27], v[230:233], v[172:175], v[24:27]
	v_mfma_f32_16x16x32_bf16 v[28:31], v[144:147], v[172:175], v[28:31]
	v_mfma_f32_16x16x32_bf16 v[32:35], v[160:163], v[172:175], v[32:35]
	v_mfma_f32_16x16x32_bf16 v[36:39], v[226:229], v[176:179], v[36:39]
	v_mfma_f32_16x16x32_bf16 v[40:43], v[230:233], v[176:179], v[40:43]
	v_mfma_f32_16x16x32_bf16 v[44:47], v[144:147], v[176:179], v[44:47]
	v_mfma_f32_16x16x32_bf16 v[48:51], v[160:163], v[176:179], v[48:51]
	v_mfma_f32_16x16x32_bf16 v[52:55], v[226:229], v[180:183], v[52:55]
	v_mfma_f32_16x16x32_bf16 v[56:59], v[230:233], v[180:183], v[56:59]
	v_mfma_f32_16x16x32_bf16 v[60:63], v[144:147], v[180:183], v[60:63]
	v_mfma_f32_16x16x32_bf16 v[64:67], v[160:163], v[180:183], v[64:67]
	s_barrier
	s_branch .Lpc_ck1_4
.Lpc_ctop_4:
	ds_read_b128 v[222:225], v251
	ds_read_b128 v[238:241], v251 offset:2048
	ds_read_b128 v[242:245], v251 offset:4096
	ds_read_b128 v[246:249], v251 offset:6144
	ds_read_b128 v[172:175], v250
	ds_read_b128 v[176:179], v250 offset:2048
	ds_read_b128 v[180:183], v250 offset:4096
	ds_read_b128 v[184:187], v250 offset:6144
	ds_read_b128 v[132:135], v250 offset:8192
	ds_read_b128 v[208:211], v250 offset:10240
	v_mfma_f32_16x16x32_bf16 v[80:83], v[226:229], v[148:151], v[80:83]
	v_mfma_f32_16x16x32_bf16 v[76:79], v[230:233], v[148:151], v[76:79]
	v_mfma_f32_16x16x32_bf16 v[72:75], v[144:147], v[148:151], v[72:75]
	v_mfma_f32_16x16x32_bf16 v[68:71], v[160:163], v[148:151], v[68:71]
	v_mfma_f32_16x16x32_bf16 v[4:7], v[226:229], v[152:155], v[4:7]
	v_mfma_f32_16x16x32_bf16 v[8:11], v[230:233], v[152:155], v[8:11]
	v_mfma_f32_16x16x32_bf16 v[12:15], v[144:147], v[152:155], v[12:15]
	v_mfma_f32_16x16x32_bf16 v[16:19], v[160:163], v[152:155], v[16:19]
	ds_read_b128 v[214:217], v250 offset:12288
	ds_read_b128 v[218:221], v250 offset:14336
	ds_read_b128 v[226:229], v137
	ds_read_b128 v[230:233], v137 offset:2048
	ds_read_b128 v[144:147], v137 offset:4096
	s_waitcnt lgkmcnt(14)
	ds_read_b128 v[160:163], v137 offset:6144
	s_waitcnt lgkmcnt(14)
	ds_read_b128 v[164:167], v188
	s_waitcnt lgkmcnt(14)
	ds_read_b128 v[168:171], v188 offset:2048
	s_waitcnt lgkmcnt(14)
	ds_read_b128 v[140:143], v188 offset:4096
	s_waitcnt lgkmcnt(14)
	ds_read_b128 v[148:151], v188 offset:6144
	s_waitcnt lgkmcnt(14)
	ds_read_b128 v[152:155], v188 offset:8192
	v_mfma_f32_16x16x32_bf16 v[124:127], v[222:225], v[172:175], v[124:127]
	v_mfma_f32_16x16x32_bf16 v[128:131], v[238:241], v[172:175], v[128:131]
	v_mfma_f32_16x16x32_bf16 v[120:123], v[242:245], v[172:175], v[120:123]
	v_mfma_f32_16x16x32_bf16 v[116:119], v[246:249], v[172:175], v[116:119]
	s_waitcnt lgkmcnt(14)
	ds_read_b128 v[172:175], v188 offset:10240
	v_mfma_f32_16x16x32_bf16 v[112:115], v[222:225], v[176:179], v[112:115]
	v_mfma_f32_16x16x32_bf16 v[108:111], v[238:241], v[176:179], v[108:111]
	v_mfma_f32_16x16x32_bf16 v[104:107], v[242:245], v[176:179], v[104:107]
	v_mfma_f32_16x16x32_bf16 v[100:103], v[246:249], v[176:179], v[100:103]
	s_waitcnt lgkmcnt(14)
	ds_read_b128 v[176:179], v188 offset:12288
	v_mfma_f32_16x16x32_bf16 v[96:99], v[222:225], v[180:183], v[96:99]
	v_mfma_f32_16x16x32_bf16 v[92:95], v[238:241], v[180:183], v[92:95]
	v_mfma_f32_16x16x32_bf16 v[88:91], v[242:245], v[180:183], v[88:91]
	v_mfma_f32_16x16x32_bf16 v[84:87], v[246:249], v[180:183], v[84:87]
	s_waitcnt lgkmcnt(14)
	ds_read_b128 v[180:183], v188 offset:14336
	v_mfma_f32_16x16x32_bf16 v[80:83], v[222:225], v[184:187], v[80:83]
	v_mfma_f32_16x16x32_bf16 v[76:79], v[238:241], v[184:187], v[76:79]
	v_mfma_f32_16x16x32_bf16 v[72:75], v[242:245], v[184:187], v[72:75]
	v_mfma_f32_16x16x32_bf16 v[68:71], v[246:249], v[184:187], v[68:71]
	v_mfma_f32_16x16x32_bf16 v[4:7], v[222:225], v[132:135], v[4:7]
	v_mfma_f32_16x16x32_bf16 v[8:11], v[238:241], v[132:135], v[8:11]
	v_mfma_f32_16x16x32_bf16 v[12:15], v[242:245], v[132:135], v[12:15]
	v_mfma_f32_16x16x32_bf16 v[16:19], v[246:249], v[132:135], v[16:19]
	s_waitcnt lgkmcnt(0)
	s_barrier
	v_mfma_f32_16x16x32_bf16 v[20:23], v[222:225], v[208:211], v[20:23]
	v_mfma_f32_16x16x32_bf16 v[24:27], v[238:241], v[208:211], v[24:27]
	v_mfma_f32_16x16x32_bf16 v[28:31], v[242:245], v[208:211], v[28:31]
	v_mfma_f32_16x16x32_bf16 v[32:35], v[246:249], v[208:211], v[32:35]
	v_mfma_f32_16x16x32_bf16 v[36:39], v[222:225], v[214:217], v[36:39]
	v_mfma_f32_16x16x32_bf16 v[40:43], v[238:241], v[214:217], v[40:43]
	v_mfma_f32_16x16x32_bf16 v[44:47], v[242:245], v[214:217], v[44:47]
	v_mfma_f32_16x16x32_bf16 v[48:51], v[246:249], v[214:217], v[48:51]
	v_mfma_f32_16x16x32_bf16 v[52:55], v[222:225], v[218:221], v[52:55]
	v_mfma_f32_16x16x32_bf16 v[56:59], v[238:241], v[218:221], v[56:59]
	v_mfma_f32_16x16x32_bf16 v[60:63], v[242:245], v[218:221], v[60:63]
	v_mfma_f32_16x16x32_bf16 v[64:67], v[246:249], v[218:221], v[64:67]
	v_mfma_f32_16x16x32_bf16 v[124:127], v[226:229], v[164:167], v[124:127]
	v_mfma_f32_16x16x32_bf16 v[128:131], v[230:233], v[164:167], v[128:131]
	v_mfma_f32_16x16x32_bf16 v[120:123], v[144:147], v[164:167], v[120:123]
	v_mfma_f32_16x16x32_bf16 v[116:119], v[160:163], v[164:167], v[116:119]
	v_mfma_f32_16x16x32_bf16 v[112:115], v[226:229], v[168:171], v[112:115]
	v_mfma_f32_16x16x32_bf16 v[108:111], v[230:233], v[168:171], v[108:111]
	v_mfma_f32_16x16x32_bf16 v[104:107], v[144:147], v[168:171], v[104:107]
	v_mfma_f32_16x16x32_bf16 v[100:103], v[160:163], v[168:171], v[100:103]
	v_mfma_f32_16x16x32_bf16 v[96:99], v[226:229], v[140:143], v[96:99]
	v_mfma_f32_16x16x32_bf16 v[92:95], v[230:233], v[140:143], v[92:95]
	v_mfma_f32_16x16x32_bf16 v[88:91], v[144:147], v[140:143], v[88:91]
	v_mfma_f32_16x16x32_bf16 v[84:87], v[160:163], v[140:143], v[84:87]
	v_mfma_f32_16x16x32_bf16 v[20:23], v[226:229], v[172:175], v[20:23]
	v_mfma_f32_16x16x32_bf16 v[24:27], v[230:233], v[172:175], v[24:27]
	v_mfma_f32_16x16x32_bf16 v[28:31], v[144:147], v[172:175], v[28:31]
	v_mfma_f32_16x16x32_bf16 v[32:35], v[160:163], v[172:175], v[32:35]
	v_mfma_f32_16x16x32_bf16 v[36:39], v[226:229], v[176:179], v[36:39]
	v_mfma_f32_16x16x32_bf16 v[40:43], v[230:233], v[176:179], v[40:43]
	v_mfma_f32_16x16x32_bf16 v[44:47], v[144:147], v[176:179], v[44:47]
	v_mfma_f32_16x16x32_bf16 v[48:51], v[160:163], v[176:179], v[48:51]
	v_mfma_f32_16x16x32_bf16 v[52:55], v[226:229], v[180:183], v[52:55]
	v_mfma_f32_16x16x32_bf16 v[56:59], v[230:233], v[180:183], v[56:59]
	v_mfma_f32_16x16x32_bf16 v[60:63], v[144:147], v[180:183], v[60:63]
	v_mfma_f32_16x16x32_bf16 v[64:67], v[160:163], v[180:183], v[64:67]
	s_barrier
.Lpc_ck1_4:
	ds_read_b128 v[222:225], v251 offset:32768
	ds_read_b128 v[238:241], v251 offset:34816
	ds_read_b128 v[242:245], v251 offset:36864
	ds_read_b128 v[246:249], v251 offset:38912
	ds_read_b128 v[172:175], v250 offset:32768
	ds_read_b128 v[176:179], v250 offset:34816
	ds_read_b128 v[180:183], v250 offset:36864
	ds_read_b128 v[184:187], v250 offset:38912
	ds_read_b128 v[132:135], v250 offset:40960
	ds_read_b128 v[208:211], v250 offset:43008
	v_mfma_f32_16x16x32_bf16 v[80:83], v[226:229], v[148:151], v[80:83]
	v_mfma_f32_16x16x32_bf16 v[76:79], v[230:233], v[148:151], v[76:79]
	v_mfma_f32_16x16x32_bf16 v[72:75], v[144:147], v[148:151], v[72:75]
	v_mfma_f32_16x16x32_bf16 v[68:71], v[160:163], v[148:151], v[68:71]
	v_mfma_f32_16x16x32_bf16 v[4:7], v[226:229], v[152:155], v[4:7]
	v_mfma_f32_16x16x32_bf16 v[8:11], v[230:233], v[152:155], v[8:11]
	v_mfma_f32_16x16x32_bf16 v[12:15], v[144:147], v[152:155], v[12:15]
	v_mfma_f32_16x16x32_bf16 v[16:19], v[160:163], v[152:155], v[16:19]
	ds_read_b128 v[214:217], v250 offset:45056
	ds_read_b128 v[218:221], v250 offset:47104
	ds_read_b128 v[226:229], v137 offset:32768
	ds_read_b128 v[230:233], v137 offset:34816
	ds_read_b128 v[144:147], v137 offset:36864
	s_waitcnt lgkmcnt(14)
	ds_read_b128 v[160:163], v137 offset:38912
	s_waitcnt lgkmcnt(14)
	ds_read_b128 v[164:167], v188 offset:32768
	s_waitcnt lgkmcnt(14)
	ds_read_b128 v[168:171], v188 offset:34816
	s_waitcnt lgkmcnt(14)
	ds_read_b128 v[140:143], v188 offset:36864
	s_waitcnt lgkmcnt(14)
	ds_read_b128 v[148:151], v188 offset:38912
	s_waitcnt lgkmcnt(14)
	ds_read_b128 v[152:155], v188 offset:40960
	v_mfma_f32_16x16x32_bf16 v[124:127], v[222:225], v[172:175], v[124:127]
	v_mfma_f32_16x16x32_bf16 v[128:131], v[238:241], v[172:175], v[128:131]
	v_mfma_f32_16x16x32_bf16 v[120:123], v[242:245], v[172:175], v[120:123]
	v_mfma_f32_16x16x32_bf16 v[116:119], v[246:249], v[172:175], v[116:119]
	s_waitcnt lgkmcnt(14)
	ds_read_b128 v[172:175], v188 offset:43008
	v_mfma_f32_16x16x32_bf16 v[112:115], v[222:225], v[176:179], v[112:115]
	v_mfma_f32_16x16x32_bf16 v[108:111], v[238:241], v[176:179], v[108:111]
	v_mfma_f32_16x16x32_bf16 v[104:107], v[242:245], v[176:179], v[104:107]
	v_mfma_f32_16x16x32_bf16 v[100:103], v[246:249], v[176:179], v[100:103]
	s_waitcnt lgkmcnt(14)
	ds_read_b128 v[176:179], v188 offset:45056
	v_mfma_f32_16x16x32_bf16 v[96:99], v[222:225], v[180:183], v[96:99]
	v_mfma_f32_16x16x32_bf16 v[92:95], v[238:241], v[180:183], v[92:95]
	v_mfma_f32_16x16x32_bf16 v[88:91], v[242:245], v[180:183], v[88:91]
	v_mfma_f32_16x16x32_bf16 v[84:87], v[246:249], v[180:183], v[84:87]
	s_waitcnt lgkmcnt(14)
	ds_read_b128 v[180:183], v188 offset:47104
	v_mfma_f32_16x16x32_bf16 v[80:83], v[222:225], v[184:187], v[80:83]
	v_mfma_f32_16x16x32_bf16 v[76:79], v[238:241], v[184:187], v[76:79]
	v_mfma_f32_16x16x32_bf16 v[72:75], v[242:245], v[184:187], v[72:75]
	v_mfma_f32_16x16x32_bf16 v[68:71], v[246:249], v[184:187], v[68:71]
	v_mfma_f32_16x16x32_bf16 v[4:7], v[222:225], v[132:135], v[4:7]
	v_mfma_f32_16x16x32_bf16 v[8:11], v[238:241], v[132:135], v[8:11]
	v_mfma_f32_16x16x32_bf16 v[12:15], v[242:245], v[132:135], v[12:15]
	v_mfma_f32_16x16x32_bf16 v[16:19], v[246:249], v[132:135], v[16:19]
	s_waitcnt lgkmcnt(0)
	s_barrier
	v_mfma_f32_16x16x32_bf16 v[20:23], v[222:225], v[208:211], v[20:23]
	v_mfma_f32_16x16x32_bf16 v[24:27], v[238:241], v[208:211], v[24:27]
	v_mfma_f32_16x16x32_bf16 v[28:31], v[242:245], v[208:211], v[28:31]
	v_mfma_f32_16x16x32_bf16 v[32:35], v[246:249], v[208:211], v[32:35]
	v_mfma_f32_16x16x32_bf16 v[36:39], v[222:225], v[214:217], v[36:39]
	v_mfma_f32_16x16x32_bf16 v[40:43], v[238:241], v[214:217], v[40:43]
	v_mfma_f32_16x16x32_bf16 v[44:47], v[242:245], v[214:217], v[44:47]
	v_mfma_f32_16x16x32_bf16 v[48:51], v[246:249], v[214:217], v[48:51]
	v_mfma_f32_16x16x32_bf16 v[52:55], v[222:225], v[218:221], v[52:55]
	v_mfma_f32_16x16x32_bf16 v[56:59], v[238:241], v[218:221], v[56:59]
	v_mfma_f32_16x16x32_bf16 v[60:63], v[242:245], v[218:221], v[60:63]
	v_mfma_f32_16x16x32_bf16 v[64:67], v[246:249], v[218:221], v[64:67]
	v_mfma_f32_16x16x32_bf16 v[124:127], v[226:229], v[164:167], v[124:127]
	v_mfma_f32_16x16x32_bf16 v[128:131], v[230:233], v[164:167], v[128:131]
	v_mfma_f32_16x16x32_bf16 v[120:123], v[144:147], v[164:167], v[120:123]
	v_mfma_f32_16x16x32_bf16 v[116:119], v[160:163], v[164:167], v[116:119]
	v_mfma_f32_16x16x32_bf16 v[112:115], v[226:229], v[168:171], v[112:115]
	v_mfma_f32_16x16x32_bf16 v[108:111], v[230:233], v[168:171], v[108:111]
	v_mfma_f32_16x16x32_bf16 v[104:107], v[144:147], v[168:171], v[104:107]
	v_mfma_f32_16x16x32_bf16 v[100:103], v[160:163], v[168:171], v[100:103]
	v_mfma_f32_16x16x32_bf16 v[96:99], v[226:229], v[140:143], v[96:99]
	v_mfma_f32_16x16x32_bf16 v[92:95], v[230:233], v[140:143], v[92:95]
	v_mfma_f32_16x16x32_bf16 v[88:91], v[144:147], v[140:143], v[88:91]
	v_mfma_f32_16x16x32_bf16 v[84:87], v[160:163], v[140:143], v[84:87]
	v_mfma_f32_16x16x32_bf16 v[20:23], v[226:229], v[172:175], v[20:23]
	v_mfma_f32_16x16x32_bf16 v[24:27], v[230:233], v[172:175], v[24:27]
	v_mfma_f32_16x16x32_bf16 v[28:31], v[144:147], v[172:175], v[28:31]
	v_mfma_f32_16x16x32_bf16 v[32:35], v[160:163], v[172:175], v[32:35]
	v_mfma_f32_16x16x32_bf16 v[36:39], v[226:229], v[176:179], v[36:39]
	v_mfma_f32_16x16x32_bf16 v[40:43], v[230:233], v[176:179], v[40:43]
	v_mfma_f32_16x16x32_bf16 v[44:47], v[144:147], v[176:179], v[44:47]
	v_mfma_f32_16x16x32_bf16 v[48:51], v[160:163], v[176:179], v[48:51]
	v_mfma_f32_16x16x32_bf16 v[52:55], v[226:229], v[180:183], v[52:55]
	v_mfma_f32_16x16x32_bf16 v[56:59], v[230:233], v[180:183], v[56:59]
	v_mfma_f32_16x16x32_bf16 v[60:63], v[144:147], v[180:183], v[60:63]
	v_mfma_f32_16x16x32_bf16 v[64:67], v[160:163], v[180:183], v[64:67]
	s_barrier
	s_add_i32 s55, s55, 2
	s_cmp_le_i32 s55, s47
	s_cbranch_scc1 .Lpc_ctop_4
	v_mfma_f32_16x16x32_bf16 v[80:83], v[226:229], v[148:151], v[80:83]
	v_mfma_f32_16x16x32_bf16 v[76:79], v[230:233], v[148:151], v[76:79]
	v_mfma_f32_16x16x32_bf16 v[72:75], v[144:147], v[148:151], v[72:75]
	v_mfma_f32_16x16x32_bf16 v[68:71], v[160:163], v[148:151], v[68:71]
	v_mfma_f32_16x16x32_bf16 v[4:7], v[226:229], v[152:155], v[4:7]
	v_mfma_f32_16x16x32_bf16 v[8:11], v[230:233], v[152:155], v[8:11]
	v_mfma_f32_16x16x32_bf16 v[12:15], v[144:147], v[152:155], v[12:15]
	v_mfma_f32_16x16x32_bf16 v[16:19], v[160:163], v[152:155], v[16:19]
	s_mov_b32 s98, s53
	s_mov_b32 s99, s52
	s_mov_b32 s100, -2
	s_bfe_u32 vcc_lo, s101, 0x10001
	s_lshl_b32 vcc_lo, vcc_lo, 6
	v_add_u32_e32 v194, vcc_lo, v202
	s_branch .LBB0_322
.Lpc_edone_4:
	s_cmp_eq_u32 s100, -2
	s_cbranch_scc0 .Lpc_efin_4
	s_mov_b32 s100, -3
	s_mov_b32 s53, s98
	s_mov_b32 s52, s99
	v_mov_b64_e32 v[124:125], v[4:5]
	v_mov_b64_e32 v[126:127], v[6:7]
	v_mov_b64_e32 v[128:129], v[8:9]
	v_mov_b64_e32 v[130:131], v[10:11]
	v_mov_b64_e32 v[120:121], v[12:13]
	v_mov_b64_e32 v[122:123], v[14:15]
	v_mov_b64_e32 v[116:117], v[16:17]
	v_mov_b64_e32 v[118:119], v[18:19]
	v_mov_b64_e32 v[112:113], v[20:21]
	v_mov_b64_e32 v[114:115], v[22:23]
	v_mov_b64_e32 v[108:109], v[24:25]
	v_mov_b64_e32 v[110:111], v[26:27]
	v_mov_b64_e32 v[104:105], v[28:29]
	v_mov_b64_e32 v[106:107], v[30:31]
	v_mov_b64_e32 v[100:101], v[32:33]
	v_mov_b64_e32 v[102:103], v[34:35]
	v_mov_b64_e32 v[96:97], v[36:37]
	v_mov_b64_e32 v[98:99], v[38:39]
	v_mov_b64_e32 v[92:93], v[40:41]
	v_mov_b64_e32 v[94:95], v[42:43]
	v_mov_b64_e32 v[88:89], v[44:45]
	v_mov_b64_e32 v[90:91], v[46:47]
	v_mov_b64_e32 v[84:85], v[48:49]
	v_mov_b64_e32 v[86:87], v[50:51]
	v_mov_b64_e32 v[80:81], v[52:53]
	v_mov_b64_e32 v[82:83], v[54:55]
	v_mov_b64_e32 v[76:77], v[56:57]
	v_mov_b64_e32 v[78:79], v[58:59]
	v_mov_b64_e32 v[72:73], v[60:61]
	v_mov_b64_e32 v[74:75], v[62:63]
	v_mov_b64_e32 v[68:69], v[64:65]
	v_mov_b64_e32 v[70:71], v[66:67]
	v_add_u32_e32 v194, 0x80, v194
	s_branch .LBB0_322

.Lpc_pgo_4:
	s_nop 0
	s_sub_u32 s40, s40, s98
	s_subb_u32 s41, s41, 0
	s_sub_u32 s38, s38, s99
	s_subb_u32 s39, s39, 0
	s_bfe_u32 vcc_hi, s101, 0x80008
	s_add_u32 vcc_hi, vcc_hi, vcc_lo
	s_add_u32 m0, s47, -1
	s_and_b32 vcc_hi, vcc_hi, m0
	s_lshl_b32 vcc_hi, vcc_hi, 7
	v_add_u32_e32 v20, vcc_hi, v4
	v_add_u32_e32 v21, vcc_hi, v5
	v_add_u32_e32 v22, vcc_hi, v6
	v_add_u32_e32 v23, vcc_hi, v7
	v_add_u32_e32 v24, vcc_hi, v8
	v_add_u32_e32 v25, vcc_hi, v9
	v_add_u32_e32 v26, vcc_hi, v10
	v_add_u32_e32 v27, vcc_hi, v11
	v_add_u32_e32 v28, vcc_hi, v12
	v_add_u32_e32 v29, vcc_hi, v13
	v_add_u32_e32 v30, vcc_hi, v14
	v_add_u32_e32 v31, vcc_hi, v15
	v_add_u32_e32 v32, vcc_hi, v16
	v_add_u32_e32 v33, vcc_hi, v17
	v_add_u32_e32 v34, vcc_hi, v18
	v_add_u32_e32 v35, vcc_hi, v19
	s_add_u32 vcc_lo, vcc_lo, 1
	s_barrier
	s_add_u32 m0, s100, 0x0
	s_nop 0
	global_load_lds_dwordx4 v20, s[40:41]
	s_add_u32 m0, s100, 0x400
	s_nop 0
	global_load_lds_dwordx4 v21, s[40:41]
	s_add_u32 m0, s100, 0x1000
	s_nop 0
	global_load_lds_dwordx4 v22, s[40:41]
	s_add_u32 m0, s100, 0x1400
	s_nop 0
	global_load_lds_dwordx4 v23, s[40:41]
	s_add_u32 m0, s100, 0x2000
	s_nop 0
	global_load_lds_dwordx4 v24, s[40:41]
	s_add_u32 m0, s100, 0x2400
	s_nop 0
	global_load_lds_dwordx4 v25, s[40:41]
	s_add_u32 m0, s100, 0x3000
	s_nop 0
	global_load_lds_dwordx4 v26, s[40:41]
	s_add_u32 m0, s100, 0x3400
	s_nop 0
	global_load_lds_dwordx4 v27, s[40:41]
	s_waitcnt vmcnt(8)
	s_barrier
	s_add_u32 m0, s100, 0x4000
	s_nop 0
	global_load_lds_dwordx4 v28, s[38:39]
	s_add_u32 m0, s100, 0x4400
	s_nop 0
	global_load_lds_dwordx4 v29, s[38:39]
	s_add_u32 m0, s100, 0x5000
	s_nop 0
	global_load_lds_dwordx4 v30, s[38:39]
	s_add_u32 m0, s100, 0x5400
	s_nop 0
	global_load_lds_dwordx4 v31, s[38:39]
	s_add_u32 m0, s100, 0x6000
	s_nop 0
	global_load_lds_dwordx4 v32, s[38:39]
	s_add_u32 m0, s100, 0x6400
	s_nop 0
	global_load_lds_dwordx4 v33, s[38:39]
	s_add_u32 m0, s100, 0x7000
	s_nop 0
	global_load_lds_dwordx4 v34, s[38:39]
	s_add_u32 m0, s100, 0x7400
	s_nop 0
	global_load_lds_dwordx4 v35, s[38:39]
	s_bfe_u32 vcc_hi, s101, 0x80008
	s_add_u32 vcc_hi, vcc_hi, vcc_lo
	s_add_u32 m0, s47, -1
	s_and_b32 vcc_hi, vcc_hi, m0
	s_lshl_b32 vcc_hi, vcc_hi, 7
	v_add_u32_e32 v20, vcc_hi, v4
	v_add_u32_e32 v21, vcc_hi, v5
	v_add_u32_e32 v22, vcc_hi, v6
	v_add_u32_e32 v23, vcc_hi, v7
	v_add_u32_e32 v24, vcc_hi, v8
	v_add_u32_e32 v25, vcc_hi, v9
	v_add_u32_e32 v26, vcc_hi, v10
	v_add_u32_e32 v27, vcc_hi, v11
	v_add_u32_e32 v28, vcc_hi, v12
	v_add_u32_e32 v29, vcc_hi, v13
	v_add_u32_e32 v30, vcc_hi, v14
	v_add_u32_e32 v31, vcc_hi, v15
	v_add_u32_e32 v32, vcc_hi, v16
	v_add_u32_e32 v33, vcc_hi, v17
	v_add_u32_e32 v34, vcc_hi, v18
	v_add_u32_e32 v35, vcc_hi, v19
	s_add_u32 vcc_lo, vcc_lo, 1
	s_barrier
	s_add_u32 m0, s100, 0x8000
	s_nop 0
	global_load_lds_dwordx4 v20, s[40:41]
	s_add_u32 m0, s100, 0x8400
	s_nop 0
	global_load_lds_dwordx4 v21, s[40:41]
	s_add_u32 m0, s100, 0x9000
	s_nop 0
	global_load_lds_dwordx4 v22, s[40:41]
	s_add_u32 m0, s100, 0x9400
	s_nop 0
	global_load_lds_dwordx4 v23, s[40:41]
	s_add_u32 m0, s100, 0xa000
	s_nop 0
	global_load_lds_dwordx4 v24, s[40:41]
	s_add_u32 m0, s100, 0xa400
	s_nop 0
	global_load_lds_dwordx4 v25, s[40:41]
	s_add_u32 m0, s100, 0xb000
	s_nop 0
	global_load_lds_dwordx4 v26, s[40:41]
	s_add_u32 m0, s100, 0xb400
	s_nop 0
	global_load_lds_dwordx4 v27, s[40:41]
	s_waitcnt vmcnt(8)
	s_barrier
	s_add_u32 m0, s100, 0xc000
	s_nop 0
	global_load_lds_dwordx4 v28, s[38:39]
	s_add_u32 m0, s100, 0xc400
	s_nop 0
	global_load_lds_dwordx4 v29, s[38:39]
	s_add_u32 m0, s100, 0xd000
	s_nop 0
	global_load_lds_dwordx4 v30, s[38:39]
	s_add_u32 m0, s100, 0xd400
	s_nop 0
	global_load_lds_dwordx4 v31, s[38:39]
	s_add_u32 m0, s100, 0xe000
	s_nop 0
	global_load_lds_dwordx4 v32, s[38:39]
	s_add_u32 m0, s100, 0xe400
	s_nop 0
	global_load_lds_dwordx4 v33, s[38:39]
	s_add_u32 m0, s100, 0xf000
	s_nop 0
	global_load_lds_dwordx4 v34, s[38:39]
	s_add_u32 m0, s100, 0xf400
	s_nop 0
	global_load_lds_dwordx4 v35, s[38:39]
	s_add_u32 s34, s34, 0x100
	s_addc_u32 s35, s35, 0
	s_add_i32 s55, s55, 2
	s_cmp_le_i32 s55, s47
	s_cbranch_scc1 .Lpc_ptop_4
	s_mov_b32 s53, s49
	s_mov_b32 s52, s1
	v_mov_b64_e32 v[146:147], v[142:143]
	v_mov_b64_e32 v[144:145], v[140:141]
	s_and_b64 vcc, exec, s[26:27]
	s_cbranch_vccz .Lpc_pnd_4
	s_waitcnt vmcnt(0)
	s_branch .LBB0_342

.LBB0_940:
	s_andn2_b64 vcc, exec, s[0:1]
	s_cbranch_vccnz .LBB0_992
	v_readlane_b32 s0, v255, 2
	s_cmp_gt_i32 s0, 0
	s_mov_b64 s[0:1], -1
	s_cbranch_scc0 .LBB0_966
	v_readlane_b32 s4, v253, 13
	s_waitcnt vmcnt(1)
	v_mov_b32_e32 v68, v194
	s_movk_i32 s0, 0x400
	s_movk_i32 s2, 0x400
	s_movk_i32 s3, 0x400
	v_readlane_b32 s5, v253, 14
	s_load_dword s1, s[4:5], 0x0
	v_readlane_b32 s4, v254, 30
	s_waitcnt lgkmcnt(0)
	s_lshr_b32 s46, s1, 3
	v_readlane_b32 s1, v254, 36
	s_mul_i32 s1, s46, s1
	s_add_i32 s1, s1, s4
	s_cmpk_gt_i32 s1, 0x1a07
	s_cbranch_scc1 .LBB0_965
	v_readlane_b32 s4, v254, 63
	s_ashr_i32 s47, s3, 6
	v_readlane_b32 s5, v255, 0
	s_and_b64 s[20:21], s[4:5], exec
	v_readlane_b32 s4, v252, 37
	s_cselect_b32 s3, 0x1440000, 0
	v_readlane_b32 s12, v252, 45
	v_readlane_b32 s13, v252, 46
	s_add_u32 s24, s12, s3
	s_mul_hi_i32 s3, s1, 0x5397829d
	s_addc_u32 s25, s13, 0
	s_lshr_b32 s20, s3, 31
	s_ashr_i32 s3, s3, 7
	s_add_i32 s3, s3, s20
	s_mul_i32 s20, s3, 0xfffffe78
	s_add_i32 s20, s20, s1
	s_lshl_b32 s1, s1, 7
	v_lshlrev_b32_e32 v0, 3, v68
	v_ashrrev_i32_e32 v3, 3, v68
	s_lshl_b32 s3, s3, 10
	s_and_b32 s1, s1, 0x380
	v_and_b32_e32 v0, 56, v0
	v_lshrrev_b32_e32 v132, 4, v68
	v_xor_b32_e32 v132, v132, v68
	v_and_b32_e32 v132, 7, v132
	v_lshlrev_b32_e32 v0, 3, v132
	v_mov_b32_e32 v1, v2
	s_or_b32 s52, s3, s1
	s_lshl_b32 s1, s20, 4
	v_mad_i64_i32 v[4:5], s[20:21], s0, v3, v[0:1]
	v_mad_i64_i32 v[0:1], s[20:21], s2, v3, v[0:1]
	s_mul_hi_i32 s21, s52, s0
	s_mul_i32 s20, s52, s0
	s_and_b32 s49, s1, 0xffffff80
	s_ashr_i32 s1, s0, 31
	s_ashr_i32 s3, s2, 31
	s_lshl_b64 s[20:21], s[20:21], 1
	s_add_u32 s20, s76, s20
	s_addc_u32 s21, s77, s21
	v_lshlrev_b64 v[70:71], 1, v[4:5]
	v_lshl_add_u64 v[144:145], s[20:21], 0, v[70:71]
	s_mul_hi_i32 s21, s49, s2
	s_mul_i32 s20, s49, s2
	s_lshl_b64 s[20:21], s[20:21], 1
	s_add_u32 s20, s24, s20
	s_addc_u32 s21, s25, s21
	s_waitcnt vmcnt(0)
	v_lshlrev_b64 v[72:73], 1, v[0:1]
	v_lshl_add_u64 v[146:147], s[20:21], 0, v[72:73]
	s_lshl_b64 s[20:21], s[0:1], 6
	v_lshl_add_u64 v[0:1], v[144:145], 0, s[20:21]
	s_lshl_b64 s[22:23], s[2:3], 6
	v_lshl_add_u64 v[36:37], v[0:1], 0, s[20:21]
	v_lshl_add_u64 v[56:57], v[146:147], 0, s[22:23]
	v_lshl_add_u64 v[40:41], v[36:37], 0, s[20:21]
	v_lshl_add_u64 v[60:61], v[56:57], 0, s[22:23]
	v_lshl_add_u64 v[64:65], v[60:61], 0, s[22:23]
	s_bfe_u32 s100, s101, 0x20002
	s_lshl_b32 s100, s100, 10
	s_bfe_u32 vcc_lo, s101, 0x80008
	s_add_u32 vcc_lo, vcc_lo, 0
	s_add_u32 vcc_hi, s47, -1
	s_and_b32 vcc_lo, vcc_lo, vcc_hi
	s_lshl_b32 vcc_lo, vcc_lo, 7
	s_mov_b32 vcc_hi, 0
	v_lshl_add_u64 v[20:21], v[144:145], 0, vcc
	s_add_u32 m0, s100, 0x0
	s_nop 0
	global_load_lds_dwordx4 v[20:21], off
	v_lshl_add_u64 v[20:21], v[0:1], 0, vcc
	s_add_u32 m0, s100, 0x1000
	s_nop 0
	global_load_lds_dwordx4 v[20:21], off
	v_lshl_add_u64 v[20:21], v[36:37], 0, vcc
	s_add_u32 m0, s100, 0x2000
	s_nop 0
	global_load_lds_dwordx4 v[20:21], off
	v_lshl_add_u64 v[20:21], v[40:41], 0, vcc
	s_add_u32 m0, s100, 0x3000
	s_nop 0
	global_load_lds_dwordx4 v[20:21], off
	v_lshl_add_u64 v[20:21], v[146:147], 0, vcc
	s_add_u32 m0, s100, 0x4000
	s_nop 0
	global_load_lds_dwordx4 v[20:21], off
	v_lshl_add_u64 v[20:21], v[56:57], 0, vcc
	s_add_u32 m0, s100, 0x5000
	s_nop 0
	global_load_lds_dwordx4 v[20:21], off
	v_lshl_add_u64 v[20:21], v[60:61], 0, vcc
	s_add_u32 m0, s100, 0x6000
	s_nop 0
	global_load_lds_dwordx4 v[20:21], off
	v_lshl_add_u64 v[20:21], v[64:65], 0, vcc
	s_add_u32 m0, s100, 0x7000
	s_nop 0
	global_load_lds_dwordx4 v[20:21], off
	s_bfe_u32 vcc_lo, s101, 0x80008
	s_add_u32 vcc_lo, vcc_lo, 1
	s_add_u32 vcc_hi, s47, -1
	s_and_b32 vcc_lo, vcc_lo, vcc_hi
	s_lshl_b32 vcc_lo, vcc_lo, 7
	s_mov_b32 vcc_hi, 0
	v_lshl_add_u64 v[20:21], v[144:145], 0, vcc
	s_add_u32 m0, s100, 0x8000
	s_nop 0
	global_load_lds_dwordx4 v[20:21], off
	v_lshl_add_u64 v[20:21], v[0:1], 0, vcc
	s_add_u32 m0, s100, 0x9000
	s_nop 0
	global_load_lds_dwordx4 v[20:21], off
	v_lshl_add_u64 v[20:21], v[36:37], 0, vcc
	s_add_u32 m0, s100, 0xa000
	s_nop 0
	global_load_lds_dwordx4 v[20:21], off
	v_lshl_add_u64 v[20:21], v[40:41], 0, vcc
	s_add_u32 m0, s100, 0xb000
	s_nop 0
	global_load_lds_dwordx4 v[20:21], off
	v_lshl_add_u64 v[20:21], v[146:147], 0, vcc
	s_add_u32 m0, s100, 0xc000
	s_nop 0
	global_load_lds_dwordx4 v[20:21], off
	v_lshl_add_u64 v[20:21], v[56:57], 0, vcc
	s_add_u32 m0, s100, 0xd000
	s_nop 0
	global_load_lds_dwordx4 v[20:21], off
	v_lshl_add_u64 v[20:21], v[60:61], 0, vcc
	s_add_u32 m0, s100, 0xe000
	s_nop 0
	global_load_lds_dwordx4 v[20:21], off
	v_lshl_add_u64 v[20:21], v[64:65], 0, vcc
	s_add_u32 m0, s100, 0xf000
	s_nop 0
	global_load_lds_dwordx4 v[20:21], off
	v_lshrrev_b32_e32 v1, 1, v3
	v_xor_b32_e32 v1, v1, v68
	v_lshlrev_b32_e32 v0, 7, v3
	v_lshlrev_b32_e32 v1, 4, v1
	s_movk_i32 s1, 0x70
	v_lshrrev_b32_e32 v69, 4, v68
	v_bfe_u32 v74, v68, 4, 2
	v_and_or_b32 v3, v1, s1, v0
	v_lshl_add_u64 v[0:1], s[76:77], 0, v[70:71]
	v_bfe_u32 v70, v68, 1, 3
	v_bitop3_b32 v69, v69, v70, 3 bitop3:0x6c
	v_lshlrev_b32_e32 v71, 6, v68
	v_lshlrev_b32_e32 v68, 7, v68
	v_bitop3_b32 v70, v74, v70, 4 bitop3:0x36
	v_lshl_add_u64 v[138:139], s[24:25], 0, v[72:73]
	v_lshlrev_b32_e32 v69, 4, v69
	v_and_b32_e32 v71, 0xffffe000, v71
	v_and_b32_e32 v72, 0x780, v68
	v_and_b32_e32 v68, 0x2000, v68
	v_lshlrev_b32_e32 v70, 4, v70
	s_cmp_gt_i32 s47, 0
	v_or_b32_e32 v73, v69, v71
	v_or_b32_e32 v69, v69, v68
	v_or_b32_e32 v71, v70, v71
	v_or_b32_e32 v68, v70, v68
	s_mov_b32 s48, 0
	s_cselect_b64 s[24:25], -1, 0
	v_add_u32_e32 v137, v73, v72
	v_add_u32_e32 v188, v69, v72
	v_add_u32_e32 v189, v71, v72
	v_add_u32_e32 v190, v68, v72
	s_mov_b32 s1, 0
	s_mov_b32 s3, 0
	v_readlane_b32 s5, v252, 38
	v_readlane_b32 s6, v252, 39
	v_readlane_b32 s7, v252, 40
	v_readlane_b32 s8, v252, 41
	v_readlane_b32 s9, v252, 42
	v_readlane_b32 s10, v252, 43
	v_readlane_b32 s11, v252, 44
	v_readlane_b32 s14, v252, 47
	v_readlane_b32 s15, v252, 48
	v_readlane_b32 s16, v252, 49
	v_readlane_b32 s17, v252, 50
	v_readlane_b32 s18, v252, 51
	v_readlane_b32 s19, v252, 52
	s_bfe_u32 vcc_lo, s101, 0x10001
	v_and_b32_e32 v20, 15, v194
	v_lshrrev_b32_e32 v21, 1, v20
	v_bfe_u32 v22, v194, 4, 2
	v_xor_b32_e32 v21, v21, v22
	v_lshlrev_b32_e32 v21, 4, v21
	v_lshl_or_b32 v250, v20, 7, v21
	v_mov_b32_e32 v22, vcc_lo
	v_lshl_or_b32 v22, v22, 13, v250
	v_or_b32_e32 v251, 0x4000, v22
	v_and_b32_e32 v20, 63, v194
	v_mov_b32_e32 v21, vcc_lo
	v_lshlrev_b32_e32 v21, 4, v21
	v_lshrrev_b32_e32 v22, 3, v20
	v_add_u32_e32 v21, v21, v22
	v_lshrrev_b32_e32 v22, 4, v20
	v_and_b32_e32 v23, 7, v20
	v_xor_b32_e32 v24, v23, v22
	v_lshlrev_b32_e32 v24, 4, v24
	v_or_b32_e32 v22, 4, v22
	v_xor_b32_e32 v25, v23, v22
	v_lshlrev_b32_e32 v25, 4, v25
	s_lshl_b32 s98, s0, 1
	s_lshl_b32 s99, s2, 1
	v_add_u32_e32 v26, 0, v21
	v_mad_u32_u24 v4, v26, s98, v24
	v_add_u32_e32 v26, 8, v21
	v_mad_u32_u24 v5, v26, s98, v25
	v_add_u32_e32 v26, 32, v21
	v_mad_u32_u24 v6, v26, s98, v24
	v_add_u32_e32 v26, 40, v21
	v_mad_u32_u24 v7, v26, s98, v25
	v_add_u32_e32 v26, 64, v21
	v_mad_u32_u24 v8, v26, s98, v24
	v_add_u32_e32 v26, 72, v21
	v_mad_u32_u24 v9, v26, s98, v25
	v_add_u32_e32 v26, 96, v21
	v_mad_u32_u24 v10, v26, s98, v24
	v_add_u32_e32 v26, 104, v21
	v_mad_u32_u24 v11, v26, s98, v25
	v_add_u32_e32 v26, 0, v21
	v_mad_u32_u24 v12, v26, s99, v24
	v_add_u32_e32 v26, 8, v21
	v_mad_u32_u24 v13, v26, s99, v25
	v_add_u32_e32 v26, 32, v21
	v_mad_u32_u24 v14, v26, s99, v24
	v_add_u32_e32 v26, 40, v21
	v_mad_u32_u24 v15, v26, s99, v25
	v_add_u32_e32 v26, 64, v21
	v_mad_u32_u24 v16, v26, s99, v24
	v_add_u32_e32 v26, 72, v21
	v_mad_u32_u24 v17, v26, s99, v25
	v_add_u32_e32 v26, 96, v21
	v_mad_u32_u24 v18, v26, s99, v24
	v_add_u32_e32 v26, 104, v21
	v_mad_u32_u24 v19, v26, s99, v25
	s_bfe_u32 vcc_hi, s101, 0x20002
	s_lshl_b32 vcc_hi, vcc_hi, 3
	s_mul_i32 s98, s98, vcc_hi
	s_mul_i32 s99, s99, vcc_hi
	s_lshl_b32 vcc_hi, vcc_hi, 3
	s_and_b32 vcc_hi, vcc_hi, 0x70
	s_add_u32 s98, s98, vcc_hi
	s_add_u32 s99, s99, vcc_hi
	s_lshl_b32 s100, vcc_lo, 11
	s_bitcmp1_b32 s101, 0
	s_cselect_b32 s100, -1, s100
	s_waitcnt vmcnt(0) lgkmcnt(0)
	s_barrier
	s_branch .LBB0_946

.LBB0_945:
	v_mov_b32_e32 v132, v194
	v_mov_b32_e32 v133, v194
	v_and_b32_e32 v145, 64, v202
	v_and_b32_e32 v134, 64, v133
	v_ashrrev_i32_e32 v133, 1, v133
	v_and_b32_e32 v135, 15, v132
	v_and_b32_e32 v133, 0xffffffc0, v133
	v_xor_b32_e32 v144, 16, v202
	v_add_u32_e32 v145, 64, v145
	v_add3_u32 v135, v135, s52, v133
	v_and_b32_e32 v133, 16, v132
	v_cmp_lt_i32_e32 vcc, v144, v145
	v_cvt_pk_bf16_f32 v124, v124, v125
	v_cvt_pk_bf16_f32 v125, v126, v127
	v_cndmask_b32_e32 v144, v202, v144, vcc
	v_cvt_pk_bf16_f32 v126, v128, v129
	v_cvt_pk_bf16_f32 v127, v130, v131
	v_cmp_eq_u32_e32 vcc, 0, v133
	v_cvt_pk_bf16_f32 v112, v112, v113
	v_cvt_pk_bf16_f32 v108, v108, v109
	v_cvt_pk_bf16_f32 v96, v96, v97
	v_cvt_pk_bf16_f32 v92, v92, v93
	v_cvt_pk_bf16_f32 v80, v80, v81
	v_cvt_pk_bf16_f32 v76, v76, v77
	v_lshlrev_b32_e32 v144, 2, v144
	v_cvt_pk_bf16_f32 v130, v116, v117
	v_cndmask_b32_e32 v116, v124, v126, vcc
	v_cndmask_b32_e32 v117, v125, v127, vcc
	v_cvt_pk_bf16_f32 v106, v106, v107
	v_cvt_pk_bf16_f32 v107, v100, v101
	v_cndmask_b32_e32 v100, v112, v108, vcc
	v_cvt_pk_bf16_f32 v90, v90, v91
	v_cvt_pk_bf16_f32 v91, v84, v85
	v_cndmask_b32_e32 v84, v96, v92, vcc
	v_cvt_pk_bf16_f32 v74, v74, v75
	v_cvt_pk_bf16_f32 v75, v68, v69
	v_cndmask_b32_e32 v68, v80, v76, vcc
	v_cvt_pk_bf16_f32 v131, v118, v119
	ds_bpermute_b32 v118, v144, v116
	ds_bpermute_b32 v119, v144, v117
	v_cvt_pk_bf16_f32 v109, v110, v111
	v_cvt_pk_bf16_f32 v111, v102, v103
	ds_bpermute_b32 v102, v144, v100
	v_cvt_pk_bf16_f32 v93, v94, v95
	v_cvt_pk_bf16_f32 v95, v86, v87
	ds_bpermute_b32 v86, v144, v84
	v_cvt_pk_bf16_f32 v77, v78, v79
	v_cvt_pk_bf16_f32 v79, v70, v71
	ds_bpermute_b32 v70, v144, v68
	v_cvt_pk_bf16_f32 v113, v114, v115
	v_cvt_pk_bf16_f32 v97, v98, v99
	v_cvt_pk_bf16_f32 v81, v82, v83
	v_cvt_pk_bf16_f32 v128, v120, v121
	v_cvt_pk_bf16_f32 v129, v122, v123
	v_mov_b64_e32 v[120:121], s[78:79]
	s_movk_i32 s4, 0x3100
	v_cvt_pk_bf16_f32 v110, v104, v105
	v_cndmask_b32_e32 v101, v113, v109, vcc
	v_add_u32_e32 v100, 16, v135
	v_cvt_pk_bf16_f32 v94, v88, v89
	v_cndmask_b32_e32 v85, v97, v93, vcc
	v_add_u32_e32 v84, 32, v135
	v_cvt_pk_bf16_f32 v78, v72, v73
	v_cndmask_b32_e32 v69, v81, v77, vcc
	v_add_u32_e32 v68, 48, v135
	v_lshrrev_b32_e32 v132, 2, v132
	s_waitcnt lgkmcnt(4)
	v_cndmask_b32_e32 v116, v118, v124, vcc
	s_waitcnt lgkmcnt(3)
	v_cndmask_b32_e32 v117, v119, v125, vcc
	v_cndmask_b32_e32 v124, v128, v130, vcc
	v_cndmask_b32_e32 v125, v129, v131, vcc
	ds_bpermute_b32 v103, v144, v101
	v_mad_i64_i32 v[104:105], s[30:31], v100, s4, v[120:121]
	s_waitcnt lgkmcnt(3)
	v_cndmask_b32_e32 v100, v102, v112, vcc
	v_cndmask_b32_e32 v102, v108, v102, vcc
	v_cndmask_b32_e32 v108, v110, v107, vcc
	v_cndmask_b32_e32 v112, v106, v111, vcc
	ds_bpermute_b32 v87, v144, v85
	v_mad_i64_i32 v[88:89], s[30:31], v84, s4, v[120:121]
	s_waitcnt lgkmcnt(3)
	v_cndmask_b32_e32 v84, v86, v96, vcc
	v_cndmask_b32_e32 v86, v92, v86, vcc
	v_cndmask_b32_e32 v92, v94, v91, vcc
	v_cndmask_b32_e32 v96, v90, v95, vcc
	ds_bpermute_b32 v71, v144, v69
	v_mad_i64_i32 v[72:73], s[30:31], v68, s4, v[120:121]
	s_waitcnt lgkmcnt(3)
	v_cndmask_b32_e32 v68, v70, v80, vcc
	v_cndmask_b32_e32 v70, v76, v70, vcc
	v_cndmask_b32_e32 v76, v78, v75, vcc
	v_cndmask_b32_e32 v80, v74, v79, vcc
	v_and_b32_e32 v132, 8, v132
	v_add_u32_e32 v145, s49, v133
	v_cndmask_b32_e32 v118, v126, v118, vcc
	v_cndmask_b32_e32 v119, v127, v119, vcc
	ds_bpermute_b32 v126, v144, v124
	ds_bpermute_b32 v127, v144, v125
	ds_bpermute_b32 v108, v144, v108
	ds_bpermute_b32 v112, v144, v112
	ds_bpermute_b32 v92, v144, v92
	ds_bpermute_b32 v96, v144, v96
	ds_bpermute_b32 v76, v144, v76
	ds_bpermute_b32 v80, v144, v80
	v_add3_u32 v132, v145, v134, v132
	v_ashrrev_i32_e32 v133, 31, v132
	v_mad_i64_i32 v[122:123], s[30:31], v135, s4, v[120:121]
	v_lshlrev_b64 v[124:125], 1, v[132:133]
	v_lshl_add_u64 v[122:123], v[122:123], 0, v[124:125]
	s_waitcnt lgkmcnt(10)
	v_cndmask_b32_e32 v101, v103, v113, vcc
	v_cndmask_b32_e32 v103, v109, v103, vcc
	v_lshl_add_u64 v[104:105], v[104:105], 0, v[124:125]
	s_waitcnt lgkmcnt(9)
	v_cndmask_b32_e32 v85, v87, v97, vcc
	v_cndmask_b32_e32 v87, v93, v87, vcc
	v_lshl_add_u64 v[88:89], v[88:89], 0, v[124:125]
	s_waitcnt lgkmcnt(8)
	v_cndmask_b32_e32 v69, v71, v81, vcc
	v_cndmask_b32_e32 v71, v77, v71, vcc
	v_lshl_add_u64 v[72:73], v[72:73], 0, v[124:125]
	global_store_dwordx4 v[122:123], v[116:119], off
	global_store_dwordx4 v[104:105], v[100:103], off
	global_store_dwordx4 v[88:89], v[84:87], off
	s_waitcnt lgkmcnt(7)
	v_cndmask_b32_e32 v116, v126, v128, vcc
	s_waitcnt lgkmcnt(6)
	v_cndmask_b32_e32 v117, v127, v129, vcc
	v_cndmask_b32_e32 v118, v130, v126, vcc
	v_cndmask_b32_e32 v119, v131, v127, vcc
	s_waitcnt lgkmcnt(5)
	v_cndmask_b32_e32 v100, v108, v110, vcc
	s_waitcnt lgkmcnt(4)
	v_cndmask_b32_e32 v101, v112, v106, vcc
	v_cndmask_b32_e32 v102, v107, v108, vcc
	v_cndmask_b32_e32 v103, v111, v112, vcc
	s_waitcnt lgkmcnt(3)
	v_cndmask_b32_e32 v84, v92, v94, vcc
	s_waitcnt lgkmcnt(2)
	v_cndmask_b32_e32 v85, v96, v90, vcc
	v_cndmask_b32_e32 v86, v91, v92, vcc
	v_cndmask_b32_e32 v87, v95, v96, vcc
	global_store_dwordx4 v[72:73], v[68:71], off
	s_mov_b32 s52, s48
	s_mov_b32 s49, s1
	s_waitcnt lgkmcnt(1)
	v_cndmask_b32_e32 v68, v76, v78, vcc
	s_waitcnt lgkmcnt(0)
	v_cndmask_b32_e32 v69, v80, v74, vcc
	v_cndmask_b32_e32 v70, v75, v76, vcc
	v_cndmask_b32_e32 v71, v79, v80, vcc
	s_and_b64 vcc, exec, s[26:27]
	v_mov_b64_e32 v[146:147], v[142:143]
	v_mov_b64_e32 v[144:145], v[140:141]
	global_store_dwordx4 v[122:123], v[116:119], off offset:64
	global_store_dwordx4 v[104:105], v[100:103], off offset:64
	global_store_dwordx4 v[88:89], v[84:87], off offset:64
	global_store_dwordx4 v[72:73], v[68:71], off offset:64
	s_branch .Lpc_edone_1

.LBB0_948:
	s_mul_hi_i32 s35, s48, s0
	s_mul_i32 s34, s48, s0
	v_lshl_add_u64 v[140:141], s[34:35], 1, v[0:1]
	s_mul_hi_i32 s35, s1, s2
	s_mul_i32 s34, s1, s2
	v_lshl_add_u64 v[142:143], s[34:35], 1, v[138:139]
	s_andn2_b64 vcc, exec, s[24:25]
	s_cbranch_vccnz .LBB0_944
	v_lshl_add_u64 v[148:149], v[140:141], 0, s[20:21]
	v_lshl_add_u64 v[154:155], v[142:143], 0, s[22:23]
	v_lshl_add_u64 v[160:161], v[144:145], 0, s[20:21]
	v_lshl_add_u64 v[166:167], v[146:147], 0, s[22:23]
	v_lshl_add_u64 v[150:151], v[148:149], 0, s[20:21]
	v_lshl_add_u64 v[156:157], v[154:155], 0, s[22:23]
	v_lshl_add_u64 v[162:163], v[160:161], 0, s[20:21]
	v_lshl_add_u64 v[168:169], v[166:167], 0, s[22:23]
	v_mov_b32_e32 v68, 0
	v_lshl_add_u64 v[152:153], v[150:151], 0, s[20:21]
	v_lshl_add_u64 v[158:159], v[156:157], 0, s[22:23]
	v_lshl_add_u64 v[164:165], v[162:163], 0, s[20:21]
	v_lshl_add_u64 v[170:171], v[168:169], 0, s[22:23]
	s_mov_b64 s[34:35], 0x100
	s_mov_b32 s53, 2
	v_mov_b32_e32 v69, v68
	v_mov_b32_e32 v70, v68
	v_mov_b32_e32 v71, v68
	v_mov_b32_e32 v72, v68
	v_mov_b32_e32 v73, v68
	v_mov_b32_e32 v74, v68
	v_mov_b32_e32 v75, v68
	v_mov_b32_e32 v76, v68
	v_mov_b32_e32 v77, v68
	v_mov_b32_e32 v78, v68
	v_mov_b32_e32 v79, v68
	v_mov_b32_e32 v80, v68
	v_mov_b32_e32 v81, v68
	v_mov_b32_e32 v82, v68
	v_mov_b32_e32 v83, v68
	v_mov_b32_e32 v84, v68
	v_mov_b32_e32 v85, v68
	v_mov_b32_e32 v86, v68
	v_mov_b32_e32 v87, v68
	v_mov_b32_e32 v88, v68
	v_mov_b32_e32 v89, v68
	v_mov_b32_e32 v90, v68
	v_mov_b32_e32 v91, v68
	v_mov_b32_e32 v92, v68
	v_mov_b32_e32 v93, v68
	v_mov_b32_e32 v94, v68
	v_mov_b32_e32 v95, v68
	v_mov_b32_e32 v96, v68
	v_mov_b32_e32 v97, v68
	v_mov_b32_e32 v98, v68
	v_mov_b32_e32 v99, v68
	v_mov_b32_e32 v100, v68
	v_mov_b32_e32 v101, v68
	v_mov_b32_e32 v102, v68
	v_mov_b32_e32 v103, v68
	v_mov_b32_e32 v104, v68
	v_mov_b32_e32 v105, v68
	v_mov_b32_e32 v106, v68
	v_mov_b32_e32 v107, v68
	v_mov_b32_e32 v108, v68
	v_mov_b32_e32 v109, v68
	v_mov_b32_e32 v110, v68
	v_mov_b32_e32 v111, v68
	v_mov_b32_e32 v112, v68
	v_mov_b32_e32 v113, v68
	v_mov_b32_e32 v114, v68
	v_mov_b32_e32 v115, v68
	v_mov_b32_e32 v116, v68
	v_mov_b32_e32 v117, v68
	v_mov_b32_e32 v118, v68
	v_mov_b32_e32 v119, v68
	v_mov_b32_e32 v120, v68
	v_mov_b32_e32 v121, v68
	v_mov_b32_e32 v122, v68
	v_mov_b32_e32 v123, v68
	v_mov_b32_e32 v128, v68
	v_mov_b32_e32 v129, v68
	v_mov_b32_e32 v130, v68
	v_mov_b32_e32 v131, v68
	v_mov_b32_e32 v124, v68
	v_mov_b32_e32 v125, v68
	v_mov_b32_e32 v126, v68
	v_mov_b32_e32 v127, v68
	s_branch .LBB0_951
.LBB0_951:
	s_cmp_ge_i32 s100, 0
	s_cbranch_scc1 .Lpc_prod_1
	v_mov_b64_e32 v[4:5], 0
	v_mov_b64_e32 v[6:7], 0
	v_mov_b64_e32 v[8:9], 0
	v_mov_b64_e32 v[10:11], 0
	v_mov_b64_e32 v[12:13], 0
	v_mov_b64_e32 v[14:15], 0
	v_mov_b64_e32 v[16:17], 0
	v_mov_b64_e32 v[18:19], 0
	v_mov_b64_e32 v[20:21], 0
	v_mov_b64_e32 v[22:23], 0
	v_mov_b64_e32 v[24:25], 0
	v_mov_b64_e32 v[26:27], 0
	v_mov_b64_e32 v[28:29], 0
	v_mov_b64_e32 v[30:31], 0
	v_mov_b64_e32 v[32:33], 0
	v_mov_b64_e32 v[34:35], 0
	v_mov_b64_e32 v[36:37], 0
	v_mov_b64_e32 v[38:39], 0
	v_mov_b64_e32 v[40:41], 0
	v_mov_b64_e32 v[42:43], 0
	v_mov_b64_e32 v[44:45], 0
	v_mov_b64_e32 v[46:47], 0
	v_mov_b64_e32 v[48:49], 0
	v_mov_b64_e32 v[50:51], 0
	v_mov_b64_e32 v[52:53], 0
	v_mov_b64_e32 v[54:55], 0
	v_mov_b64_e32 v[56:57], 0
	v_mov_b64_e32 v[58:59], 0
	v_mov_b64_e32 v[60:61], 0
	v_mov_b64_e32 v[62:63], 0
	v_mov_b64_e32 v[64:65], 0
	v_mov_b64_e32 v[66:67], 0
	v_xor_b32_e32 v188, 64, v250
	v_xor_b32_e32 v137, 64, v251
	ds_read_b128 v[230:233], v251
	ds_read_b128 v[246:249], v251 offset:2048
	ds_read_b128 v[132:135], v251 offset:4096
	ds_read_b128 v[208:211], v251 offset:6144
	ds_read_b128 v[172:175], v250
	ds_read_b128 v[176:179], v250 offset:2048
	ds_read_b128 v[180:183], v250 offset:4096
	ds_read_b128 v[184:187], v250 offset:6144
	ds_read_b128 v[214:217], v250 offset:8192
	ds_read_b128 v[218:221], v250 offset:10240
	ds_read_b128 v[222:225], v250 offset:12288
	ds_read_b128 v[226:229], v250 offset:14336
	ds_read_b128 v[234:237], v137
	ds_read_b128 v[144:147], v137 offset:2048
	ds_read_b128 v[160:163], v137 offset:4096
	s_waitcnt lgkmcnt(14)
	ds_read_b128 v[164:167], v137 offset:6144
	s_waitcnt lgkmcnt(14)
	ds_read_b128 v[168:171], v188
	s_waitcnt lgkmcnt(14)
	ds_read_b128 v[140:143], v188 offset:2048
	s_waitcnt lgkmcnt(14)
	ds_read_b128 v[148:151], v188 offset:4096
	s_waitcnt lgkmcnt(14)
	ds_read_b128 v[152:155], v188 offset:6144
	s_waitcnt lgkmcnt(14)
	ds_read_b128 v[156:159], v188 offset:8192
	v_mfma_f32_16x16x32_bf16 v[124:127], v[230:233], v[172:175], v[124:127]
	v_mfma_f32_16x16x32_bf16 v[128:131], v[246:249], v[172:175], v[128:131]
	v_mfma_f32_16x16x32_bf16 v[120:123], v[132:135], v[172:175], v[120:123]
	v_mfma_f32_16x16x32_bf16 v[116:119], v[208:211], v[172:175], v[116:119]
	s_waitcnt lgkmcnt(14)
	ds_read_b128 v[172:175], v188 offset:10240
	v_mfma_f32_16x16x32_bf16 v[112:115], v[230:233], v[176:179], v[112:115]
	v_mfma_f32_16x16x32_bf16 v[108:111], v[246:249], v[176:179], v[108:111]
	v_mfma_f32_16x16x32_bf16 v[104:107], v[132:135], v[176:179], v[104:107]
	v_mfma_f32_16x16x32_bf16 v[100:103], v[208:211], v[176:179], v[100:103]
	s_waitcnt lgkmcnt(14)
	ds_read_b128 v[176:179], v188 offset:12288
	v_mfma_f32_16x16x32_bf16 v[96:99], v[230:233], v[180:183], v[96:99]
	v_mfma_f32_16x16x32_bf16 v[92:95], v[246:249], v[180:183], v[92:95]
	v_mfma_f32_16x16x32_bf16 v[88:91], v[132:135], v[180:183], v[88:91]
	v_mfma_f32_16x16x32_bf16 v[84:87], v[208:211], v[180:183], v[84:87]
	s_waitcnt lgkmcnt(14)
	ds_read_b128 v[180:183], v188 offset:14336
	v_mfma_f32_16x16x32_bf16 v[80:83], v[230:233], v[184:187], v[80:83]
	v_mfma_f32_16x16x32_bf16 v[76:79], v[246:249], v[184:187], v[76:79]
	v_mfma_f32_16x16x32_bf16 v[72:75], v[132:135], v[184:187], v[72:75]
	v_mfma_f32_16x16x32_bf16 v[68:71], v[208:211], v[184:187], v[68:71]
	v_mfma_f32_16x16x32_bf16 v[4:7], v[230:233], v[214:217], v[4:7]
	v_mfma_f32_16x16x32_bf16 v[8:11], v[246:249], v[214:217], v[8:11]
	v_mfma_f32_16x16x32_bf16 v[12:15], v[132:135], v[214:217], v[12:15]
	v_mfma_f32_16x16x32_bf16 v[16:19], v[208:211], v[214:217], v[16:19]
	s_waitcnt lgkmcnt(0)
	s_barrier
	v_mfma_f32_16x16x32_bf16 v[20:23], v[230:233], v[218:221], v[20:23]
	v_mfma_f32_16x16x32_bf16 v[24:27], v[246:249], v[218:221], v[24:27]
	v_mfma_f32_16x16x32_bf16 v[28:31], v[132:135], v[218:221], v[28:31]
	v_mfma_f32_16x16x32_bf16 v[32:35], v[208:211], v[218:221], v[32:35]
	v_mfma_f32_16x16x32_bf16 v[36:39], v[230:233], v[222:225], v[36:39]
	v_mfma_f32_16x16x32_bf16 v[40:43], v[246:249], v[222:225], v[40:43]
	v_mfma_f32_16x16x32_bf16 v[44:47], v[132:135], v[222:225], v[44:47]
	v_mfma_f32_16x16x32_bf16 v[48:51], v[208:211], v[222:225], v[48:51]
	v_mfma_f32_16x16x32_bf16 v[52:55], v[230:233], v[226:229], v[52:55]
	v_mfma_f32_16x16x32_bf16 v[56:59], v[246:249], v[226:229], v[56:59]
	v_mfma_f32_16x16x32_bf16 v[60:63], v[132:135], v[226:229], v[60:63]
	v_mfma_f32_16x16x32_bf16 v[64:67], v[208:211], v[226:229], v[64:67]
	v_mfma_f32_16x16x32_bf16 v[124:127], v[234:237], v[168:171], v[124:127]
	v_mfma_f32_16x16x32_bf16 v[128:131], v[144:147], v[168:171], v[128:131]
	v_mfma_f32_16x16x32_bf16 v[120:123], v[160:163], v[168:171], v[120:123]
	v_mfma_f32_16x16x32_bf16 v[116:119], v[164:167], v[168:171], v[116:119]
	v_mfma_f32_16x16x32_bf16 v[112:115], v[234:237], v[140:143], v[112:115]
	v_mfma_f32_16x16x32_bf16 v[108:111], v[144:147], v[140:143], v[108:111]
	v_mfma_f32_16x16x32_bf16 v[104:107], v[160:163], v[140:143], v[104:107]
	v_mfma_f32_16x16x32_bf16 v[100:103], v[164:167], v[140:143], v[100:103]
	v_mfma_f32_16x16x32_bf16 v[96:99], v[234:237], v[148:151], v[96:99]
	v_mfma_f32_16x16x32_bf16 v[92:95], v[144:147], v[148:151], v[92:95]
	v_mfma_f32_16x16x32_bf16 v[88:91], v[160:163], v[148:151], v[88:91]
	v_mfma_f32_16x16x32_bf16 v[84:87], v[164:167], v[148:151], v[84:87]
	v_mfma_f32_16x16x32_bf16 v[20:23], v[234:237], v[172:175], v[20:23]
	v_mfma_f32_16x16x32_bf16 v[24:27], v[144:147], v[172:175], v[24:27]
	v_mfma_f32_16x16x32_bf16 v[28:31], v[160:163], v[172:175], v[28:31]
	v_mfma_f32_16x16x32_bf16 v[32:35], v[164:167], v[172:175], v[32:35]
	v_mfma_f32_16x16x32_bf16 v[36:39], v[234:237], v[176:179], v[36:39]
	v_mfma_f32_16x16x32_bf16 v[40:43], v[144:147], v[176:179], v[40:43]
	v_mfma_f32_16x16x32_bf16 v[44:47], v[160:163], v[176:179], v[44:47]
	v_mfma_f32_16x16x32_bf16 v[48:51], v[164:167], v[176:179], v[48:51]
	v_mfma_f32_16x16x32_bf16 v[52:55], v[234:237], v[180:183], v[52:55]
	v_mfma_f32_16x16x32_bf16 v[56:59], v[144:147], v[180:183], v[56:59]
	v_mfma_f32_16x16x32_bf16 v[60:63], v[160:163], v[180:183], v[60:63]
	v_mfma_f32_16x16x32_bf16 v[64:67], v[164:167], v[180:183], v[64:67]
	s_barrier
	s_branch .Lpc_ck1_1
.Lpc_ctop_1:
	ds_read_b128 v[230:233], v251
	ds_read_b128 v[246:249], v251 offset:2048
	ds_read_b128 v[132:135], v251 offset:4096
	ds_read_b128 v[208:211], v251 offset:6144
	ds_read_b128 v[172:175], v250
	ds_read_b128 v[176:179], v250 offset:2048
	ds_read_b128 v[180:183], v250 offset:4096
	ds_read_b128 v[184:187], v250 offset:6144
	ds_read_b128 v[214:217], v250 offset:8192
	ds_read_b128 v[218:221], v250 offset:10240
	v_mfma_f32_16x16x32_bf16 v[80:83], v[234:237], v[152:155], v[80:83]
	v_mfma_f32_16x16x32_bf16 v[76:79], v[144:147], v[152:155], v[76:79]
	v_mfma_f32_16x16x32_bf16 v[72:75], v[160:163], v[152:155], v[72:75]
	v_mfma_f32_16x16x32_bf16 v[68:71], v[164:167], v[152:155], v[68:71]
	v_mfma_f32_16x16x32_bf16 v[4:7], v[234:237], v[156:159], v[4:7]
	v_mfma_f32_16x16x32_bf16 v[8:11], v[144:147], v[156:159], v[8:11]
	v_mfma_f32_16x16x32_bf16 v[12:15], v[160:163], v[156:159], v[12:15]
	v_mfma_f32_16x16x32_bf16 v[16:19], v[164:167], v[156:159], v[16:19]
	ds_read_b128 v[222:225], v250 offset:12288
	ds_read_b128 v[226:229], v250 offset:14336
	ds_read_b128 v[234:237], v137
	ds_read_b128 v[144:147], v137 offset:2048
	ds_read_b128 v[160:163], v137 offset:4096
	s_waitcnt lgkmcnt(14)
	ds_read_b128 v[164:167], v137 offset:6144
	s_waitcnt lgkmcnt(14)
	ds_read_b128 v[168:171], v188
	s_waitcnt lgkmcnt(14)
	ds_read_b128 v[140:143], v188 offset:2048
	s_waitcnt lgkmcnt(14)
	ds_read_b128 v[148:151], v188 offset:4096
	s_waitcnt lgkmcnt(14)
	ds_read_b128 v[152:155], v188 offset:6144
	s_waitcnt lgkmcnt(14)
	ds_read_b128 v[156:159], v188 offset:8192
	v_mfma_f32_16x16x32_bf16 v[124:127], v[230:233], v[172:175], v[124:127]
	v_mfma_f32_16x16x32_bf16 v[128:131], v[246:249], v[172:175], v[128:131]
	v_mfma_f32_16x16x32_bf16 v[120:123], v[132:135], v[172:175], v[120:123]
	v_mfma_f32_16x16x32_bf16 v[116:119], v[208:211], v[172:175], v[116:119]
	s_waitcnt lgkmcnt(14)
	ds_read_b128 v[172:175], v188 offset:10240
	v_mfma_f32_16x16x32_bf16 v[112:115], v[230:233], v[176:179], v[112:115]
	v_mfma_f32_16x16x32_bf16 v[108:111], v[246:249], v[176:179], v[108:111]
	v_mfma_f32_16x16x32_bf16 v[104:107], v[132:135], v[176:179], v[104:107]
	v_mfma_f32_16x16x32_bf16 v[100:103], v[208:211], v[176:179], v[100:103]
	s_waitcnt lgkmcnt(14)
	ds_read_b128 v[176:179], v188 offset:12288
	v_mfma_f32_16x16x32_bf16 v[96:99], v[230:233], v[180:183], v[96:99]
	v_mfma_f32_16x16x32_bf16 v[92:95], v[246:249], v[180:183], v[92:95]
	v_mfma_f32_16x16x32_bf16 v[88:91], v[132:135], v[180:183], v[88:91]
	v_mfma_f32_16x16x32_bf16 v[84:87], v[208:211], v[180:183], v[84:87]
	s_waitcnt lgkmcnt(14)
	ds_read_b128 v[180:183], v188 offset:14336
	v_mfma_f32_16x16x32_bf16 v[80:83], v[230:233], v[184:187], v[80:83]
	v_mfma_f32_16x16x32_bf16 v[76:79], v[246:249], v[184:187], v[76:79]
	v_mfma_f32_16x16x32_bf16 v[72:75], v[132:135], v[184:187], v[72:75]
	v_mfma_f32_16x16x32_bf16 v[68:71], v[208:211], v[184:187], v[68:71]
	v_mfma_f32_16x16x32_bf16 v[4:7], v[230:233], v[214:217], v[4:7]
	v_mfma_f32_16x16x32_bf16 v[8:11], v[246:249], v[214:217], v[8:11]
	v_mfma_f32_16x16x32_bf16 v[12:15], v[132:135], v[214:217], v[12:15]
	v_mfma_f32_16x16x32_bf16 v[16:19], v[208:211], v[214:217], v[16:19]
	s_waitcnt lgkmcnt(0)
	s_barrier
	v_mfma_f32_16x16x32_bf16 v[20:23], v[230:233], v[218:221], v[20:23]
	v_mfma_f32_16x16x32_bf16 v[24:27], v[246:249], v[218:221], v[24:27]
	v_mfma_f32_16x16x32_bf16 v[28:31], v[132:135], v[218:221], v[28:31]
	v_mfma_f32_16x16x32_bf16 v[32:35], v[208:211], v[218:221], v[32:35]
	v_mfma_f32_16x16x32_bf16 v[36:39], v[230:233], v[222:225], v[36:39]
	v_mfma_f32_16x16x32_bf16 v[40:43], v[246:249], v[222:225], v[40:43]
	v_mfma_f32_16x16x32_bf16 v[44:47], v[132:135], v[222:225], v[44:47]
	v_mfma_f32_16x16x32_bf16 v[48:51], v[208:211], v[222:225], v[48:51]
	v_mfma_f32_16x16x32_bf16 v[52:55], v[230:233], v[226:229], v[52:55]
	v_mfma_f32_16x16x32_bf16 v[56:59], v[246:249], v[226:229], v[56:59]
	v_mfma_f32_16x16x32_bf16 v[60:63], v[132:135], v[226:229], v[60:63]
	v_mfma_f32_16x16x32_bf16 v[64:67], v[208:211], v[226:229], v[64:67]
	v_mfma_f32_16x16x32_bf16 v[124:127], v[234:237], v[168:171], v[124:127]
	v_mfma_f32_16x16x32_bf16 v[128:131], v[144:147], v[168:171], v[128:131]
	v_mfma_f32_16x16x32_bf16 v[120:123], v[160:163], v[168:171], v[120:123]
	v_mfma_f32_16x16x32_bf16 v[116:119], v[164:167], v[168:171], v[116:119]
	v_mfma_f32_16x16x32_bf16 v[112:115], v[234:237], v[140:143], v[112:115]
	v_mfma_f32_16x16x32_bf16 v[108:111], v[144:147], v[140:143], v[108:111]
	v_mfma_f32_16x16x32_bf16 v[104:107], v[160:163], v[140:143], v[104:107]
	v_mfma_f32_16x16x32_bf16 v[100:103], v[164:167], v[140:143], v[100:103]
	v_mfma_f32_16x16x32_bf16 v[96:99], v[234:237], v[148:151], v[96:99]
	v_mfma_f32_16x16x32_bf16 v[92:95], v[144:147], v[148:151], v[92:95]
	v_mfma_f32_16x16x32_bf16 v[88:91], v[160:163], v[148:151], v[88:91]
	v_mfma_f32_16x16x32_bf16 v[84:87], v[164:167], v[148:151], v[84:87]
	v_mfma_f32_16x16x32_bf16 v[20:23], v[234:237], v[172:175], v[20:23]
	v_mfma_f32_16x16x32_bf16 v[24:27], v[144:147], v[172:175], v[24:27]
	v_mfma_f32_16x16x32_bf16 v[28:31], v[160:163], v[172:175], v[28:31]
	v_mfma_f32_16x16x32_bf16 v[32:35], v[164:167], v[172:175], v[32:35]
	v_mfma_f32_16x16x32_bf16 v[36:39], v[234:237], v[176:179], v[36:39]
	v_mfma_f32_16x16x32_bf16 v[40:43], v[144:147], v[176:179], v[40:43]
	v_mfma_f32_16x16x32_bf16 v[44:47], v[160:163], v[176:179], v[44:47]
	v_mfma_f32_16x16x32_bf16 v[48:51], v[164:167], v[176:179], v[48:51]
	v_mfma_f32_16x16x32_bf16 v[52:55], v[234:237], v[180:183], v[52:55]
	v_mfma_f32_16x16x32_bf16 v[56:59], v[144:147], v[180:183], v[56:59]
	v_mfma_f32_16x16x32_bf16 v[60:63], v[160:163], v[180:183], v[60:63]
	v_mfma_f32_16x16x32_bf16 v[64:67], v[164:167], v[180:183], v[64:67]
	s_barrier
.Lpc_ck1_1:
	ds_read_b128 v[230:233], v251 offset:32768
	ds_read_b128 v[246:249], v251 offset:34816
	ds_read_b128 v[132:135], v251 offset:36864
	ds_read_b128 v[208:211], v251 offset:38912
	ds_read_b128 v[172:175], v250 offset:32768
	ds_read_b128 v[176:179], v250 offset:34816
	ds_read_b128 v[180:183], v250 offset:36864
	ds_read_b128 v[184:187], v250 offset:38912
	ds_read_b128 v[214:217], v250 offset:40960
	ds_read_b128 v[218:221], v250 offset:43008
	v_mfma_f32_16x16x32_bf16 v[80:83], v[234:237], v[152:155], v[80:83]
	v_mfma_f32_16x16x32_bf16 v[76:79], v[144:147], v[152:155], v[76:79]
	v_mfma_f32_16x16x32_bf16 v[72:75], v[160:163], v[152:155], v[72:75]
	v_mfma_f32_16x16x32_bf16 v[68:71], v[164:167], v[152:155], v[68:71]
	v_mfma_f32_16x16x32_bf16 v[4:7], v[234:237], v[156:159], v[4:7]
	v_mfma_f32_16x16x32_bf16 v[8:11], v[144:147], v[156:159], v[8:11]
	v_mfma_f32_16x16x32_bf16 v[12:15], v[160:163], v[156:159], v[12:15]
	v_mfma_f32_16x16x32_bf16 v[16:19], v[164:167], v[156:159], v[16:19]
	ds_read_b128 v[222:225], v250 offset:45056
	ds_read_b128 v[226:229], v250 offset:47104
	ds_read_b128 v[234:237], v137 offset:32768
	ds_read_b128 v[144:147], v137 offset:34816
	ds_read_b128 v[160:163], v137 offset:36864
	s_waitcnt lgkmcnt(14)
	ds_read_b128 v[164:167], v137 offset:38912
	s_waitcnt lgkmcnt(14)
	ds_read_b128 v[168:171], v188 offset:32768
	s_waitcnt lgkmcnt(14)
	ds_read_b128 v[140:143], v188 offset:34816
	s_waitcnt lgkmcnt(14)
	ds_read_b128 v[148:151], v188 offset:36864
	s_waitcnt lgkmcnt(14)
	ds_read_b128 v[152:155], v188 offset:38912
	s_waitcnt lgkmcnt(14)
	ds_read_b128 v[156:159], v188 offset:40960
	v_mfma_f32_16x16x32_bf16 v[124:127], v[230:233], v[172:175], v[124:127]
	v_mfma_f32_16x16x32_bf16 v[128:131], v[246:249], v[172:175], v[128:131]
	v_mfma_f32_16x16x32_bf16 v[120:123], v[132:135], v[172:175], v[120:123]
	v_mfma_f32_16x16x32_bf16 v[116:119], v[208:211], v[172:175], v[116:119]
	s_waitcnt lgkmcnt(14)
	ds_read_b128 v[172:175], v188 offset:43008
	v_mfma_f32_16x16x32_bf16 v[112:115], v[230:233], v[176:179], v[112:115]
	v_mfma_f32_16x16x32_bf16 v[108:111], v[246:249], v[176:179], v[108:111]
	v_mfma_f32_16x16x32_bf16 v[104:107], v[132:135], v[176:179], v[104:107]
	v_mfma_f32_16x16x32_bf16 v[100:103], v[208:211], v[176:179], v[100:103]
	s_waitcnt lgkmcnt(14)
	ds_read_b128 v[176:179], v188 offset:45056
	v_mfma_f32_16x16x32_bf16 v[96:99], v[230:233], v[180:183], v[96:99]
	v_mfma_f32_16x16x32_bf16 v[92:95], v[246:249], v[180:183], v[92:95]
	v_mfma_f32_16x16x32_bf16 v[88:91], v[132:135], v[180:183], v[88:91]
	v_mfma_f32_16x16x32_bf16 v[84:87], v[208:211], v[180:183], v[84:87]
	s_waitcnt lgkmcnt(14)
	ds_read_b128 v[180:183], v188 offset:47104
	v_mfma_f32_16x16x32_bf16 v[80:83], v[230:233], v[184:187], v[80:83]
	v_mfma_f32_16x16x32_bf16 v[76:79], v[246:249], v[184:187], v[76:79]
	v_mfma_f32_16x16x32_bf16 v[72:75], v[132:135], v[184:187], v[72:75]
	v_mfma_f32_16x16x32_bf16 v[68:71], v[208:211], v[184:187], v[68:71]
	v_mfma_f32_16x16x32_bf16 v[4:7], v[230:233], v[214:217], v[4:7]
	v_mfma_f32_16x16x32_bf16 v[8:11], v[246:249], v[214:217], v[8:11]
	v_mfma_f32_16x16x32_bf16 v[12:15], v[132:135], v[214:217], v[12:15]
	v_mfma_f32_16x16x32_bf16 v[16:19], v[208:211], v[214:217], v[16:19]
	s_waitcnt lgkmcnt(0)
	s_barrier
	v_mfma_f32_16x16x32_bf16 v[20:23], v[230:233], v[218:221], v[20:23]
	v_mfma_f32_16x16x32_bf16 v[24:27], v[246:249], v[218:221], v[24:27]
	v_mfma_f32_16x16x32_bf16 v[28:31], v[132:135], v[218:221], v[28:31]
	v_mfma_f32_16x16x32_bf16 v[32:35], v[208:211], v[218:221], v[32:35]
	v_mfma_f32_16x16x32_bf16 v[36:39], v[230:233], v[222:225], v[36:39]
	v_mfma_f32_16x16x32_bf16 v[40:43], v[246:249], v[222:225], v[40:43]
	v_mfma_f32_16x16x32_bf16 v[44:47], v[132:135], v[222:225], v[44:47]
	v_mfma_f32_16x16x32_bf16 v[48:51], v[208:211], v[222:225], v[48:51]
	v_mfma_f32_16x16x32_bf16 v[52:55], v[230:233], v[226:229], v[52:55]
	v_mfma_f32_16x16x32_bf16 v[56:59], v[246:249], v[226:229], v[56:59]
	v_mfma_f32_16x16x32_bf16 v[60:63], v[132:135], v[226:229], v[60:63]
	v_mfma_f32_16x16x32_bf16 v[64:67], v[208:211], v[226:229], v[64:67]
	v_mfma_f32_16x16x32_bf16 v[124:127], v[234:237], v[168:171], v[124:127]
	v_mfma_f32_16x16x32_bf16 v[128:131], v[144:147], v[168:171], v[128:131]
	v_mfma_f32_16x16x32_bf16 v[120:123], v[160:163], v[168:171], v[120:123]
	v_mfma_f32_16x16x32_bf16 v[116:119], v[164:167], v[168:171], v[116:119]
	v_mfma_f32_16x16x32_bf16 v[112:115], v[234:237], v[140:143], v[112:115]
	v_mfma_f32_16x16x32_bf16 v[108:111], v[144:147], v[140:143], v[108:111]
	v_mfma_f32_16x16x32_bf16 v[104:107], v[160:163], v[140:143], v[104:107]
	v_mfma_f32_16x16x32_bf16 v[100:103], v[164:167], v[140:143], v[100:103]
	v_mfma_f32_16x16x32_bf16 v[96:99], v[234:237], v[148:151], v[96:99]
	v_mfma_f32_16x16x32_bf16 v[92:95], v[144:147], v[148:151], v[92:95]
	v_mfma_f32_16x16x32_bf16 v[88:91], v[160:163], v[148:151], v[88:91]
	v_mfma_f32_16x16x32_bf16 v[84:87], v[164:167], v[148:151], v[84:87]
	v_mfma_f32_16x16x32_bf16 v[20:23], v[234:237], v[172:175], v[20:23]
	v_mfma_f32_16x16x32_bf16 v[24:27], v[144:147], v[172:175], v[24:27]
	v_mfma_f32_16x16x32_bf16 v[28:31], v[160:163], v[172:175], v[28:31]
	v_mfma_f32_16x16x32_bf16 v[32:35], v[164:167], v[172:175], v[32:35]
	v_mfma_f32_16x16x32_bf16 v[36:39], v[234:237], v[176:179], v[36:39]
	v_mfma_f32_16x16x32_bf16 v[40:43], v[144:147], v[176:179], v[40:43]
	v_mfma_f32_16x16x32_bf16 v[44:47], v[160:163], v[176:179], v[44:47]
	v_mfma_f32_16x16x32_bf16 v[48:51], v[164:167], v[176:179], v[48:51]
	v_mfma_f32_16x16x32_bf16 v[52:55], v[234:237], v[180:183], v[52:55]
	v_mfma_f32_16x16x32_bf16 v[56:59], v[144:147], v[180:183], v[56:59]
	v_mfma_f32_16x16x32_bf16 v[60:63], v[160:163], v[180:183], v[60:63]
	v_mfma_f32_16x16x32_bf16 v[64:67], v[164:167], v[180:183], v[64:67]
	s_barrier
	s_add_i32 s53, s53, 2
	s_cmp_le_i32 s53, s47
	s_cbranch_scc1 .Lpc_ctop_1
	v_mfma_f32_16x16x32_bf16 v[80:83], v[234:237], v[152:155], v[80:83]
	v_mfma_f32_16x16x32_bf16 v[76:79], v[144:147], v[152:155], v[76:79]
	v_mfma_f32_16x16x32_bf16 v[72:75], v[160:163], v[152:155], v[72:75]
	v_mfma_f32_16x16x32_bf16 v[68:71], v[164:167], v[152:155], v[68:71]
	v_mfma_f32_16x16x32_bf16 v[4:7], v[234:237], v[156:159], v[4:7]
	v_mfma_f32_16x16x32_bf16 v[8:11], v[144:147], v[156:159], v[8:11]
	v_mfma_f32_16x16x32_bf16 v[12:15], v[160:163], v[156:159], v[12:15]
	v_mfma_f32_16x16x32_bf16 v[16:19], v[164:167], v[156:159], v[16:19]
	s_mov_b32 s98, s52
	s_mov_b32 s99, s49
	s_mov_b32 s100, -2
	s_bfe_u32 vcc_lo, s101, 0x10001
	s_lshl_b32 vcc_lo, vcc_lo, 6
	v_add_u32_e32 v194, vcc_lo, v202
	s_branch .LBB0_945
.Lpc_edone_1:
	s_cmp_eq_u32 s100, -2
	s_cbranch_scc0 .Lpc_efin_1
	s_mov_b32 s100, -3
	s_mov_b32 s52, s98
	s_mov_b32 s49, s99
	v_mov_b64_e32 v[124:125], v[4:5]
	v_mov_b64_e32 v[126:127], v[6:7]
	v_mov_b64_e32 v[128:129], v[8:9]
	v_mov_b64_e32 v[130:131], v[10:11]
	v_mov_b64_e32 v[120:121], v[12:13]
	v_mov_b64_e32 v[122:123], v[14:15]
	v_mov_b64_e32 v[116:117], v[16:17]
	v_mov_b64_e32 v[118:119], v[18:19]
	v_mov_b64_e32 v[112:113], v[20:21]
	v_mov_b64_e32 v[114:115], v[22:23]
	v_mov_b64_e32 v[108:109], v[24:25]
	v_mov_b64_e32 v[110:111], v[26:27]
	v_mov_b64_e32 v[104:105], v[28:29]
	v_mov_b64_e32 v[106:107], v[30:31]
	v_mov_b64_e32 v[100:101], v[32:33]
	v_mov_b64_e32 v[102:103], v[34:35]
	v_mov_b64_e32 v[96:97], v[36:37]
	v_mov_b64_e32 v[98:99], v[38:39]
	v_mov_b64_e32 v[92:93], v[40:41]
	v_mov_b64_e32 v[94:95], v[42:43]
	v_mov_b64_e32 v[88:89], v[44:45]
	v_mov_b64_e32 v[90:91], v[46:47]
	v_mov_b64_e32 v[84:85], v[48:49]
	v_mov_b64_e32 v[86:87], v[50:51]
	v_mov_b64_e32 v[80:81], v[52:53]
	v_mov_b64_e32 v[82:83], v[54:55]
	v_mov_b64_e32 v[76:77], v[56:57]
	v_mov_b64_e32 v[78:79], v[58:59]
	v_mov_b64_e32 v[72:73], v[60:61]
	v_mov_b64_e32 v[74:75], v[62:63]
	v_mov_b64_e32 v[68:69], v[64:65]
	v_mov_b64_e32 v[70:71], v[66:67]
	v_add_u32_e32 v194, 0x80, v194
	s_branch .LBB0_945

.Lpc_prod_1:
.Lpc_ptop_1:
	s_cmp_lt_i32 s53, s47
	s_cbranch_scc1 .Lpc_pcur_1
	s_mov_b32 vcc_lo, 0
	s_cmp_lg_u64 s[30:31], 0
	s_cbranch_scc1 .Lpc_pnext_1
	v_readfirstlane_b32 s40, v144
	v_readfirstlane_b32 s41, v145
	v_readfirstlane_b32 s38, v146
	v_readfirstlane_b32 s39, v147
	s_branch .Lpc_pgo_1

.Lpc_pcur_1:
	s_mov_b32 vcc_lo, s53
	v_readfirstlane_b32 s40, v144
	v_readfirstlane_b32 s41, v145
	v_readfirstlane_b32 s38, v146
	v_readfirstlane_b32 s39, v147
.Lpc_pgo_1:
	s_nop 0
	s_sub_u32 s40, s40, s98
	s_subb_u32 s41, s41, 0
	s_sub_u32 s38, s38, s99
	s_subb_u32 s39, s39, 0
	s_bfe_u32 vcc_hi, s101, 0x80008
	s_add_u32 vcc_hi, vcc_hi, vcc_lo
	s_add_u32 m0, s47, -1
	s_and_b32 vcc_hi, vcc_hi, m0
	s_lshl_b32 vcc_hi, vcc_hi, 7
	v_add_u32_e32 v20, vcc_hi, v4
	v_add_u32_e32 v21, vcc_hi, v5
	v_add_u32_e32 v22, vcc_hi, v6
	v_add_u32_e32 v23, vcc_hi, v7
	v_add_u32_e32 v24, vcc_hi, v8
	v_add_u32_e32 v25, vcc_hi, v9
	v_add_u32_e32 v26, vcc_hi, v10
	v_add_u32_e32 v27, vcc_hi, v11
	v_add_u32_e32 v28, vcc_hi, v12
	v_add_u32_e32 v29, vcc_hi, v13
	v_add_u32_e32 v30, vcc_hi, v14
	v_add_u32_e32 v31, vcc_hi, v15
	v_add_u32_e32 v32, vcc_hi, v16
	v_add_u32_e32 v33, vcc_hi, v17
	v_add_u32_e32 v34, vcc_hi, v18
	v_add_u32_e32 v35, vcc_hi, v19
	s_add_u32 vcc_lo, vcc_lo, 1
	s_barrier
	s_add_u32 m0, s100, 0x0
	s_nop 0
	global_load_lds_dwordx4 v20, s[40:41]
	s_add_u32 m0, s100, 0x400
	s_nop 0
	global_load_lds_dwordx4 v21, s[40:41]
	s_add_u32 m0, s100, 0x1000
	s_nop 0
	global_load_lds_dwordx4 v22, s[40:41]
	s_add_u32 m0, s100, 0x1400
	s_nop 0
	global_load_lds_dwordx4 v23, s[40:41]
	s_add_u32 m0, s100, 0x2000
	s_nop 0
	global_load_lds_dwordx4 v24, s[40:41]
	s_add_u32 m0, s100, 0x2400
	s_nop 0
	global_load_lds_dwordx4 v25, s[40:41]
	s_add_u32 m0, s100, 0x3000
	s_nop 0
	global_load_lds_dwordx4 v26, s[40:41]
	s_add_u32 m0, s100, 0x3400
	s_nop 0
	global_load_lds_dwordx4 v27, s[40:41]
	s_waitcnt vmcnt(8)
	s_barrier
	s_add_u32 m0, s100, 0x4000
	s_nop 0
	global_load_lds_dwordx4 v28, s[38:39]
	s_add_u32 m0, s100, 0x4400
	s_nop 0
	global_load_lds_dwordx4 v29, s[38:39]
	s_add_u32 m0, s100, 0x5000
	s_nop 0
	global_load_lds_dwordx4 v30, s[38:39]
	s_add_u32 m0, s100, 0x5400
	s_nop 0
	global_load_lds_dwordx4 v31, s[38:39]
	s_add_u32 m0, s100, 0x6000
	s_nop 0
	global_load_lds_dwordx4 v32, s[38:39]
	s_add_u32 m0, s100, 0x6400
	s_nop 0
	global_load_lds_dwordx4 v33, s[38:39]
	s_add_u32 m0, s100, 0x7000
	s_nop 0
	global_load_lds_dwordx4 v34, s[38:39]
	s_add_u32 m0, s100, 0x7400
	s_nop 0
	global_load_lds_dwordx4 v35, s[38:39]
	s_bfe_u32 vcc_hi, s101, 0x80008
	s_add_u32 vcc_hi, vcc_hi, vcc_lo
	s_add_u32 m0, s47, -1
	s_and_b32 vcc_hi, vcc_hi, m0
	s_lshl_b32 vcc_hi, vcc_hi, 7
	v_add_u32_e32 v20, vcc_hi, v4
	v_add_u32_e32 v21, vcc_hi, v5
	v_add_u32_e32 v22, vcc_hi, v6
	v_add_u32_e32 v23, vcc_hi, v7
	v_add_u32_e32 v24, vcc_hi, v8
	v_add_u32_e32 v25, vcc_hi, v9
	v_add_u32_e32 v26, vcc_hi, v10
	v_add_u32_e32 v27, vcc_hi, v11
	v_add_u32_e32 v28, vcc_hi, v12
	v_add_u32_e32 v29, vcc_hi, v13
	v_add_u32_e32 v30, vcc_hi, v14
	v_add_u32_e32 v31, vcc_hi, v15
	v_add_u32_e32 v32, vcc_hi, v16
	v_add_u32_e32 v33, vcc_hi, v17
	v_add_u32_e32 v34, vcc_hi, v18
	v_add_u32_e32 v35, vcc_hi, v19
	s_add_u32 vcc_lo, vcc_lo, 1
	s_barrier
	s_add_u32 m0, s100, 0x8000
	s_nop 0
	global_load_lds_dwordx4 v20, s[40:41]
	s_add_u32 m0, s100, 0x8400
	s_nop 0
	global_load_lds_dwordx4 v21, s[40:41]
	s_add_u32 m0, s100, 0x9000
	s_nop 0
	global_load_lds_dwordx4 v22, s[40:41]
	s_add_u32 m0, s100, 0x9400
	s_nop 0
	global_load_lds_dwordx4 v23, s[40:41]
	s_add_u32 m0, s100, 0xa000
	s_nop 0
	global_load_lds_dwordx4 v24, s[40:41]
	s_add_u32 m0, s100, 0xa400
	s_nop 0
	global_load_lds_dwordx4 v25, s[40:41]
	s_add_u32 m0, s100, 0xb000
	s_nop 0
	global_load_lds_dwordx4 v26, s[40:41]
	s_add_u32 m0, s100, 0xb400
	s_nop 0
	global_load_lds_dwordx4 v27, s[40:41]
	s_waitcnt vmcnt(8)
	s_barrier
	s_add_u32 m0, s100, 0xc000
	s_nop 0
	global_load_lds_dwordx4 v28, s[38:39]
	s_add_u32 m0, s100, 0xc400
	s_nop 0
	global_load_lds_dwordx4 v29, s[38:39]
	s_add_u32 m0, s100, 0xd000
	s_nop 0
	global_load_lds_dwordx4 v30, s[38:39]
	s_add_u32 m0, s100, 0xd400
	s_nop 0
	global_load_lds_dwordx4 v31, s[38:39]
	s_add_u32 m0, s100, 0xe000
	s_nop 0
	global_load_lds_dwordx4 v32, s[38:39]
	s_add_u32 m0, s100, 0xe400
	s_nop 0
	global_load_lds_dwordx4 v33, s[38:39]
	s_add_u32 m0, s100, 0xf000
	s_nop 0
	global_load_lds_dwordx4 v34, s[38:39]
	s_add_u32 m0, s100, 0xf400
	s_nop 0
	global_load_lds_dwordx4 v35, s[38:39]
	s_add_u32 s34, s34, 0x100
	s_addc_u32 s35, s35, 0
	s_add_i32 s53, s53, 2
	s_cmp_le_i32 s53, s47
	s_cbranch_scc1 .Lpc_ptop_1
	s_movk_i32 s4, 0x3100
	s_mov_b32 s52, s48
	s_mov_b32 s49, s1
	s_and_b64 vcc, exec, s[26:27]
	v_mov_b64_e32 v[146:147], v[142:143]
	v_mov_b64_e32 v[144:145], v[140:141]
	s_cbranch_vccz .Lpc_pnd_1
	s_waitcnt vmcnt(0)
	s_branch .LBB0_965
